# all 88 16-MFMA runs of the GEMM K loops start 8-byte aligned (s_nop 0 in front of 29 of them) + placeholder nop runs compressed
# speedup vs baseline: 1.0050x; 1.0050x over previous
; #define PG8_STAGE(bufoff, gbase, voff) do { _Pragma("unroll") for (int _i = 0; _i < 2; ++_i) \
;         __builtin_amdgcn_global_load_lds((const unsigned*)((const char*)(gbase) + (voff)[_i]), (PG8_LAS unsigned*)(lds + (bufoff) + ldsw + _i * 8192), 16, 0, 0); } while (0)
; #define PG8_LDA(dst, b, h) do { _Pragma("unroll") for (int m = 0; m < 4; ++m) _Pragma("unroll") for (int k = 0; k < 2; ++k) dst[m][k] = *(const PG8_LAS bf16x8*)(lds + PG8_SA(b, h) + aoff + m * 2048 + k * 1024); } while (0)
; #define PG8_LDB(dst, b, h) do { _Pragma("unroll") for (int n = 0; n < 2; ++n) _Pragma("unroll") for (int k = 0; k < 2; ++k) dst[n][k] = *(const PG8_LAS bf16x8*)(lds + PG8_SB(b, h) + boff + n * 2048 + k * 1024); } while (0)
; #define PG8_MMA(ai, bj, At, Bt) do { __builtin_amdgcn_s_setprio(1); _Pragma("unroll") for (int m = 0; m < 4; ++m) _Pragma("unroll") for (int n = 0; n < 2; ++n) _Pragma("unroll") for (int k = 0; k < 2; ++k) \
;         acc[ai][bj][m][n] = __builtin_amdgcn_mfma_f32_16x16x32_bf16(Bt[n][k], At[m][k], acc[ai][bj][m][n], 0, 0, 0); __builtin_amdgcn_s_setprio(0); } while (0)
; #define PG8_WAIT_V(n) asm volatile("s_waitcnt vmcnt(" #n ")" ::: "memory")
; #define PG8_BAR __builtin_amdgcn_s_barrier()
; template <class Epi, class Sched, bool ALIGN_EPI = false, bool SP2 = false>
; __device__ __forceinline__ void gemm_phase(PG8_LAS unsigned char* lds, const Gemm g, const Sched& S, const Epi& E) {
;     ...
;         for (int t = 0; t < nt; t += 2) {
;             const bool last = (t == nt - 2);
;             const char* a1 = cA + (size_t)(t + 1) * kstep;
;             const char* a2 = last ? nA : cA + (size_t)(t + 2) * kstep; const char* b2 = last ? nB : cB + (size_t)(t + 2) * kstep;
;             const char* a3 = a2 + kstep; const char* b3 = b2 + kstep;
;             if (last && has_next) S.a_ready(nxt);
;             if constexpr (SP2) {
;             PG8_LDB(B0, 0, 0); PG8_LDB(B1, 0, 1); PG8_SCHED; PG8_LDA(At, 0, 0); PG8_STAGE(PG8_SA(1, 1), a1 + hstepA, voffA);
;             PG8_WAIT_V(8); PG8_WAIT_L(0); PG8_BAR; PG8_MMA(0, 0, At, B0); PG8_MMA(0, 1, At, B1); PG8_BAR; PG8_SCHED;
;             PG8_LDA(At, 0, 1); PG8_STAGE(PG8_SB(0, 0), b2, voffB); PG8_STAGE(PG8_SB(0, 1), b2 + hstepB, voffB); PG8_STAGE(PG8_SA(0, 0), a2, voffA);
;             PG8_WAIT_V(8); PG8_WAIT_L(0); PG8_BAR; PG8_MMA(1, 0, At, B0); PG8_MMA(1, 1, At, B1); PG8_BAR; PG8_SCHED;
.LBB0_156:
	v_add_u32_e32 v156, s25, v149
	v_add_u32_e32 v172, s40, v149
	ds_read_b128 v[140:143], v156
	ds_read_b128 v[144:147], v156 offset:1024
	ds_read_b128 v[152:155], v156 offset:2048
	ds_read_b128 v[156:159], v156 offset:3072
	ds_read_b128 v[160:163], v172
	ds_read_b128 v[164:167], v172 offset:1024
	ds_read_b128 v[168:171], v172 offset:2048
	ds_read_b128 v[172:175], v172 offset:3072
	s_add_u32 s2, s26, 0xfffc0080
	s_addc_u32 s8, s27, -1
	s_cmp_eq_u32 s78, 12
	s_cselect_b32 s31, s19, s8
	s_cselect_b32 s30, s71, s2
	s_cselect_b32 s29, s17, s75
	s_cselect_b32 s28, s72, s74
	v_lshl_add_u64 v[226:227], s[26:27], 0, v[138:139]
	s_add_i32 m0, s43, 0xc000
	ds_read_b128 v[176:179], v151
	ds_read_b128 v[180:183], v151 offset:1024
	ds_read_b128 v[184:187], v151 offset:2048
	ds_read_b128 v[188:191], v151 offset:3072
	ds_read_b128 v[204:207], v151 offset:4096
	ds_read_b128 v[208:211], v151 offset:5120
	ds_read_b128 v[218:221], v151 offset:6144
	ds_read_b128 v[222:225], v151 offset:7168
	global_load_lds_dwordx4 v[226:227], off
	v_lshl_add_u64 v[226:227], s[26:27], 0, v[136:137]
	s_add_i32 m0, s43, 0xe000
	s_nop 0
	global_load_lds_dwordx4 v[226:227], off
	s_waitcnt vmcnt(8)
	s_waitcnt lgkmcnt(0)
	s_barrier
	s_setprio 1
	s_waitcnt lgkmcnt(0)
	v_mfma_f32_16x16x32_bf16 v[116:119], v[140:143], v[176:179], v[116:119]
	v_mfma_f32_16x16x32_bf16 v[112:115], v[152:155], v[176:179], v[112:115]
	v_mfma_f32_16x16x32_bf16 v[108:111], v[140:143], v[184:187], v[108:111]
	v_mfma_f32_16x16x32_bf16 v[104:107], v[152:155], v[184:187], v[104:107]
	v_mfma_f32_16x16x32_bf16 v[92:95], v[140:143], v[204:207], v[92:95]
	v_mfma_f32_16x16x32_bf16 v[88:91], v[152:155], v[204:207], v[88:91]
	v_mfma_f32_16x16x32_bf16 v[76:79], v[140:143], v[218:221], v[76:79]
	v_mfma_f32_16x16x32_bf16 v[72:75], v[152:155], v[218:221], v[72:75]
	v_mfma_f32_16x16x32_bf16 v[116:119], v[144:147], v[180:183], v[116:119]
	v_mfma_f32_16x16x32_bf16 v[112:115], v[156:159], v[180:183], v[112:115]
	v_mfma_f32_16x16x32_bf16 v[108:111], v[144:147], v[188:191], v[108:111]
	v_mfma_f32_16x16x32_bf16 v[104:107], v[156:159], v[188:191], v[104:107]
	v_mfma_f32_16x16x32_bf16 v[92:95], v[144:147], v[208:211], v[92:95]
	v_mfma_f32_16x16x32_bf16 v[88:91], v[156:159], v[208:211], v[88:91]
	v_mfma_f32_16x16x32_bf16 v[76:79], v[144:147], v[222:225], v[76:79]
	v_mfma_f32_16x16x32_bf16 v[72:75], v[156:159], v[222:225], v[72:75]
	s_setprio 0
	s_setprio 1
	v_mfma_f32_16x16x32_bf16 v[124:127], v[160:163], v[176:179], v[124:127]
	v_mfma_f32_16x16x32_bf16 v[120:123], v[168:171], v[176:179], v[120:123]
	v_mfma_f32_16x16x32_bf16 v[100:103], v[160:163], v[184:187], v[100:103]
	v_mfma_f32_16x16x32_bf16 v[96:99], v[168:171], v[184:187], v[96:99]
	v_mfma_f32_16x16x32_bf16 v[84:87], v[160:163], v[204:207], v[84:87]
	v_mfma_f32_16x16x32_bf16 v[80:83], v[168:171], v[204:207], v[80:83]
	v_mfma_f32_16x16x32_bf16 v[68:71], v[160:163], v[218:221], v[68:71]
	v_mfma_f32_16x16x32_bf16 v[64:67], v[168:171], v[218:221], v[64:67]
	v_mfma_f32_16x16x32_bf16 v[124:127], v[164:167], v[180:183], v[124:127]
	v_mfma_f32_16x16x32_bf16 v[120:123], v[172:175], v[180:183], v[120:123]
	v_mfma_f32_16x16x32_bf16 v[100:103], v[164:167], v[188:191], v[100:103]
	v_mfma_f32_16x16x32_bf16 v[96:99], v[172:175], v[188:191], v[96:99]
	v_mfma_f32_16x16x32_bf16 v[84:87], v[164:167], v[208:211], v[84:87]
	v_mfma_f32_16x16x32_bf16 v[80:83], v[172:175], v[208:211], v[80:83]
	v_mfma_f32_16x16x32_bf16 v[68:71], v[164:167], v[222:225], v[68:71]
	v_mfma_f32_16x16x32_bf16 v[64:67], v[172:175], v[222:225], v[64:67]
	s_setprio 0
	s_barrier
	s_mov_b32 m0, s38
	v_lshl_add_u64 v[226:227], s[28:29], 0, v[192:193]
	s_add_u32 s8, s28, 0x40000
	ds_read_b128 v[176:179], v151 offset:16384
	ds_read_b128 v[180:183], v151 offset:17408
	ds_read_b128 v[184:187], v151 offset:18432
	ds_read_b128 v[188:191], v151 offset:19456
	ds_read_b128 v[204:207], v151 offset:20480
	ds_read_b128 v[208:211], v151 offset:21504
	ds_read_b128 v[218:221], v151 offset:22528
	ds_read_b128 v[222:225], v151 offset:23552
	global_load_lds_dwordx4 v[226:227], off
	v_lshl_add_u64 v[228:229], s[28:29], 0, v[128:129]
	s_mov_b32 m0, s39
	s_addc_u32 s9, s29, 0
	global_load_lds_dwordx4 v[228:229], off
	v_lshl_add_u64 v[230:231], s[8:9], 0, v[192:193]
	s_mov_b32 m0, s41
	v_lshl_add_u64 v[232:233], s[30:31], 0, v[130:131]
	global_load_lds_dwordx4 v[230:231], off
	v_lshl_add_u64 v[230:231], s[8:9], 0, v[128:129]
	s_mov_b32 m0, s42
	s_nop 0
	global_load_lds_dwordx4 v[230:231], off
	v_lshl_add_u64 v[230:231], s[30:31], 0, v[132:133]
	s_mov_b32 m0, s43
	s_nop 0
	global_load_lds_dwordx4 v[230:231], off
	s_mov_b32 m0, s44
	s_nop 0
	global_load_lds_dwordx4 v[232:233], off
	s_waitcnt vmcnt(8)
	s_waitcnt lgkmcnt(0)
	s_barrier
; #define PG8_STAGE(bufoff, gbase, voff) do { _Pragma("unroll") for (int _i = 0; _i < 2; ++_i) \
;         __builtin_amdgcn_global_load_lds((const unsigned*)((const char*)(gbase) + (voff)[_i]), (PG8_LAS unsigned*)(lds + (bufoff) + ldsw + _i * 8192), 16, 0, 0); } while (0)
; #define PG8_LDA(dst, b, h) do { _Pragma("unroll") for (int m = 0; m < 4; ++m) _Pragma("unroll") for (int k = 0; k < 2; ++k) dst[m][k] = *(const PG8_LAS bf16x8*)(lds + PG8_SA(b, h) + aoff + m * 2048 + k * 1024); } while (0)
; #define PG8_LDB(dst, b, h) do { _Pragma("unroll") for (int n = 0; n < 2; ++n) _Pragma("unroll") for (int k = 0; k < 2; ++k) dst[n][k] = *(const PG8_LAS bf16x8*)(lds + PG8_SB(b, h) + boff + n * 2048 + k * 1024); } while (0)
; #define PG8_MMA(ai, bj, At, Bt) do { __builtin_amdgcn_s_setprio(1); _Pragma("unroll") for (int m = 0; m < 4; ++m) _Pragma("unroll") for (int n = 0; n < 2; ++n) _Pragma("unroll") for (int k = 0; k < 2; ++k) \
;         acc[ai][bj][m][n] = __builtin_amdgcn_mfma_f32_16x16x32_bf16(Bt[n][k], At[m][k], acc[ai][bj][m][n], 0, 0, 0); __builtin_amdgcn_s_setprio(0); } while (0)
; #define PG8_WAIT_V(n) asm volatile("s_waitcnt vmcnt(" #n ")" ::: "memory")
; #define PG8_WAIT_L(n) asm volatile("s_waitcnt lgkmcnt(" #n ")" ::: "memory")
; #define PG8_BAR __builtin_amdgcn_s_barrier()
; #define PG8_SCHED __builtin_amdgcn_sched_barrier(0)
; template <class Epi, class Sched, bool ALIGN_EPI = false, bool SP2 = false>
; __device__ __forceinline__ void gemm_phase(PG8_LAS unsigned char* lds, const Gemm g, const Sched& S, const Epi& E) {
;     ...
;             PG8_WAIT_V(8); PG8_WAIT_L(0); PG8_BAR; PG8_MMA(0, 0, At, B0); PG8_MMA(0, 1, At, B1); PG8_BAR; PG8_SCHED;
;             PG8_LDA(At, 0, 1); PG8_STAGE(PG8_SB(0, 0), b2, voffB); PG8_STAGE(PG8_SB(0, 1), b2 + hstepB, voffB); PG8_STAGE(PG8_SA(0, 0), a2, voffA);
;             PG8_WAIT_V(8); PG8_WAIT_L(0); PG8_BAR; PG8_MMA(1, 0, At, B0); PG8_MMA(1, 1, At, B1); PG8_BAR; PG8_SCHED;
;             PG8_LDB(B0, 1, 0); PG8_LDB(B1, 1, 1); PG8_SCHED; PG8_LDA(At, 1, 0); PG8_STAGE(PG8_SA(0, 1), a2 + hstepA, voffA);
;             PG8_WAIT_V(8); PG8_WAIT_L(0); PG8_BAR; PG8_MMA(0, 0, At, B0); PG8_MMA(0, 1, At, B1); PG8_BAR; PG8_SCHED;
	s_setprio 1
	s_waitcnt lgkmcnt(0)
	s_nop 0
	v_mfma_f32_16x16x32_bf16 v[60:63], v[140:143], v[176:179], v[60:63]
	v_mfma_f32_16x16x32_bf16 v[56:59], v[152:155], v[176:179], v[56:59]
	v_mfma_f32_16x16x32_bf16 v[44:47], v[140:143], v[184:187], v[44:47]
	v_mfma_f32_16x16x32_bf16 v[40:43], v[152:155], v[184:187], v[40:43]
	v_mfma_f32_16x16x32_bf16 v[28:31], v[140:143], v[204:207], v[28:31]
	v_mfma_f32_16x16x32_bf16 v[24:27], v[152:155], v[204:207], v[24:27]
	v_mfma_f32_16x16x32_bf16 v[12:15], v[140:143], v[218:221], v[12:15]
	v_mfma_f32_16x16x32_bf16 v[8:11], v[152:155], v[218:221], v[8:11]
	v_mfma_f32_16x16x32_bf16 v[60:63], v[144:147], v[180:183], v[60:63]
	v_mfma_f32_16x16x32_bf16 v[56:59], v[156:159], v[180:183], v[56:59]
	v_mfma_f32_16x16x32_bf16 v[44:47], v[144:147], v[188:191], v[44:47]
	v_mfma_f32_16x16x32_bf16 v[40:43], v[156:159], v[188:191], v[40:43]
	v_mfma_f32_16x16x32_bf16 v[28:31], v[144:147], v[208:211], v[28:31]
	v_mfma_f32_16x16x32_bf16 v[24:27], v[156:159], v[208:211], v[24:27]
	v_mfma_f32_16x16x32_bf16 v[12:15], v[144:147], v[222:225], v[12:15]
	v_mfma_f32_16x16x32_bf16 v[8:11], v[156:159], v[222:225], v[8:11]
	s_setprio 0
	s_setprio 1
	v_mfma_f32_16x16x32_bf16 v[52:55], v[160:163], v[176:179], v[52:55]
	v_mfma_f32_16x16x32_bf16 v[48:51], v[168:171], v[176:179], v[48:51]
	v_mfma_f32_16x16x32_bf16 v[36:39], v[160:163], v[184:187], v[36:39]
	v_mfma_f32_16x16x32_bf16 v[32:35], v[168:171], v[184:187], v[32:35]
	v_mfma_f32_16x16x32_bf16 v[20:23], v[160:163], v[204:207], v[20:23]
	v_mfma_f32_16x16x32_bf16 v[16:19], v[168:171], v[204:207], v[16:19]
	v_mfma_f32_16x16x32_bf16 v[4:7], v[160:163], v[218:221], v[4:7]
	v_mfma_f32_16x16x32_bf16 v[0:3], v[168:171], v[218:221], v[0:3]
	v_mfma_f32_16x16x32_bf16 v[52:55], v[164:167], v[180:183], v[52:55]
	v_mfma_f32_16x16x32_bf16 v[48:51], v[172:175], v[180:183], v[48:51]
	v_mfma_f32_16x16x32_bf16 v[36:39], v[164:167], v[188:191], v[36:39]
	v_mfma_f32_16x16x32_bf16 v[32:35], v[172:175], v[188:191], v[32:35]
	v_mfma_f32_16x16x32_bf16 v[20:23], v[164:167], v[208:211], v[20:23]
	v_mfma_f32_16x16x32_bf16 v[16:19], v[172:175], v[208:211], v[16:19]
	v_mfma_f32_16x16x32_bf16 v[4:7], v[164:167], v[222:225], v[4:7]
	v_mfma_f32_16x16x32_bf16 v[0:3], v[172:175], v[222:225], v[0:3]
	s_setprio 0
	s_barrier
	v_add_u32_e32 v156, s49, v149
	v_add_u32_e32 v172, s64, v149
	ds_read_b128 v[140:143], v156
	ds_read_b128 v[144:147], v156 offset:1024
	ds_read_b128 v[152:155], v156 offset:2048
	ds_read_b128 v[156:159], v156 offset:3072
	ds_read_b128 v[160:163], v172
	ds_read_b128 v[164:167], v172 offset:1024
	ds_read_b128 v[168:171], v172 offset:2048
	ds_read_b128 v[172:175], v172 offset:3072
	s_add_u32 s8, s30, 0x40000
	s_addc_u32 s9, s31, 0
	s_mov_b32 m0, s45
	v_lshl_add_u64 v[234:235], s[8:9], 0, v[132:133]
	ds_read_b128 v[176:179], v151 offset:32768
	ds_read_b128 v[180:183], v151 offset:33792
	ds_read_b128 v[184:187], v151 offset:34816
	ds_read_b128 v[188:191], v151 offset:35840
	ds_read_b128 v[204:207], v151 offset:36864
	ds_read_b128 v[208:211], v151 offset:37888
	ds_read_b128 v[218:221], v151 offset:38912
	ds_read_b128 v[222:225], v151 offset:39936
	global_load_lds_dwordx4 v[234:235], off
	v_lshl_add_u64 v[234:235], s[8:9], 0, v[130:131]
	s_mov_b32 m0, s48
	s_nop 0
	global_load_lds_dwordx4 v[234:235], off
	s_waitcnt vmcnt(8)
	s_waitcnt lgkmcnt(0)
	s_barrier
	s_setprio 1
	s_waitcnt lgkmcnt(0)
	s_nop 0
	v_mfma_f32_16x16x32_bf16 v[116:119], v[140:143], v[176:179], v[116:119]
	v_mfma_f32_16x16x32_bf16 v[112:115], v[152:155], v[176:179], v[112:115]
	v_mfma_f32_16x16x32_bf16 v[108:111], v[140:143], v[184:187], v[108:111]
	v_mfma_f32_16x16x32_bf16 v[104:107], v[152:155], v[184:187], v[104:107]
	v_mfma_f32_16x16x32_bf16 v[92:95], v[140:143], v[204:207], v[92:95]
	v_mfma_f32_16x16x32_bf16 v[88:91], v[152:155], v[204:207], v[88:91]
	v_mfma_f32_16x16x32_bf16 v[76:79], v[140:143], v[218:221], v[76:79]
	v_mfma_f32_16x16x32_bf16 v[72:75], v[152:155], v[218:221], v[72:75]
	v_mfma_f32_16x16x32_bf16 v[116:119], v[144:147], v[180:183], v[116:119]
	v_mfma_f32_16x16x32_bf16 v[112:115], v[156:159], v[180:183], v[112:115]
	v_mfma_f32_16x16x32_bf16 v[108:111], v[144:147], v[188:191], v[108:111]
	v_mfma_f32_16x16x32_bf16 v[104:107], v[156:159], v[188:191], v[104:107]
	v_mfma_f32_16x16x32_bf16 v[92:95], v[144:147], v[208:211], v[92:95]
	v_mfma_f32_16x16x32_bf16 v[88:91], v[156:159], v[208:211], v[88:91]
	v_mfma_f32_16x16x32_bf16 v[76:79], v[144:147], v[222:225], v[76:79]
	v_mfma_f32_16x16x32_bf16 v[72:75], v[156:159], v[222:225], v[72:75]
	s_setprio 0
	s_setprio 1
	v_mfma_f32_16x16x32_bf16 v[124:127], v[160:163], v[176:179], v[124:127]
	v_mfma_f32_16x16x32_bf16 v[120:123], v[168:171], v[176:179], v[120:123]
	v_mfma_f32_16x16x32_bf16 v[100:103], v[160:163], v[184:187], v[100:103]
	v_mfma_f32_16x16x32_bf16 v[96:99], v[168:171], v[184:187], v[96:99]
	v_mfma_f32_16x16x32_bf16 v[84:87], v[160:163], v[204:207], v[84:87]
	v_mfma_f32_16x16x32_bf16 v[80:83], v[168:171], v[204:207], v[80:83]
	v_mfma_f32_16x16x32_bf16 v[68:71], v[160:163], v[218:221], v[68:71]
	v_mfma_f32_16x16x32_bf16 v[64:67], v[168:171], v[218:221], v[64:67]
	v_mfma_f32_16x16x32_bf16 v[124:127], v[164:167], v[180:183], v[124:127]
	v_mfma_f32_16x16x32_bf16 v[120:123], v[172:175], v[180:183], v[120:123]
	v_mfma_f32_16x16x32_bf16 v[100:103], v[164:167], v[188:191], v[100:103]
	v_mfma_f32_16x16x32_bf16 v[96:99], v[172:175], v[188:191], v[96:99]
	v_mfma_f32_16x16x32_bf16 v[84:87], v[164:167], v[208:211], v[84:87]
	v_mfma_f32_16x16x32_bf16 v[80:83], v[172:175], v[208:211], v[80:83]
	v_mfma_f32_16x16x32_bf16 v[68:71], v[164:167], v[222:225], v[68:71]
	v_mfma_f32_16x16x32_bf16 v[64:67], v[172:175], v[222:225], v[64:67]
	s_setprio 0
	s_barrier
; #define PG8_STAGE(bufoff, gbase, voff) do { _Pragma("unroll") for (int _i = 0; _i < 2; ++_i) \
;         __builtin_amdgcn_global_load_lds((const unsigned*)((const char*)(gbase) + (voff)[_i]), (PG8_LAS unsigned*)(lds + (bufoff) + ldsw + _i * 8192), 16, 0, 0); } while (0)
; #define PG8_LDA(dst, b, h) do { _Pragma("unroll") for (int m = 0; m < 4; ++m) _Pragma("unroll") for (int k = 0; k < 2; ++k) dst[m][k] = *(const PG8_LAS bf16x8*)(lds + PG8_SA(b, h) + aoff + m * 2048 + k * 1024); } while (0)
; #define PG8_MMA(ai, bj, At, Bt) do { __builtin_amdgcn_s_setprio(1); _Pragma("unroll") for (int m = 0; m < 4; ++m) _Pragma("unroll") for (int n = 0; n < 2; ++n) _Pragma("unroll") for (int k = 0; k < 2; ++k) \
;         acc[ai][bj][m][n] = __builtin_amdgcn_mfma_f32_16x16x32_bf16(Bt[n][k], At[m][k], acc[ai][bj][m][n], 0, 0, 0); __builtin_amdgcn_s_setprio(0); } while (0)
; #define PG8_WAIT_V(n) asm volatile("s_waitcnt vmcnt(" #n ")" ::: "memory")
; #define PG8_WAIT_L(n) asm volatile("s_waitcnt lgkmcnt(" #n ")" ::: "memory")
; #define PG8_BAR __builtin_amdgcn_s_barrier()
; #define PG8_SCHED __builtin_amdgcn_sched_barrier(0)
; template <class Epi, class Sched, bool ALIGN_EPI = false, bool SP2 = false>
; __device__ __forceinline__ void gemm_phase(PG8_LAS unsigned char* lds, const Gemm g, const Sched& S, const Epi& E) {
;     ...
;             PG8_LDA(At, 1, 1); PG8_STAGE(PG8_SB(1, 0), b3, voffB); PG8_STAGE(PG8_SB(1, 1), b3 + hstepB, voffB); PG8_STAGE(PG8_SA(1, 0), a3, voffA);
;             PG8_WAIT_V(8); PG8_WAIT_L(0); PG8_BAR; PG8_MMA(1, 0, At, B0); PG8_MMA(1, 1, At, B1); PG8_BAR; PG8_SCHED;
;     ...
;         if constexpr (ALIGN_EPI) { if (wr == 0) PG8_BAR; }
;         if constexpr (!Epi::AFTER_DRAIN) { E(acc, cur, wr, wc, fr, fq); S.done(cur); }
	s_mov_b32 m0, s50
	v_lshl_add_u64 v[226:227], v[226:227], 0, s[76:77]
	s_add_u32 s8, s28, 0x40080
	ds_read_b128 v[176:179], v151 offset:49152
	ds_read_b128 v[180:183], v151 offset:50176
	ds_read_b128 v[184:187], v151 offset:51200
	ds_read_b128 v[188:191], v151 offset:52224
	ds_read_b128 v[204:207], v151 offset:53248
	ds_read_b128 v[208:211], v151 offset:54272
	ds_read_b128 v[218:221], v151 offset:55296
	ds_read_b128 v[222:225], v151 offset:56320
	global_load_lds_dwordx4 v[226:227], off
	v_lshl_add_u64 v[226:227], v[228:229], 0, s[76:77]
	s_mov_b32 m0, s51
	s_addc_u32 s9, s29, 0
	global_load_lds_dwordx4 v[226:227], off
	v_lshl_add_u64 v[226:227], s[8:9], 0, v[192:193]
	s_mov_b32 m0, s65
	s_nop 0
	global_load_lds_dwordx4 v[226:227], off
	v_lshl_add_u64 v[226:227], s[8:9], 0, v[128:129]
	s_mov_b32 m0, s66
	s_nop 0
	global_load_lds_dwordx4 v[226:227], off
	v_lshl_add_u64 v[226:227], v[230:231], 0, s[76:77]
	s_mov_b32 m0, s60
	s_nop 0
	global_load_lds_dwordx4 v[226:227], off
	v_lshl_add_u64 v[226:227], v[232:233], 0, s[76:77]
	s_mov_b32 m0, s61
	s_nop 0
	global_load_lds_dwordx4 v[226:227], off
	s_waitcnt vmcnt(8)
	s_waitcnt lgkmcnt(0)
	s_barrier
	s_setprio 1
	s_waitcnt lgkmcnt(0)
	v_mfma_f32_16x16x32_bf16 v[60:63], v[140:143], v[176:179], v[60:63]
	v_mfma_f32_16x16x32_bf16 v[56:59], v[152:155], v[176:179], v[56:59]
	v_mfma_f32_16x16x32_bf16 v[44:47], v[140:143], v[184:187], v[44:47]
	v_mfma_f32_16x16x32_bf16 v[40:43], v[152:155], v[184:187], v[40:43]
	v_mfma_f32_16x16x32_bf16 v[28:31], v[140:143], v[204:207], v[28:31]
	v_mfma_f32_16x16x32_bf16 v[24:27], v[152:155], v[204:207], v[24:27]
	v_mfma_f32_16x16x32_bf16 v[12:15], v[140:143], v[218:221], v[12:15]
	v_mfma_f32_16x16x32_bf16 v[8:11], v[152:155], v[218:221], v[8:11]
	v_mfma_f32_16x16x32_bf16 v[60:63], v[144:147], v[180:183], v[60:63]
	v_mfma_f32_16x16x32_bf16 v[56:59], v[156:159], v[180:183], v[56:59]
	v_mfma_f32_16x16x32_bf16 v[44:47], v[144:147], v[188:191], v[44:47]
	v_mfma_f32_16x16x32_bf16 v[40:43], v[156:159], v[188:191], v[40:43]
	v_mfma_f32_16x16x32_bf16 v[28:31], v[144:147], v[208:211], v[28:31]
	v_mfma_f32_16x16x32_bf16 v[24:27], v[156:159], v[208:211], v[24:27]
	v_mfma_f32_16x16x32_bf16 v[12:15], v[144:147], v[222:225], v[12:15]
	v_mfma_f32_16x16x32_bf16 v[8:11], v[156:159], v[222:225], v[8:11]
	s_setprio 0
	s_setprio 1
	v_mfma_f32_16x16x32_bf16 v[52:55], v[160:163], v[176:179], v[52:55]
	v_mfma_f32_16x16x32_bf16 v[48:51], v[168:171], v[176:179], v[48:51]
	v_mfma_f32_16x16x32_bf16 v[36:39], v[160:163], v[184:187], v[36:39]
	v_mfma_f32_16x16x32_bf16 v[32:35], v[168:171], v[184:187], v[32:35]
	v_mfma_f32_16x16x32_bf16 v[20:23], v[160:163], v[204:207], v[20:23]
	v_mfma_f32_16x16x32_bf16 v[16:19], v[168:171], v[204:207], v[16:19]
	v_mfma_f32_16x16x32_bf16 v[4:7], v[160:163], v[218:221], v[4:7]
	v_mfma_f32_16x16x32_bf16 v[0:3], v[168:171], v[218:221], v[0:3]
	v_mfma_f32_16x16x32_bf16 v[52:55], v[164:167], v[180:183], v[52:55]
	v_mfma_f32_16x16x32_bf16 v[48:51], v[172:175], v[180:183], v[48:51]
	v_mfma_f32_16x16x32_bf16 v[36:39], v[164:167], v[188:191], v[36:39]
	v_mfma_f32_16x16x32_bf16 v[32:35], v[172:175], v[188:191], v[32:35]
	v_mfma_f32_16x16x32_bf16 v[20:23], v[164:167], v[208:211], v[20:23]
	v_mfma_f32_16x16x32_bf16 v[16:19], v[172:175], v[208:211], v[16:19]
	v_mfma_f32_16x16x32_bf16 v[4:7], v[164:167], v[222:225], v[4:7]
	v_mfma_f32_16x16x32_bf16 v[0:3], v[172:175], v[222:225], v[0:3]
	s_setprio 0
	s_barrier
	s_add_i32 s78, s78, 2
	s_add_u32 s74, s74, 0x100
	s_addc_u32 s75, s75, 0
	s_add_u32 s26, s26, 0x100
	s_addc_u32 s27, s27, 0
	s_cmp_gt_u32 s78, 13
	s_cbranch_scc0 .LBB0_156
	s_and_b64 vcc, exec, s[14:15]
	s_cbranch_vccz .LBB0_159
	s_barrier

; #define PG8_STAGE(bufoff, gbase, voff) do { _Pragma("unroll") for (int _i = 0; _i < 2; ++_i) \
;         __builtin_amdgcn_global_load_lds((const unsigned*)((const char*)(gbase) + (voff)[_i]), (PG8_LAS unsigned*)(lds + (bufoff) + ldsw + _i * 8192), 16, 0, 0); } while (0)
; #define PG8_LDA(dst, b, h) do { _Pragma("unroll") for (int m = 0; m < 4; ++m) _Pragma("unroll") for (int k = 0; k < 2; ++k) dst[m][k] = *(const PG8_LAS bf16x8*)(lds + PG8_SA(b, h) + aoff + m * 2048 + k * 1024); } while (0)
; #define PG8_LDB(dst, b, h) do { _Pragma("unroll") for (int n = 0; n < 2; ++n) _Pragma("unroll") for (int k = 0; k < 2; ++k) dst[n][k] = *(const PG8_LAS bf16x8*)(lds + PG8_SB(b, h) + boff + n * 2048 + k * 1024); } while (0)
; #define PG8_MMA(ai, bj, At, Bt) do { __builtin_amdgcn_s_setprio(1); _Pragma("unroll") for (int m = 0; m < 4; ++m) _Pragma("unroll") for (int n = 0; n < 2; ++n) _Pragma("unroll") for (int k = 0; k < 2; ++k) \
;         acc[ai][bj][m][n] = __builtin_amdgcn_mfma_f32_16x16x32_bf16(Bt[n][k], At[m][k], acc[ai][bj][m][n], 0, 0, 0); __builtin_amdgcn_s_setprio(0); } while (0)
; #define PG8_WAIT_V(n) asm volatile("s_waitcnt vmcnt(" #n ")" ::: "memory")
; #define PG8_BAR __builtin_amdgcn_s_barrier()
; template <class Epi, class Sched, bool ALIGN_EPI = false, bool SP2 = false>
; __device__ __forceinline__ void gemm_phase(PG8_LAS unsigned char* lds, const Gemm g, const Sched& S, const Epi& E) {
;     ...
;         for (int t = 0; t < nt; t += 2) {
;             const bool last = (t == nt - 2);
;             const char* a1 = cA + (size_t)(t + 1) * kstep;
;             const char* a2 = last ? nA : cA + (size_t)(t + 2) * kstep; const char* b2 = last ? nB : cB + (size_t)(t + 2) * kstep;
;             const char* a3 = a2 + kstep; const char* b3 = b2 + kstep;
;             if (last && has_next) S.a_ready(nxt);
;             if constexpr (SP2) {
;             PG8_LDB(B0, 0, 0); PG8_LDB(B1, 0, 1); PG8_SCHED; PG8_LDA(At, 0, 0); PG8_STAGE(PG8_SA(1, 1), a1 + hstepA, voffA);
;             PG8_WAIT_V(8); PG8_WAIT_L(0); PG8_BAR; PG8_MMA(0, 0, At, B0); PG8_MMA(0, 1, At, B1); PG8_BAR; PG8_SCHED;
;             PG8_LDA(At, 0, 1); PG8_STAGE(PG8_SB(0, 0), b2, voffB); PG8_STAGE(PG8_SB(0, 1), b2 + hstepB, voffB); PG8_STAGE(PG8_SA(0, 0), a2, voffA);
;             PG8_WAIT_V(8); PG8_WAIT_L(0); PG8_BAR; PG8_MMA(1, 0, At, B0); PG8_MMA(1, 1, At, B1); PG8_BAR; PG8_SCHED;
.LBB0_180:
	v_add_u32_e32 v154, s38, v139
	v_add_u32_e32 v170, s41, v139
	ds_read_b128 v[142:145], v154
	ds_read_b128 v[146:149], v154 offset:1024
	ds_read_b128 v[150:153], v154 offset:2048
	ds_read_b128 v[154:157], v154 offset:3072
	ds_read_b128 v[158:161], v170
	ds_read_b128 v[162:165], v170 offset:1024
	ds_read_b128 v[166:169], v170 offset:2048
	ds_read_b128 v[170:173], v170 offset:3072
	s_add_u32 s2, s24, 0xfffc0080
	s_addc_u32 s8, s25, -1
	s_cmp_eq_u32 s75, 12
	s_cselect_b32 s29, s1, s8
	s_cselect_b32 s28, s19, s2
	s_cselect_b32 s27, s17, s74
	s_cselect_b32 s26, s71, s72
	v_lshl_add_u64 v[190:191], s[24:25], 0, v[136:137]
	s_add_i32 m0, s44, 0xc000
	ds_read_b128 v[174:177], v141
	ds_read_b128 v[178:181], v141 offset:1024
	ds_read_b128 v[182:185], v141 offset:2048
	ds_read_b128 v[186:189], v141 offset:3072
	ds_read_b128 v[204:207], v141 offset:4096
	ds_read_b128 v[208:211], v141 offset:5120
	ds_read_b128 v[218:221], v141 offset:6144
	ds_read_b128 v[222:225], v141 offset:7168
	global_load_lds_dwordx4 v[190:191], off
	v_lshl_add_u64 v[190:191], s[24:25], 0, v[134:135]
	s_add_i32 m0, s44, 0xe000
	s_nop 0
	global_load_lds_dwordx4 v[190:191], off
	s_waitcnt vmcnt(8)
	s_waitcnt lgkmcnt(0)
	s_barrier
	s_setprio 1
	s_waitcnt lgkmcnt(0)
	v_mfma_f32_16x16x32_bf16 v[124:127], v[142:145], v[174:177], v[124:127]
	v_mfma_f32_16x16x32_bf16 v[120:123], v[150:153], v[174:177], v[120:123]
	v_mfma_f32_16x16x32_bf16 v[116:119], v[142:145], v[182:185], v[116:119]
	v_mfma_f32_16x16x32_bf16 v[112:115], v[150:153], v[182:185], v[112:115]
	v_mfma_f32_16x16x32_bf16 v[100:103], v[142:145], v[204:207], v[100:103]
	v_mfma_f32_16x16x32_bf16 v[96:99], v[150:153], v[204:207], v[96:99]
	v_mfma_f32_16x16x32_bf16 v[84:87], v[142:145], v[218:221], v[84:87]
	v_mfma_f32_16x16x32_bf16 v[80:83], v[150:153], v[218:221], v[80:83]
	v_mfma_f32_16x16x32_bf16 v[124:127], v[146:149], v[178:181], v[124:127]
	v_mfma_f32_16x16x32_bf16 v[120:123], v[154:157], v[178:181], v[120:123]
	v_mfma_f32_16x16x32_bf16 v[116:119], v[146:149], v[186:189], v[116:119]
	v_mfma_f32_16x16x32_bf16 v[112:115], v[154:157], v[186:189], v[112:115]
	v_mfma_f32_16x16x32_bf16 v[100:103], v[146:149], v[208:211], v[100:103]
	v_mfma_f32_16x16x32_bf16 v[96:99], v[154:157], v[208:211], v[96:99]
	v_mfma_f32_16x16x32_bf16 v[84:87], v[146:149], v[222:225], v[84:87]
	v_mfma_f32_16x16x32_bf16 v[80:83], v[154:157], v[222:225], v[80:83]
	s_setprio 0
	s_setprio 1
	v_mfma_f32_16x16x32_bf16 v[108:111], v[158:161], v[174:177], v[108:111]
	v_mfma_f32_16x16x32_bf16 v[104:107], v[166:169], v[174:177], v[104:107]
	v_mfma_f32_16x16x32_bf16 v[92:95], v[158:161], v[182:185], v[92:95]
	v_mfma_f32_16x16x32_bf16 v[88:91], v[166:169], v[182:185], v[88:91]
	v_mfma_f32_16x16x32_bf16 v[76:79], v[158:161], v[204:207], v[76:79]
	v_mfma_f32_16x16x32_bf16 v[72:75], v[166:169], v[204:207], v[72:75]
	v_mfma_f32_16x16x32_bf16 v[68:71], v[158:161], v[218:221], v[68:71]
	v_mfma_f32_16x16x32_bf16 v[64:67], v[166:169], v[218:221], v[64:67]
	v_mfma_f32_16x16x32_bf16 v[108:111], v[162:165], v[178:181], v[108:111]
	v_mfma_f32_16x16x32_bf16 v[104:107], v[170:173], v[178:181], v[104:107]
	v_mfma_f32_16x16x32_bf16 v[92:95], v[162:165], v[186:189], v[92:95]
	v_mfma_f32_16x16x32_bf16 v[88:91], v[170:173], v[186:189], v[88:91]
	v_mfma_f32_16x16x32_bf16 v[76:79], v[162:165], v[208:211], v[76:79]
	v_mfma_f32_16x16x32_bf16 v[72:75], v[170:173], v[208:211], v[72:75]
	v_mfma_f32_16x16x32_bf16 v[68:71], v[162:165], v[222:225], v[68:71]
	v_mfma_f32_16x16x32_bf16 v[64:67], v[170:173], v[222:225], v[64:67]
	s_setprio 0
	s_barrier
	s_mov_b32 m0, s39
	v_lshl_add_u64 v[190:191], s[26:27], 0, v[192:193]
	s_add_u32 s8, s26, 0x40000
	ds_read_b128 v[174:177], v141 offset:16384
	ds_read_b128 v[178:181], v141 offset:17408
	ds_read_b128 v[182:185], v141 offset:18432
	ds_read_b128 v[186:189], v141 offset:19456
	ds_read_b128 v[204:207], v141 offset:20480
	ds_read_b128 v[208:211], v141 offset:21504
	ds_read_b128 v[218:221], v141 offset:22528
	ds_read_b128 v[222:225], v141 offset:23552
	global_load_lds_dwordx4 v[190:191], off
	v_lshl_add_u64 v[226:227], s[26:27], 0, v[132:133]
	s_mov_b32 m0, s40
	s_addc_u32 s9, s27, 0
	global_load_lds_dwordx4 v[226:227], off
	v_lshl_add_u64 v[228:229], s[8:9], 0, v[192:193]
	s_mov_b32 m0, s42
	v_lshl_add_u64 v[230:231], s[28:29], 0, v[130:131]
	global_load_lds_dwordx4 v[228:229], off
	v_lshl_add_u64 v[228:229], s[8:9], 0, v[132:133]
	s_mov_b32 m0, s43
	s_nop 0
	global_load_lds_dwordx4 v[228:229], off
	v_lshl_add_u64 v[228:229], s[28:29], 0, v[128:129]
	s_mov_b32 m0, s44
	s_nop 0
	global_load_lds_dwordx4 v[228:229], off
	s_mov_b32 m0, s45
	s_nop 0
	global_load_lds_dwordx4 v[230:231], off
	s_waitcnt vmcnt(8)
	s_waitcnt lgkmcnt(0)
	s_barrier
; #define PG8_STAGE(bufoff, gbase, voff) do { _Pragma("unroll") for (int _i = 0; _i < 2; ++_i) \
;         __builtin_amdgcn_global_load_lds((const unsigned*)((const char*)(gbase) + (voff)[_i]), (PG8_LAS unsigned*)(lds + (bufoff) + ldsw + _i * 8192), 16, 0, 0); } while (0)
; #define PG8_LDA(dst, b, h) do { _Pragma("unroll") for (int m = 0; m < 4; ++m) _Pragma("unroll") for (int k = 0; k < 2; ++k) dst[m][k] = *(const PG8_LAS bf16x8*)(lds + PG8_SA(b, h) + aoff + m * 2048 + k * 1024); } while (0)
; #define PG8_LDB(dst, b, h) do { _Pragma("unroll") for (int n = 0; n < 2; ++n) _Pragma("unroll") for (int k = 0; k < 2; ++k) dst[n][k] = *(const PG8_LAS bf16x8*)(lds + PG8_SB(b, h) + boff + n * 2048 + k * 1024); } while (0)
; #define PG8_MMA(ai, bj, At, Bt) do { __builtin_amdgcn_s_setprio(1); _Pragma("unroll") for (int m = 0; m < 4; ++m) _Pragma("unroll") for (int n = 0; n < 2; ++n) _Pragma("unroll") for (int k = 0; k < 2; ++k) \
;         acc[ai][bj][m][n] = __builtin_amdgcn_mfma_f32_16x16x32_bf16(Bt[n][k], At[m][k], acc[ai][bj][m][n], 0, 0, 0); __builtin_amdgcn_s_setprio(0); } while (0)
; #define PG8_WAIT_V(n) asm volatile("s_waitcnt vmcnt(" #n ")" ::: "memory")
; #define PG8_WAIT_L(n) asm volatile("s_waitcnt lgkmcnt(" #n ")" ::: "memory")
; #define PG8_BAR __builtin_amdgcn_s_barrier()
; #define PG8_SCHED __builtin_amdgcn_sched_barrier(0)
; template <class Epi, class Sched, bool ALIGN_EPI = false, bool SP2 = false>
; __device__ __forceinline__ void gemm_phase(PG8_LAS unsigned char* lds, const Gemm g, const Sched& S, const Epi& E) {
;     ...
;             PG8_WAIT_V(8); PG8_WAIT_L(0); PG8_BAR; PG8_MMA(0, 0, At, B0); PG8_MMA(0, 1, At, B1); PG8_BAR; PG8_SCHED;
;             PG8_LDA(At, 0, 1); PG8_STAGE(PG8_SB(0, 0), b2, voffB); PG8_STAGE(PG8_SB(0, 1), b2 + hstepB, voffB); PG8_STAGE(PG8_SA(0, 0), a2, voffA);
;             PG8_WAIT_V(8); PG8_WAIT_L(0); PG8_BAR; PG8_MMA(1, 0, At, B0); PG8_MMA(1, 1, At, B1); PG8_BAR; PG8_SCHED;
;             PG8_LDB(B0, 1, 0); PG8_LDB(B1, 1, 1); PG8_SCHED; PG8_LDA(At, 1, 0); PG8_STAGE(PG8_SA(0, 1), a2 + hstepA, voffA);
;             PG8_WAIT_V(8); PG8_WAIT_L(0); PG8_BAR; PG8_MMA(0, 0, At, B0); PG8_MMA(0, 1, At, B1); PG8_BAR; PG8_SCHED;
	s_setprio 1
	s_waitcnt lgkmcnt(0)
	s_nop 0
	v_mfma_f32_16x16x32_bf16 v[60:63], v[142:145], v[174:177], v[60:63]
	v_mfma_f32_16x16x32_bf16 v[56:59], v[150:153], v[174:177], v[56:59]
	v_mfma_f32_16x16x32_bf16 v[52:55], v[142:145], v[182:185], v[52:55]
	v_mfma_f32_16x16x32_bf16 v[48:51], v[150:153], v[182:185], v[48:51]
	v_mfma_f32_16x16x32_bf16 v[36:39], v[142:145], v[204:207], v[36:39]
	v_mfma_f32_16x16x32_bf16 v[32:35], v[150:153], v[204:207], v[32:35]
	v_mfma_f32_16x16x32_bf16 v[20:23], v[142:145], v[218:221], v[20:23]
	v_mfma_f32_16x16x32_bf16 v[16:19], v[150:153], v[218:221], v[16:19]
	v_mfma_f32_16x16x32_bf16 v[60:63], v[146:149], v[178:181], v[60:63]
	v_mfma_f32_16x16x32_bf16 v[56:59], v[154:157], v[178:181], v[56:59]
	v_mfma_f32_16x16x32_bf16 v[52:55], v[146:149], v[186:189], v[52:55]
	v_mfma_f32_16x16x32_bf16 v[48:51], v[154:157], v[186:189], v[48:51]
	v_mfma_f32_16x16x32_bf16 v[36:39], v[146:149], v[208:211], v[36:39]
	v_mfma_f32_16x16x32_bf16 v[32:35], v[154:157], v[208:211], v[32:35]
	v_mfma_f32_16x16x32_bf16 v[20:23], v[146:149], v[222:225], v[20:23]
	v_mfma_f32_16x16x32_bf16 v[16:19], v[154:157], v[222:225], v[16:19]
	s_setprio 0
	s_setprio 1
	v_mfma_f32_16x16x32_bf16 v[44:47], v[158:161], v[174:177], v[44:47]
	v_mfma_f32_16x16x32_bf16 v[40:43], v[166:169], v[174:177], v[40:43]
	v_mfma_f32_16x16x32_bf16 v[28:31], v[158:161], v[182:185], v[28:31]
	v_mfma_f32_16x16x32_bf16 v[24:27], v[166:169], v[182:185], v[24:27]
	v_mfma_f32_16x16x32_bf16 v[12:15], v[158:161], v[204:207], v[12:15]
	v_mfma_f32_16x16x32_bf16 v[8:11], v[166:169], v[204:207], v[8:11]
	v_mfma_f32_16x16x32_bf16 v[4:7], v[158:161], v[218:221], v[4:7]
	v_mfma_f32_16x16x32_bf16 v[0:3], v[166:169], v[218:221], v[0:3]
	v_mfma_f32_16x16x32_bf16 v[44:47], v[162:165], v[178:181], v[44:47]
	v_mfma_f32_16x16x32_bf16 v[40:43], v[170:173], v[178:181], v[40:43]
	v_mfma_f32_16x16x32_bf16 v[28:31], v[162:165], v[186:189], v[28:31]
	v_mfma_f32_16x16x32_bf16 v[24:27], v[170:173], v[186:189], v[24:27]
	v_mfma_f32_16x16x32_bf16 v[12:15], v[162:165], v[208:211], v[12:15]
	v_mfma_f32_16x16x32_bf16 v[8:11], v[170:173], v[208:211], v[8:11]
	v_mfma_f32_16x16x32_bf16 v[4:7], v[162:165], v[222:225], v[4:7]
	v_mfma_f32_16x16x32_bf16 v[0:3], v[170:173], v[222:225], v[0:3]
	s_setprio 0
	s_barrier
	v_add_u32_e32 v154, s50, v139
	v_add_u32_e32 v170, s65, v139
	ds_read_b128 v[142:145], v154
	ds_read_b128 v[146:149], v154 offset:1024
	ds_read_b128 v[150:153], v154 offset:2048
	ds_read_b128 v[154:157], v154 offset:3072
	ds_read_b128 v[158:161], v170
	ds_read_b128 v[162:165], v170 offset:1024
	ds_read_b128 v[166:169], v170 offset:2048
	ds_read_b128 v[170:173], v170 offset:3072
	s_add_u32 s8, s28, 0x40000
	s_addc_u32 s9, s29, 0
	s_mov_b32 m0, s48
	v_lshl_add_u64 v[232:233], s[8:9], 0, v[128:129]
	ds_read_b128 v[174:177], v141 offset:32768
	ds_read_b128 v[178:181], v141 offset:33792
	ds_read_b128 v[182:185], v141 offset:34816
	ds_read_b128 v[186:189], v141 offset:35840
	ds_read_b128 v[204:207], v141 offset:36864
	ds_read_b128 v[208:211], v141 offset:37888
	ds_read_b128 v[218:221], v141 offset:38912
	ds_read_b128 v[222:225], v141 offset:39936
	global_load_lds_dwordx4 v[232:233], off
	v_lshl_add_u64 v[232:233], s[8:9], 0, v[130:131]
	s_mov_b32 m0, s49
	s_nop 0
	global_load_lds_dwordx4 v[232:233], off
	s_waitcnt vmcnt(8)
	s_waitcnt lgkmcnt(0)
	s_barrier
	s_setprio 1
	s_waitcnt lgkmcnt(0)
	s_nop 0
	v_mfma_f32_16x16x32_bf16 v[124:127], v[142:145], v[174:177], v[124:127]
	v_mfma_f32_16x16x32_bf16 v[120:123], v[150:153], v[174:177], v[120:123]
	v_mfma_f32_16x16x32_bf16 v[116:119], v[142:145], v[182:185], v[116:119]
	v_mfma_f32_16x16x32_bf16 v[112:115], v[150:153], v[182:185], v[112:115]
	v_mfma_f32_16x16x32_bf16 v[100:103], v[142:145], v[204:207], v[100:103]
	v_mfma_f32_16x16x32_bf16 v[96:99], v[150:153], v[204:207], v[96:99]
	v_mfma_f32_16x16x32_bf16 v[84:87], v[142:145], v[218:221], v[84:87]
	v_mfma_f32_16x16x32_bf16 v[80:83], v[150:153], v[218:221], v[80:83]
	v_mfma_f32_16x16x32_bf16 v[124:127], v[146:149], v[178:181], v[124:127]
	v_mfma_f32_16x16x32_bf16 v[120:123], v[154:157], v[178:181], v[120:123]
	v_mfma_f32_16x16x32_bf16 v[116:119], v[146:149], v[186:189], v[116:119]
	v_mfma_f32_16x16x32_bf16 v[112:115], v[154:157], v[186:189], v[112:115]
	v_mfma_f32_16x16x32_bf16 v[100:103], v[146:149], v[208:211], v[100:103]
	v_mfma_f32_16x16x32_bf16 v[96:99], v[154:157], v[208:211], v[96:99]
	v_mfma_f32_16x16x32_bf16 v[84:87], v[146:149], v[222:225], v[84:87]
	v_mfma_f32_16x16x32_bf16 v[80:83], v[154:157], v[222:225], v[80:83]
	s_setprio 0
	s_setprio 1
	v_mfma_f32_16x16x32_bf16 v[108:111], v[158:161], v[174:177], v[108:111]
	v_mfma_f32_16x16x32_bf16 v[104:107], v[166:169], v[174:177], v[104:107]
	v_mfma_f32_16x16x32_bf16 v[92:95], v[158:161], v[182:185], v[92:95]
	v_mfma_f32_16x16x32_bf16 v[88:91], v[166:169], v[182:185], v[88:91]
	v_mfma_f32_16x16x32_bf16 v[76:79], v[158:161], v[204:207], v[76:79]
	v_mfma_f32_16x16x32_bf16 v[72:75], v[166:169], v[204:207], v[72:75]
	v_mfma_f32_16x16x32_bf16 v[68:71], v[158:161], v[218:221], v[68:71]
	v_mfma_f32_16x16x32_bf16 v[64:67], v[166:169], v[218:221], v[64:67]
	v_mfma_f32_16x16x32_bf16 v[108:111], v[162:165], v[178:181], v[108:111]
	v_mfma_f32_16x16x32_bf16 v[104:107], v[170:173], v[178:181], v[104:107]
	v_mfma_f32_16x16x32_bf16 v[92:95], v[162:165], v[186:189], v[92:95]
	v_mfma_f32_16x16x32_bf16 v[88:91], v[170:173], v[186:189], v[88:91]
	v_mfma_f32_16x16x32_bf16 v[76:79], v[162:165], v[208:211], v[76:79]
	v_mfma_f32_16x16x32_bf16 v[72:75], v[170:173], v[208:211], v[72:75]
	v_mfma_f32_16x16x32_bf16 v[68:71], v[162:165], v[222:225], v[68:71]
	v_mfma_f32_16x16x32_bf16 v[64:67], v[170:173], v[222:225], v[64:67]
	s_setprio 0
	s_barrier
; #define PG8_STAGE(bufoff, gbase, voff) do { _Pragma("unroll") for (int _i = 0; _i < 2; ++_i) \
;         __builtin_amdgcn_global_load_lds((const unsigned*)((const char*)(gbase) + (voff)[_i]), (PG8_LAS unsigned*)(lds + (bufoff) + ldsw + _i * 8192), 16, 0, 0); } while (0)
; #define PG8_LDA(dst, b, h) do { _Pragma("unroll") for (int m = 0; m < 4; ++m) _Pragma("unroll") for (int k = 0; k < 2; ++k) dst[m][k] = *(const PG8_LAS bf16x8*)(lds + PG8_SA(b, h) + aoff + m * 2048 + k * 1024); } while (0)
; #define PG8_MMA(ai, bj, At, Bt) do { __builtin_amdgcn_s_setprio(1); _Pragma("unroll") for (int m = 0; m < 4; ++m) _Pragma("unroll") for (int n = 0; n < 2; ++n) _Pragma("unroll") for (int k = 0; k < 2; ++k) \
;         acc[ai][bj][m][n] = __builtin_amdgcn_mfma_f32_16x16x32_bf16(Bt[n][k], At[m][k], acc[ai][bj][m][n], 0, 0, 0); __builtin_amdgcn_s_setprio(0); } while (0)
; #define PG8_WAIT_V(n) asm volatile("s_waitcnt vmcnt(" #n ")" ::: "memory")
; #define PG8_WAIT_L(n) asm volatile("s_waitcnt lgkmcnt(" #n ")" ::: "memory")
; #define PG8_BAR __builtin_amdgcn_s_barrier()
; #define PG8_SCHED __builtin_amdgcn_sched_barrier(0)
; template <class Epi, class Sched, bool ALIGN_EPI = false, bool SP2 = false>
; __device__ __forceinline__ void gemm_phase(PG8_LAS unsigned char* lds, const Gemm g, const Sched& S, const Epi& E) {
;     ...
;             PG8_LDA(At, 1, 1); PG8_STAGE(PG8_SB(1, 0), b3, voffB); PG8_STAGE(PG8_SB(1, 1), b3 + hstepB, voffB); PG8_STAGE(PG8_SA(1, 0), a3, voffA);
;             PG8_WAIT_V(8); PG8_WAIT_L(0); PG8_BAR; PG8_MMA(1, 0, At, B0); PG8_MMA(1, 1, At, B1); PG8_BAR; PG8_SCHED;
;     ...
;         if constexpr (ALIGN_EPI) { if (wr == 0) PG8_BAR; }
;         if constexpr (!Epi::AFTER_DRAIN) { E(acc, cur, wr, wc, fr, fq); S.done(cur); }
	s_mov_b32 m0, s51
	v_lshl_add_u64 v[190:191], v[190:191], 0, s[76:77]
	s_add_u32 s8, s26, 0x40080
	ds_read_b128 v[174:177], v141 offset:49152
	ds_read_b128 v[178:181], v141 offset:50176
	ds_read_b128 v[182:185], v141 offset:51200
	ds_read_b128 v[186:189], v141 offset:52224
	ds_read_b128 v[204:207], v141 offset:53248
	ds_read_b128 v[208:211], v141 offset:54272
	ds_read_b128 v[218:221], v141 offset:55296
	ds_read_b128 v[222:225], v141 offset:56320
	global_load_lds_dwordx4 v[190:191], off
	v_lshl_add_u64 v[190:191], v[226:227], 0, s[76:77]
	s_mov_b32 m0, s60
	s_addc_u32 s9, s27, 0
	global_load_lds_dwordx4 v[190:191], off
	v_lshl_add_u64 v[190:191], s[8:9], 0, v[192:193]
	s_mov_b32 m0, s66
	s_nop 0
	global_load_lds_dwordx4 v[190:191], off
	v_lshl_add_u64 v[190:191], s[8:9], 0, v[132:133]
	s_mov_b32 m0, s67
	s_nop 0
	global_load_lds_dwordx4 v[190:191], off
	v_lshl_add_u64 v[190:191], v[228:229], 0, s[76:77]
	s_mov_b32 m0, s61
	s_nop 0
	global_load_lds_dwordx4 v[190:191], off
	v_lshl_add_u64 v[190:191], v[230:231], 0, s[76:77]
	s_mov_b32 m0, s64
	s_nop 0
	global_load_lds_dwordx4 v[190:191], off
	s_waitcnt vmcnt(8)
	s_waitcnt lgkmcnt(0)
	s_barrier
	s_setprio 1
	s_waitcnt lgkmcnt(0)
	v_mfma_f32_16x16x32_bf16 v[60:63], v[142:145], v[174:177], v[60:63]
	v_mfma_f32_16x16x32_bf16 v[56:59], v[150:153], v[174:177], v[56:59]
	v_mfma_f32_16x16x32_bf16 v[52:55], v[142:145], v[182:185], v[52:55]
	v_mfma_f32_16x16x32_bf16 v[48:51], v[150:153], v[182:185], v[48:51]
	v_mfma_f32_16x16x32_bf16 v[36:39], v[142:145], v[204:207], v[36:39]
	v_mfma_f32_16x16x32_bf16 v[32:35], v[150:153], v[204:207], v[32:35]
	v_mfma_f32_16x16x32_bf16 v[20:23], v[142:145], v[218:221], v[20:23]
	v_mfma_f32_16x16x32_bf16 v[16:19], v[150:153], v[218:221], v[16:19]
	v_mfma_f32_16x16x32_bf16 v[60:63], v[146:149], v[178:181], v[60:63]
	v_mfma_f32_16x16x32_bf16 v[56:59], v[154:157], v[178:181], v[56:59]
	v_mfma_f32_16x16x32_bf16 v[52:55], v[146:149], v[186:189], v[52:55]
	v_mfma_f32_16x16x32_bf16 v[48:51], v[154:157], v[186:189], v[48:51]
	v_mfma_f32_16x16x32_bf16 v[36:39], v[146:149], v[208:211], v[36:39]
	v_mfma_f32_16x16x32_bf16 v[32:35], v[154:157], v[208:211], v[32:35]
	v_mfma_f32_16x16x32_bf16 v[20:23], v[146:149], v[222:225], v[20:23]
	v_mfma_f32_16x16x32_bf16 v[16:19], v[154:157], v[222:225], v[16:19]
	s_setprio 0
	s_setprio 1
	v_mfma_f32_16x16x32_bf16 v[44:47], v[158:161], v[174:177], v[44:47]
	v_mfma_f32_16x16x32_bf16 v[40:43], v[166:169], v[174:177], v[40:43]
	v_mfma_f32_16x16x32_bf16 v[28:31], v[158:161], v[182:185], v[28:31]
	v_mfma_f32_16x16x32_bf16 v[24:27], v[166:169], v[182:185], v[24:27]
	v_mfma_f32_16x16x32_bf16 v[12:15], v[158:161], v[204:207], v[12:15]
	v_mfma_f32_16x16x32_bf16 v[8:11], v[166:169], v[204:207], v[8:11]
	v_mfma_f32_16x16x32_bf16 v[4:7], v[158:161], v[218:221], v[4:7]
	v_mfma_f32_16x16x32_bf16 v[0:3], v[166:169], v[218:221], v[0:3]
	v_mfma_f32_16x16x32_bf16 v[44:47], v[162:165], v[178:181], v[44:47]
	v_mfma_f32_16x16x32_bf16 v[40:43], v[170:173], v[178:181], v[40:43]
	v_mfma_f32_16x16x32_bf16 v[28:31], v[162:165], v[186:189], v[28:31]
	v_mfma_f32_16x16x32_bf16 v[24:27], v[170:173], v[186:189], v[24:27]
	v_mfma_f32_16x16x32_bf16 v[12:15], v[162:165], v[208:211], v[12:15]
	v_mfma_f32_16x16x32_bf16 v[8:11], v[170:173], v[208:211], v[8:11]
	v_mfma_f32_16x16x32_bf16 v[4:7], v[162:165], v[222:225], v[4:7]
	v_mfma_f32_16x16x32_bf16 v[0:3], v[170:173], v[222:225], v[0:3]
	s_setprio 0
	s_barrier
	s_add_i32 s75, s75, 2
	s_add_u32 s72, s72, 0x100
	s_addc_u32 s74, s74, 0
	s_add_u32 s24, s24, 0x100
	s_addc_u32 s25, s25, 0
	s_cmp_gt_u32 s75, 13
	s_cbranch_scc0 .LBB0_180
	s_and_b64 vcc, exec, s[10:11]
	s_cbranch_vccz .LBB0_183
	s_barrier

; #define PG8_STAGE(bufoff, gbase, voff) do { _Pragma("unroll") for (int _i = 0; _i < 2; ++_i) \
;         __builtin_amdgcn_global_load_lds((const unsigned*)((const char*)(gbase) + (voff)[_i]), (PG8_LAS unsigned*)(lds + (bufoff) + ldsw + _i * 8192), 16, 0, 0); } while (0)
; #define PG8_LDA(dst, b, h) do { _Pragma("unroll") for (int m = 0; m < 4; ++m) _Pragma("unroll") for (int k = 0; k < 2; ++k) dst[m][k] = *(const PG8_LAS bf16x8*)(lds + PG8_SA(b, h) + aoff + m * 2048 + k * 1024); } while (0)
; #define PG8_LDB(dst, b, h) do { _Pragma("unroll") for (int n = 0; n < 2; ++n) _Pragma("unroll") for (int k = 0; k < 2; ++k) dst[n][k] = *(const PG8_LAS bf16x8*)(lds + PG8_SB(b, h) + boff + n * 2048 + k * 1024); } while (0)
; #define PG8_MMA(ai, bj, At, Bt) do { __builtin_amdgcn_s_setprio(1); _Pragma("unroll") for (int m = 0; m < 4; ++m) _Pragma("unroll") for (int n = 0; n < 2; ++n) _Pragma("unroll") for (int k = 0; k < 2; ++k) \
;         acc[ai][bj][m][n] = __builtin_amdgcn_mfma_f32_16x16x32_bf16(Bt[n][k], At[m][k], acc[ai][bj][m][n], 0, 0, 0); __builtin_amdgcn_s_setprio(0); } while (0)
; #define PG8_WAIT_V(n) asm volatile("s_waitcnt vmcnt(" #n ")" ::: "memory")
; #define PG8_BAR __builtin_amdgcn_s_barrier()
; template <class Epi, class Sched, bool ALIGN_EPI = false, bool SP2 = false>
; __device__ __forceinline__ void gemm_phase(PG8_LAS unsigned char* lds, const Gemm g, const Sched& S, const Epi& E) {
;     ...
;         for (int t = 0; t < nt; t += 2) {
;             const bool last = (t == nt - 2);
;             const char* a1 = cA + (size_t)(t + 1) * kstep;
;             const char* a2 = last ? nA : cA + (size_t)(t + 2) * kstep; const char* b2 = last ? nB : cB + (size_t)(t + 2) * kstep;
;             const char* a3 = a2 + kstep; const char* b3 = b2 + kstep;
;             if (last && has_next) S.a_ready(nxt);
;             if constexpr (SP2) {
;             PG8_LDB(B0, 0, 0); PG8_LDB(B1, 0, 1); PG8_SCHED; PG8_LDA(At, 0, 0); PG8_STAGE(PG8_SA(1, 1), a1 + hstepA, voffA);
;             PG8_WAIT_V(8); PG8_WAIT_L(0); PG8_BAR; PG8_MMA(0, 0, At, B0); PG8_MMA(0, 1, At, B1); PG8_BAR; PG8_SCHED;
;             PG8_LDA(At, 0, 1); PG8_STAGE(PG8_SB(0, 0), b2, voffB); PG8_STAGE(PG8_SB(0, 1), b2 + hstepB, voffB); PG8_STAGE(PG8_SA(0, 0), a2, voffA);
;             PG8_WAIT_V(8); PG8_WAIT_L(0); PG8_BAR; PG8_MMA(1, 0, At, B0); PG8_MMA(1, 1, At, B1); PG8_BAR; PG8_SCHED;
.LBB0_278:
	v_add_u32_e32 v142, s35, v145
	ds_read_b128 v[138:141], v142
	ds_read_b128 v[148:151], v142 offset:1024
	ds_read_b128 v[152:155], v142 offset:2048
	ds_read_b128 v[156:159], v142 offset:3072
	v_add_u32_e32 v142, s38, v145
	ds_read_b128 v[160:163], v142
	ds_read_b128 v[164:167], v142 offset:1024
	ds_read_b128 v[168:171], v142 offset:2048
	ds_read_b128 v[172:175], v142 offset:3072
	s_add_u32 s22, s20, 0x100
	s_addc_u32 s23, s21, 0
	s_cmp_eq_u32 s78, 40
	s_cselect_b32 s27, s9, s23
	s_cselect_b32 s26, s8, s22
	s_cselect_b32 s25, s19, s75
	s_cselect_b32 s24, s18, s74
	v_lshl_add_u64 v[142:143], s[20:21], 0, v[136:137]
	s_add_i32 m0, s41, 0xc000
	ds_read_b128 v[176:179], v147
	ds_read_b128 v[180:183], v147 offset:1024
	ds_read_b128 v[184:187], v147 offset:2048
	ds_read_b128 v[188:191], v147 offset:3072
	ds_read_b128 v[204:207], v147 offset:4096
	ds_read_b128 v[208:211], v147 offset:5120
	ds_read_b128 v[218:221], v147 offset:6144
	ds_read_b128 v[222:225], v147 offset:7168
	global_load_lds_dwordx4 v[142:143], off
	v_lshl_add_u64 v[142:143], s[20:21], 0, v[134:135]
	s_add_i32 m0, s41, 0xe000
	s_nop 0
	global_load_lds_dwordx4 v[142:143], off
	s_waitcnt vmcnt(8)
	s_waitcnt lgkmcnt(0)
	s_barrier
	s_setprio 1
	s_waitcnt lgkmcnt(0)
	s_nop 0
	v_mfma_f32_16x16x32_bf16 v[124:127], v[138:141], v[176:179], v[124:127]
	v_mfma_f32_16x16x32_bf16 v[120:123], v[152:155], v[176:179], v[120:123]
	v_mfma_f32_16x16x32_bf16 v[108:111], v[138:141], v[184:187], v[108:111]
	v_mfma_f32_16x16x32_bf16 v[104:107], v[152:155], v[184:187], v[104:107]
	v_mfma_f32_16x16x32_bf16 v[92:95], v[138:141], v[204:207], v[92:95]
	v_mfma_f32_16x16x32_bf16 v[88:91], v[152:155], v[204:207], v[88:91]
	v_mfma_f32_16x16x32_bf16 v[76:79], v[138:141], v[218:221], v[76:79]
	v_mfma_f32_16x16x32_bf16 v[72:75], v[152:155], v[218:221], v[72:75]
	v_mfma_f32_16x16x32_bf16 v[124:127], v[148:151], v[180:183], v[124:127]
	v_mfma_f32_16x16x32_bf16 v[120:123], v[156:159], v[180:183], v[120:123]
	v_mfma_f32_16x16x32_bf16 v[108:111], v[148:151], v[188:191], v[108:111]
	v_mfma_f32_16x16x32_bf16 v[104:107], v[156:159], v[188:191], v[104:107]
	v_mfma_f32_16x16x32_bf16 v[92:95], v[148:151], v[208:211], v[92:95]
	v_mfma_f32_16x16x32_bf16 v[88:91], v[156:159], v[208:211], v[88:91]
	v_mfma_f32_16x16x32_bf16 v[76:79], v[148:151], v[222:225], v[76:79]
	v_mfma_f32_16x16x32_bf16 v[72:75], v[156:159], v[222:225], v[72:75]
	s_setprio 0
	s_setprio 1
	v_mfma_f32_16x16x32_bf16 v[116:119], v[160:163], v[176:179], v[116:119]
	v_mfma_f32_16x16x32_bf16 v[112:115], v[168:171], v[176:179], v[112:115]
	v_mfma_f32_16x16x32_bf16 v[100:103], v[160:163], v[184:187], v[100:103]
	v_mfma_f32_16x16x32_bf16 v[96:99], v[168:171], v[184:187], v[96:99]
	v_mfma_f32_16x16x32_bf16 v[84:87], v[160:163], v[204:207], v[84:87]
	v_mfma_f32_16x16x32_bf16 v[80:83], v[168:171], v[204:207], v[80:83]
	v_mfma_f32_16x16x32_bf16 v[68:71], v[160:163], v[218:221], v[68:71]
	v_mfma_f32_16x16x32_bf16 v[64:67], v[168:171], v[218:221], v[64:67]
	v_mfma_f32_16x16x32_bf16 v[116:119], v[164:167], v[180:183], v[116:119]
	v_mfma_f32_16x16x32_bf16 v[112:115], v[172:175], v[180:183], v[112:115]
	v_mfma_f32_16x16x32_bf16 v[100:103], v[164:167], v[188:191], v[100:103]
	v_mfma_f32_16x16x32_bf16 v[96:99], v[172:175], v[188:191], v[96:99]
	v_mfma_f32_16x16x32_bf16 v[84:87], v[164:167], v[208:211], v[84:87]
	v_mfma_f32_16x16x32_bf16 v[80:83], v[172:175], v[208:211], v[80:83]
	v_mfma_f32_16x16x32_bf16 v[68:71], v[164:167], v[222:225], v[68:71]
	v_mfma_f32_16x16x32_bf16 v[64:67], v[172:175], v[222:225], v[64:67]
	s_setprio 0
	s_barrier
	s_mov_b32 m0, s36
	v_lshl_add_u64 v[142:143], s[24:25], 0, v[192:193]
	s_add_u32 s20, s24, 0xb0000
	ds_read_b128 v[176:179], v147 offset:16384
	ds_read_b128 v[180:183], v147 offset:17408
	ds_read_b128 v[184:187], v147 offset:18432
	ds_read_b128 v[188:191], v147 offset:19456
	ds_read_b128 v[204:207], v147 offset:20480
	ds_read_b128 v[208:211], v147 offset:21504
	ds_read_b128 v[218:221], v147 offset:22528
	ds_read_b128 v[222:225], v147 offset:23552
	global_load_lds_dwordx4 v[142:143], off
	v_lshl_add_u64 v[226:227], s[24:25], 0, v[132:133]
	s_mov_b32 m0, s37
	s_addc_u32 s21, s25, 0
	global_load_lds_dwordx4 v[226:227], off
	v_lshl_add_u64 v[228:229], s[20:21], 0, v[192:193]
	s_mov_b32 m0, s39
	v_lshl_add_u64 v[230:231], s[26:27], 0, v[130:131]
	global_load_lds_dwordx4 v[228:229], off
	v_lshl_add_u64 v[228:229], s[20:21], 0, v[132:133]
	s_mov_b32 m0, s40
	s_nop 0
	global_load_lds_dwordx4 v[228:229], off
	v_lshl_add_u64 v[228:229], s[26:27], 0, v[128:129]
	s_mov_b32 m0, s41
	s_nop 0
	global_load_lds_dwordx4 v[228:229], off
	s_mov_b32 m0, s42
	s_nop 0
	global_load_lds_dwordx4 v[230:231], off
	s_waitcnt vmcnt(8)
	s_waitcnt lgkmcnt(0)
	s_barrier
; #define PG8_STAGE(bufoff, gbase, voff) do { _Pragma("unroll") for (int _i = 0; _i < 2; ++_i) \
;         __builtin_amdgcn_global_load_lds((const unsigned*)((const char*)(gbase) + (voff)[_i]), (PG8_LAS unsigned*)(lds + (bufoff) + ldsw + _i * 8192), 16, 0, 0); } while (0)
; #define PG8_LDA(dst, b, h) do { _Pragma("unroll") for (int m = 0; m < 4; ++m) _Pragma("unroll") for (int k = 0; k < 2; ++k) dst[m][k] = *(const PG8_LAS bf16x8*)(lds + PG8_SA(b, h) + aoff + m * 2048 + k * 1024); } while (0)
; #define PG8_LDB(dst, b, h) do { _Pragma("unroll") for (int n = 0; n < 2; ++n) _Pragma("unroll") for (int k = 0; k < 2; ++k) dst[n][k] = *(const PG8_LAS bf16x8*)(lds + PG8_SB(b, h) + boff + n * 2048 + k * 1024); } while (0)
; #define PG8_MMA(ai, bj, At, Bt) do { __builtin_amdgcn_s_setprio(1); _Pragma("unroll") for (int m = 0; m < 4; ++m) _Pragma("unroll") for (int n = 0; n < 2; ++n) _Pragma("unroll") for (int k = 0; k < 2; ++k) \
;         acc[ai][bj][m][n] = __builtin_amdgcn_mfma_f32_16x16x32_bf16(Bt[n][k], At[m][k], acc[ai][bj][m][n], 0, 0, 0); __builtin_amdgcn_s_setprio(0); } while (0)
; #define PG8_WAIT_V(n) asm volatile("s_waitcnt vmcnt(" #n ")" ::: "memory")
; #define PG8_WAIT_L(n) asm volatile("s_waitcnt lgkmcnt(" #n ")" ::: "memory")
; #define PG8_BAR __builtin_amdgcn_s_barrier()
; #define PG8_SCHED __builtin_amdgcn_sched_barrier(0)
; template <class Epi, class Sched, bool ALIGN_EPI = false, bool SP2 = false>
; __device__ __forceinline__ void gemm_phase(PG8_LAS unsigned char* lds, const Gemm g, const Sched& S, const Epi& E) {
;     ...
;             PG8_WAIT_V(8); PG8_WAIT_L(0); PG8_BAR; PG8_MMA(0, 0, At, B0); PG8_MMA(0, 1, At, B1); PG8_BAR; PG8_SCHED;
;             PG8_LDA(At, 0, 1); PG8_STAGE(PG8_SB(0, 0), b2, voffB); PG8_STAGE(PG8_SB(0, 1), b2 + hstepB, voffB); PG8_STAGE(PG8_SA(0, 0), a2, voffA);
;             PG8_WAIT_V(8); PG8_WAIT_L(0); PG8_BAR; PG8_MMA(1, 0, At, B0); PG8_MMA(1, 1, At, B1); PG8_BAR; PG8_SCHED;
;             PG8_LDB(B0, 1, 0); PG8_LDB(B1, 1, 1); PG8_SCHED; PG8_LDA(At, 1, 0); PG8_STAGE(PG8_SA(0, 1), a2 + hstepA, voffA);
;             PG8_WAIT_V(8); PG8_WAIT_L(0); PG8_BAR; PG8_MMA(0, 0, At, B0); PG8_MMA(0, 1, At, B1); PG8_BAR; PG8_SCHED;
	s_setprio 1
	s_waitcnt lgkmcnt(0)
	s_nop 0
	v_mfma_f32_16x16x32_bf16 v[60:63], v[138:141], v[176:179], v[60:63]
	v_mfma_f32_16x16x32_bf16 v[56:59], v[152:155], v[176:179], v[56:59]
	v_mfma_f32_16x16x32_bf16 v[44:47], v[138:141], v[184:187], v[44:47]
	v_mfma_f32_16x16x32_bf16 v[40:43], v[152:155], v[184:187], v[40:43]
	v_mfma_f32_16x16x32_bf16 v[28:31], v[138:141], v[204:207], v[28:31]
	v_mfma_f32_16x16x32_bf16 v[24:27], v[152:155], v[204:207], v[24:27]
	v_mfma_f32_16x16x32_bf16 v[12:15], v[138:141], v[218:221], v[12:15]
	v_mfma_f32_16x16x32_bf16 v[8:11], v[152:155], v[218:221], v[8:11]
	v_mfma_f32_16x16x32_bf16 v[60:63], v[148:151], v[180:183], v[60:63]
	v_mfma_f32_16x16x32_bf16 v[56:59], v[156:159], v[180:183], v[56:59]
	v_mfma_f32_16x16x32_bf16 v[44:47], v[148:151], v[188:191], v[44:47]
	v_mfma_f32_16x16x32_bf16 v[40:43], v[156:159], v[188:191], v[40:43]
	v_mfma_f32_16x16x32_bf16 v[28:31], v[148:151], v[208:211], v[28:31]
	v_mfma_f32_16x16x32_bf16 v[24:27], v[156:159], v[208:211], v[24:27]
	v_mfma_f32_16x16x32_bf16 v[12:15], v[148:151], v[222:225], v[12:15]
	v_mfma_f32_16x16x32_bf16 v[8:11], v[156:159], v[222:225], v[8:11]
	s_setprio 0
	s_setprio 1
	v_mfma_f32_16x16x32_bf16 v[52:55], v[160:163], v[176:179], v[52:55]
	v_mfma_f32_16x16x32_bf16 v[48:51], v[168:171], v[176:179], v[48:51]
	v_mfma_f32_16x16x32_bf16 v[36:39], v[160:163], v[184:187], v[36:39]
	v_mfma_f32_16x16x32_bf16 v[32:35], v[168:171], v[184:187], v[32:35]
	v_mfma_f32_16x16x32_bf16 v[20:23], v[160:163], v[204:207], v[20:23]
	v_mfma_f32_16x16x32_bf16 v[16:19], v[168:171], v[204:207], v[16:19]
	v_mfma_f32_16x16x32_bf16 v[4:7], v[160:163], v[218:221], v[4:7]
	v_mfma_f32_16x16x32_bf16 v[0:3], v[168:171], v[218:221], v[0:3]
	v_mfma_f32_16x16x32_bf16 v[52:55], v[164:167], v[180:183], v[52:55]
	v_mfma_f32_16x16x32_bf16 v[48:51], v[172:175], v[180:183], v[48:51]
	v_mfma_f32_16x16x32_bf16 v[36:39], v[164:167], v[188:191], v[36:39]
	v_mfma_f32_16x16x32_bf16 v[32:35], v[172:175], v[188:191], v[32:35]
	v_mfma_f32_16x16x32_bf16 v[20:23], v[164:167], v[208:211], v[20:23]
	v_mfma_f32_16x16x32_bf16 v[16:19], v[172:175], v[208:211], v[16:19]
	v_mfma_f32_16x16x32_bf16 v[4:7], v[164:167], v[222:225], v[4:7]
	v_mfma_f32_16x16x32_bf16 v[0:3], v[172:175], v[222:225], v[0:3]
	s_setprio 0
	s_barrier
	v_add_u32_e32 v156, s48, v145
	v_add_u32_e32 v172, s61, v145
	ds_read_b128 v[138:141], v156
	ds_read_b128 v[148:151], v156 offset:1024
	ds_read_b128 v[152:155], v156 offset:2048
	ds_read_b128 v[156:159], v156 offset:3072
	ds_read_b128 v[160:163], v172
	ds_read_b128 v[164:167], v172 offset:1024
	ds_read_b128 v[168:171], v172 offset:2048
	ds_read_b128 v[172:175], v172 offset:3072
	s_add_u32 s20, s26, 0xb0000
	s_addc_u32 s21, s27, 0
	s_mov_b32 m0, s43
	v_lshl_add_u64 v[232:233], s[20:21], 0, v[128:129]
	ds_read_b128 v[176:179], v147 offset:32768
	ds_read_b128 v[180:183], v147 offset:33792
	ds_read_b128 v[184:187], v147 offset:34816
	ds_read_b128 v[188:191], v147 offset:35840
	ds_read_b128 v[204:207], v147 offset:36864
	ds_read_b128 v[208:211], v147 offset:37888
	ds_read_b128 v[218:221], v147 offset:38912
	ds_read_b128 v[222:225], v147 offset:39936
	global_load_lds_dwordx4 v[232:233], off
	v_lshl_add_u64 v[232:233], s[20:21], 0, v[130:131]
	s_mov_b32 m0, s44
	s_nop 0
	global_load_lds_dwordx4 v[232:233], off
	s_waitcnt vmcnt(8)
	s_waitcnt lgkmcnt(0)
	s_barrier
	s_setprio 1
	s_waitcnt lgkmcnt(0)
	s_nop 0
	v_mfma_f32_16x16x32_bf16 v[124:127], v[138:141], v[176:179], v[124:127]
	v_mfma_f32_16x16x32_bf16 v[120:123], v[152:155], v[176:179], v[120:123]
	v_mfma_f32_16x16x32_bf16 v[108:111], v[138:141], v[184:187], v[108:111]
	v_mfma_f32_16x16x32_bf16 v[104:107], v[152:155], v[184:187], v[104:107]
	v_mfma_f32_16x16x32_bf16 v[92:95], v[138:141], v[204:207], v[92:95]
	v_mfma_f32_16x16x32_bf16 v[88:91], v[152:155], v[204:207], v[88:91]
	v_mfma_f32_16x16x32_bf16 v[76:79], v[138:141], v[218:221], v[76:79]
	v_mfma_f32_16x16x32_bf16 v[72:75], v[152:155], v[218:221], v[72:75]
	v_mfma_f32_16x16x32_bf16 v[124:127], v[148:151], v[180:183], v[124:127]
	v_mfma_f32_16x16x32_bf16 v[120:123], v[156:159], v[180:183], v[120:123]
	v_mfma_f32_16x16x32_bf16 v[108:111], v[148:151], v[188:191], v[108:111]
	v_mfma_f32_16x16x32_bf16 v[104:107], v[156:159], v[188:191], v[104:107]
	v_mfma_f32_16x16x32_bf16 v[92:95], v[148:151], v[208:211], v[92:95]
	v_mfma_f32_16x16x32_bf16 v[88:91], v[156:159], v[208:211], v[88:91]
	v_mfma_f32_16x16x32_bf16 v[76:79], v[148:151], v[222:225], v[76:79]
	v_mfma_f32_16x16x32_bf16 v[72:75], v[156:159], v[222:225], v[72:75]
	s_setprio 0
	s_setprio 1
	v_mfma_f32_16x16x32_bf16 v[116:119], v[160:163], v[176:179], v[116:119]
	v_mfma_f32_16x16x32_bf16 v[112:115], v[168:171], v[176:179], v[112:115]
	v_mfma_f32_16x16x32_bf16 v[100:103], v[160:163], v[184:187], v[100:103]
	v_mfma_f32_16x16x32_bf16 v[96:99], v[168:171], v[184:187], v[96:99]
	v_mfma_f32_16x16x32_bf16 v[84:87], v[160:163], v[204:207], v[84:87]
	v_mfma_f32_16x16x32_bf16 v[80:83], v[168:171], v[204:207], v[80:83]
	v_mfma_f32_16x16x32_bf16 v[68:71], v[160:163], v[218:221], v[68:71]
	v_mfma_f32_16x16x32_bf16 v[64:67], v[168:171], v[218:221], v[64:67]
	v_mfma_f32_16x16x32_bf16 v[116:119], v[164:167], v[180:183], v[116:119]
	v_mfma_f32_16x16x32_bf16 v[112:115], v[172:175], v[180:183], v[112:115]
	v_mfma_f32_16x16x32_bf16 v[100:103], v[164:167], v[188:191], v[100:103]
	v_mfma_f32_16x16x32_bf16 v[96:99], v[172:175], v[188:191], v[96:99]
	v_mfma_f32_16x16x32_bf16 v[84:87], v[164:167], v[208:211], v[84:87]
	v_mfma_f32_16x16x32_bf16 v[80:83], v[172:175], v[208:211], v[80:83]
	v_mfma_f32_16x16x32_bf16 v[68:71], v[164:167], v[222:225], v[68:71]
	v_mfma_f32_16x16x32_bf16 v[64:67], v[172:175], v[222:225], v[64:67]
	s_setprio 0
	s_barrier
; #define PG8_STAGE(bufoff, gbase, voff) do { _Pragma("unroll") for (int _i = 0; _i < 2; ++_i) \
;         __builtin_amdgcn_global_load_lds((const unsigned*)((const char*)(gbase) + (voff)[_i]), (PG8_LAS unsigned*)(lds + (bufoff) + ldsw + _i * 8192), 16, 0, 0); } while (0)
; #define PG8_LDA(dst, b, h) do { _Pragma("unroll") for (int m = 0; m < 4; ++m) _Pragma("unroll") for (int k = 0; k < 2; ++k) dst[m][k] = *(const PG8_LAS bf16x8*)(lds + PG8_SA(b, h) + aoff + m * 2048 + k * 1024); } while (0)
; #define PG8_MMA(ai, bj, At, Bt) do { __builtin_amdgcn_s_setprio(1); _Pragma("unroll") for (int m = 0; m < 4; ++m) _Pragma("unroll") for (int n = 0; n < 2; ++n) _Pragma("unroll") for (int k = 0; k < 2; ++k) \
;         acc[ai][bj][m][n] = __builtin_amdgcn_mfma_f32_16x16x32_bf16(Bt[n][k], At[m][k], acc[ai][bj][m][n], 0, 0, 0); __builtin_amdgcn_s_setprio(0); } while (0)
; #define PG8_WAIT_V(n) asm volatile("s_waitcnt vmcnt(" #n ")" ::: "memory")
; #define PG8_WAIT_L(n) asm volatile("s_waitcnt lgkmcnt(" #n ")" ::: "memory")
; #define PG8_BAR __builtin_amdgcn_s_barrier()
; #define PG8_SCHED __builtin_amdgcn_sched_barrier(0)
; template <class Epi, class Sched, bool ALIGN_EPI = false, bool SP2 = false>
; __device__ __forceinline__ void gemm_phase(PG8_LAS unsigned char* lds, const Gemm g, const Sched& S, const Epi& E) {
;     ...
;             PG8_LDA(At, 1, 1); PG8_STAGE(PG8_SB(1, 0), b3, voffB); PG8_STAGE(PG8_SB(1, 1), b3 + hstepB, voffB); PG8_STAGE(PG8_SA(1, 0), a3, voffA);
;             PG8_WAIT_V(8); PG8_WAIT_L(0); PG8_BAR; PG8_MMA(1, 0, At, B0); PG8_MMA(1, 1, At, B1); PG8_BAR; PG8_SCHED;
;     __device__ __forceinline__ void operator()(const f32x4 (&acc)[2][2][4][2], const pg8::Unit& u, int wr, int wc, int fr, int fq) const {
;         const int row0 = u.pm * 256 + wr * 64 + fr, col0 = u.pn * 256 + wc * 32 + 8 * fq;
; #pragma unroll
;         for (int ai = 0; ai < 2; ++ai)
; #pragma unroll
;             for (int m = 0; m < 4; ++m) {
;                 const int row = row0 + ai * 128 + m * 16; float ss = 0.f;
; #pragma unroll
;                 for (int bj = 0; bj < 2; ++bj) {
;                     const size_t off = (size_t)row * DM + col0 + bj * 128;
;                     const v4u b = *(const v4u*)(xb + off);
	s_mov_b32 m0, s49
	v_lshl_add_u64 v[142:143], v[142:143], 0, s[76:77]
	s_add_u32 s20, s24, 0xb0080
	ds_read_b128 v[176:179], v147 offset:49152
	ds_read_b128 v[180:183], v147 offset:50176
	ds_read_b128 v[184:187], v147 offset:51200
	ds_read_b128 v[188:191], v147 offset:52224
	ds_read_b128 v[204:207], v147 offset:53248
	ds_read_b128 v[208:211], v147 offset:54272
	ds_read_b128 v[218:221], v147 offset:55296
	ds_read_b128 v[222:225], v147 offset:56320
	global_load_lds_dwordx4 v[142:143], off
	v_lshl_add_u64 v[142:143], v[226:227], 0, s[76:77]
	s_mov_b32 m0, s50
	s_addc_u32 s21, s25, 0
	global_load_lds_dwordx4 v[142:143], off
	v_lshl_add_u64 v[142:143], s[20:21], 0, v[192:193]
	s_mov_b32 m0, s64
	s_nop 0
	global_load_lds_dwordx4 v[142:143], off
	v_lshl_add_u64 v[142:143], s[20:21], 0, v[132:133]
	s_mov_b32 m0, s65
	s_nop 0
	global_load_lds_dwordx4 v[142:143], off
	v_lshl_add_u64 v[142:143], v[228:229], 0, s[76:77]
	s_mov_b32 m0, s51
	s_nop 0
	global_load_lds_dwordx4 v[142:143], off
	v_lshl_add_u64 v[142:143], v[230:231], 0, s[76:77]
	s_mov_b32 m0, s60
	s_nop 0
	global_load_lds_dwordx4 v[142:143], off
	s_waitcnt vmcnt(8)
	s_waitcnt lgkmcnt(0)
	s_barrier
	s_setprio 1
	s_waitcnt lgkmcnt(0)
	v_mfma_f32_16x16x32_bf16 v[60:63], v[138:141], v[176:179], v[60:63]
	v_mfma_f32_16x16x32_bf16 v[56:59], v[152:155], v[176:179], v[56:59]
	v_mfma_f32_16x16x32_bf16 v[44:47], v[138:141], v[184:187], v[44:47]
	v_mfma_f32_16x16x32_bf16 v[40:43], v[152:155], v[184:187], v[40:43]
	v_mfma_f32_16x16x32_bf16 v[28:31], v[138:141], v[204:207], v[28:31]
	v_mfma_f32_16x16x32_bf16 v[24:27], v[152:155], v[204:207], v[24:27]
	v_mfma_f32_16x16x32_bf16 v[12:15], v[138:141], v[218:221], v[12:15]
	v_mfma_f32_16x16x32_bf16 v[8:11], v[152:155], v[218:221], v[8:11]
	v_mfma_f32_16x16x32_bf16 v[60:63], v[148:151], v[180:183], v[60:63]
	v_mfma_f32_16x16x32_bf16 v[56:59], v[156:159], v[180:183], v[56:59]
	v_mfma_f32_16x16x32_bf16 v[44:47], v[148:151], v[188:191], v[44:47]
	v_mfma_f32_16x16x32_bf16 v[40:43], v[156:159], v[188:191], v[40:43]
	v_mfma_f32_16x16x32_bf16 v[28:31], v[148:151], v[208:211], v[28:31]
	v_mfma_f32_16x16x32_bf16 v[24:27], v[156:159], v[208:211], v[24:27]
	v_mfma_f32_16x16x32_bf16 v[12:15], v[148:151], v[222:225], v[12:15]
	v_mfma_f32_16x16x32_bf16 v[8:11], v[156:159], v[222:225], v[8:11]
	s_setprio 0
	s_setprio 1
	v_mfma_f32_16x16x32_bf16 v[52:55], v[160:163], v[176:179], v[52:55]
	v_mfma_f32_16x16x32_bf16 v[48:51], v[168:171], v[176:179], v[48:51]
	v_mfma_f32_16x16x32_bf16 v[36:39], v[160:163], v[184:187], v[36:39]
	v_mfma_f32_16x16x32_bf16 v[32:35], v[168:171], v[184:187], v[32:35]
	v_mfma_f32_16x16x32_bf16 v[20:23], v[160:163], v[204:207], v[20:23]
	v_mfma_f32_16x16x32_bf16 v[16:19], v[168:171], v[204:207], v[16:19]
	v_mfma_f32_16x16x32_bf16 v[4:7], v[160:163], v[218:221], v[4:7]
	v_mfma_f32_16x16x32_bf16 v[0:3], v[168:171], v[218:221], v[0:3]
	v_mfma_f32_16x16x32_bf16 v[52:55], v[164:167], v[180:183], v[52:55]
	v_mfma_f32_16x16x32_bf16 v[48:51], v[172:175], v[180:183], v[48:51]
	v_mfma_f32_16x16x32_bf16 v[36:39], v[164:167], v[188:191], v[36:39]
	v_mfma_f32_16x16x32_bf16 v[32:35], v[172:175], v[188:191], v[32:35]
	v_mfma_f32_16x16x32_bf16 v[20:23], v[164:167], v[208:211], v[20:23]
	v_mfma_f32_16x16x32_bf16 v[16:19], v[172:175], v[208:211], v[16:19]
	v_mfma_f32_16x16x32_bf16 v[4:7], v[164:167], v[222:225], v[4:7]
	v_mfma_f32_16x16x32_bf16 v[0:3], v[172:175], v[222:225], v[0:3]
	s_setprio 0
	s_barrier
	s_add_i32 s78, s78, 2
	s_add_u32 s74, s74, 0x100
	s_addc_u32 s75, s75, 0
	s_cmp_gt_u32 s78, 41
	s_mov_b64 s[20:21], s[22:23]
	s_cbranch_scc0 .LBB0_278
	v_lshl_add_u32 v159, s68, 8, v144
	v_lshl_or_b32 v158, s34, 8, v146
	v_lshlrev_b32_e32 v159, 11, v159
	v_lshl_add_u32 v159, v158, 1, v159
	v_add_u32_e32 v218, 0x8000, v159
	v_add_u32_e32 v219, 0x10000, v159
	v_add_u32_e32 v240, 0x18000, v159
	v_add_u32_e32 v241, 0x40000, v159
	v_add_u32_e32 v245, 0x48000, v159
	v_add_u32_e32 v246, 0x50000, v159
	v_add_u32_e32 v247, 0x58000, v159
	global_load_dwordx4 v[160:163], v159, s[12:13]
	global_load_dwordx4 v[164:167], v159, s[12:13] offset:256
	global_load_dwordx4 v[168:171], v218, s[12:13]
	global_load_dwordx4 v[172:175], v218, s[12:13] offset:256
	global_load_dwordx4 v[176:179], v219, s[12:13]
	global_load_dwordx4 v[180:183], v219, s[12:13] offset:256
	global_load_dwordx4 v[184:187], v240, s[12:13]
	global_load_dwordx4 v[188:191], v240, s[12:13] offset:256
	global_load_dwordx4 v[204:207], v241, s[12:13]
	global_load_dwordx4 v[208:211], v241, s[12:13] offset:256
	global_load_dwordx4 v[220:223], v245, s[12:13]
	global_load_dwordx4 v[224:227], v245, s[12:13] offset:256
	global_load_dwordx4 v[228:231], v246, s[12:13]
	global_load_dwordx4 v[232:235], v246, s[12:13] offset:256
	global_load_dwordx4 v[236:239], v247, s[12:13]
	global_load_dwordx4 v[248:251], v247, s[12:13] offset:256
	s_and_b64 vcc, exec, s[16:17]
	s_cbranch_vccz .LBB0_281
	s_barrier

; #define PG8_STAGE(bufoff, gbase, voff) do { _Pragma("unroll") for (int _i = 0; _i < 2; ++_i) \
;         __builtin_amdgcn_global_load_lds((const unsigned*)((const char*)(gbase) + (voff)[_i]), (PG8_LAS unsigned*)(lds + (bufoff) + ldsw + _i * 8192), 16, 0, 0); } while (0)
; #define PG8_LDA(dst, b, h) do { _Pragma("unroll") for (int m = 0; m < 4; ++m) _Pragma("unroll") for (int k = 0; k < 2; ++k) dst[m][k] = *(const PG8_LAS bf16x8*)(lds + PG8_SA(b, h) + aoff + m * 2048 + k * 1024); } while (0)
; #define PG8_LDB(dst, b, h) do { _Pragma("unroll") for (int n = 0; n < 2; ++n) _Pragma("unroll") for (int k = 0; k < 2; ++k) dst[n][k] = *(const PG8_LAS bf16x8*)(lds + PG8_SB(b, h) + boff + n * 2048 + k * 1024); } while (0)
; #define PG8_MMA(ai, bj, At, Bt) do { __builtin_amdgcn_s_setprio(1); _Pragma("unroll") for (int m = 0; m < 4; ++m) _Pragma("unroll") for (int n = 0; n < 2; ++n) _Pragma("unroll") for (int k = 0; k < 2; ++k) \
;         acc[ai][bj][m][n] = __builtin_amdgcn_mfma_f32_16x16x32_bf16(Bt[n][k], At[m][k], acc[ai][bj][m][n], 0, 0, 0); __builtin_amdgcn_s_setprio(0); } while (0)
; #define PG8_WAIT_V(n) asm volatile("s_waitcnt vmcnt(" #n ")" ::: "memory")
; #define PG8_BAR __builtin_amdgcn_s_barrier()
; template <class Epi, class Sched, bool ALIGN_EPI = false, bool SP2 = false>
; __device__ __forceinline__ void gemm_phase(PG8_LAS unsigned char* lds, const Gemm g, const Sched& S, const Epi& E) {
;     ...
;         for (int t = 0; t < nt; t += 2) {
;             const bool last = (t == nt - 2);
;             const char* a1 = cA + (size_t)(t + 1) * kstep;
;             const char* a2 = last ? nA : cA + (size_t)(t + 2) * kstep; const char* b2 = last ? nB : cB + (size_t)(t + 2) * kstep;
;             const char* a3 = a2 + kstep; const char* b3 = b2 + kstep;
;             if (last && has_next) S.a_ready(nxt);
;             if constexpr (SP2) {
;             PG8_LDB(B0, 0, 0); PG8_LDB(B1, 0, 1); PG8_SCHED; PG8_LDA(At, 0, 0); PG8_STAGE(PG8_SA(1, 1), a1 + hstepA, voffA);
;             PG8_WAIT_V(8); PG8_WAIT_L(0); PG8_BAR; PG8_MMA(0, 0, At, B0); PG8_MMA(0, 1, At, B1); PG8_BAR; PG8_SCHED;
;             PG8_LDA(At, 0, 1); PG8_STAGE(PG8_SB(0, 0), b2, voffB); PG8_STAGE(PG8_SB(0, 1), b2 + hstepB, voffB); PG8_STAGE(PG8_SA(0, 0), a2, voffA);
;             PG8_WAIT_V(8); PG8_WAIT_L(0); PG8_BAR; PG8_MMA(1, 0, At, B0); PG8_MMA(1, 1, At, B1); PG8_BAR; PG8_SCHED;
.LBB0_380:
	v_add_u32_e32 v140, s85, v173
	v_add_u32_e32 v170, s78, v173
	ds_read_b128 v[128:131], v140
	ds_read_b128 v[132:135], v140 offset:1024
	ds_read_b128 v[136:139], v140 offset:2048
	ds_read_b128 v[140:143], v140 offset:3072
	ds_read_b128 v[144:147], v170
	ds_read_b128 v[148:151], v170 offset:1024
	ds_read_b128 v[166:169], v170 offset:2048
	ds_read_b128 v[176:179], v170 offset:3072
	s_add_u32 s2, s12, 0xfffc0080
	s_addc_u32 s14, s13, -1
	s_cmp_eq_u32 s22, 12
	s_cselect_b32 s17, s9, s14
	s_cselect_b32 s16, s11, s2
	s_cselect_b32 s15, s18, s21
	s_cselect_b32 s14, s19, s20
	v_lshl_add_u64 v[170:171], s[12:13], 0, v[164:165]
	s_add_i32 m0, s61, 0xc000
	ds_read_b128 v[180:183], v175
	ds_read_b128 v[184:187], v175 offset:1024
	ds_read_b128 v[188:191], v175 offset:2048
	ds_read_b128 v[204:207], v175 offset:3072
	ds_read_b128 v[208:211], v175 offset:4096
	ds_read_b128 v[218:221], v175 offset:5120
	ds_read_b128 v[222:225], v175 offset:6144
	ds_read_b128 v[226:229], v175 offset:7168
	global_load_lds_dwordx4 v[170:171], off
	v_lshl_add_u64 v[170:171], s[12:13], 0, v[162:163]
	s_add_i32 m0, s61, 0xe000
	s_nop 0
	global_load_lds_dwordx4 v[170:171], off
	s_waitcnt vmcnt(8)
	s_waitcnt lgkmcnt(0)
	s_barrier
	s_setprio 1
	s_waitcnt lgkmcnt(0)
	s_nop 0
	v_mfma_f32_16x16x32_bf16 v[60:63], v[128:131], v[180:183], v[60:63]
	v_mfma_f32_16x16x32_bf16 v[56:59], v[136:139], v[180:183], v[56:59]
	v_mfma_f32_16x16x32_bf16 v[52:55], v[128:131], v[188:191], v[52:55]
	v_mfma_f32_16x16x32_bf16 v[48:51], v[136:139], v[188:191], v[48:51]
	v_mfma_f32_16x16x32_bf16 v[44:47], v[128:131], v[208:211], v[44:47]
	v_mfma_f32_16x16x32_bf16 v[40:43], v[136:139], v[208:211], v[40:43]
	v_mfma_f32_16x16x32_bf16 v[36:39], v[128:131], v[222:225], v[36:39]
	v_mfma_f32_16x16x32_bf16 v[32:35], v[136:139], v[222:225], v[32:35]
	v_mfma_f32_16x16x32_bf16 v[60:63], v[132:135], v[184:187], v[60:63]
	v_mfma_f32_16x16x32_bf16 v[56:59], v[140:143], v[184:187], v[56:59]
	v_mfma_f32_16x16x32_bf16 v[52:55], v[132:135], v[204:207], v[52:55]
	v_mfma_f32_16x16x32_bf16 v[48:51], v[140:143], v[204:207], v[48:51]
	v_mfma_f32_16x16x32_bf16 v[44:47], v[132:135], v[218:221], v[44:47]
	v_mfma_f32_16x16x32_bf16 v[40:43], v[140:143], v[218:221], v[40:43]
	v_mfma_f32_16x16x32_bf16 v[36:39], v[132:135], v[226:229], v[36:39]
	v_mfma_f32_16x16x32_bf16 v[32:35], v[140:143], v[226:229], v[32:35]
	s_setprio 0
	s_setprio 1
	v_mfma_f32_16x16x32_bf16 v[124:127], v[144:147], v[180:183], v[124:127]
	v_mfma_f32_16x16x32_bf16 v[120:123], v[166:169], v[180:183], v[120:123]
	v_mfma_f32_16x16x32_bf16 v[116:119], v[144:147], v[188:191], v[116:119]
	v_mfma_f32_16x16x32_bf16 v[112:115], v[166:169], v[188:191], v[112:115]
	v_mfma_f32_16x16x32_bf16 v[108:111], v[144:147], v[208:211], v[108:111]
	v_mfma_f32_16x16x32_bf16 v[104:107], v[166:169], v[208:211], v[104:107]
	v_mfma_f32_16x16x32_bf16 v[100:103], v[144:147], v[222:225], v[100:103]
	v_mfma_f32_16x16x32_bf16 v[96:99], v[166:169], v[222:225], v[96:99]
	v_mfma_f32_16x16x32_bf16 v[124:127], v[148:151], v[184:187], v[124:127]
	v_mfma_f32_16x16x32_bf16 v[120:123], v[176:179], v[184:187], v[120:123]
	v_mfma_f32_16x16x32_bf16 v[116:119], v[148:151], v[204:207], v[116:119]
	v_mfma_f32_16x16x32_bf16 v[112:115], v[176:179], v[204:207], v[112:115]
	v_mfma_f32_16x16x32_bf16 v[108:111], v[148:151], v[218:221], v[108:111]
	v_mfma_f32_16x16x32_bf16 v[104:107], v[176:179], v[218:221], v[104:107]
	v_mfma_f32_16x16x32_bf16 v[100:103], v[148:151], v[226:229], v[100:103]
	v_mfma_f32_16x16x32_bf16 v[96:99], v[176:179], v[226:229], v[96:99]
	s_setprio 0
	s_barrier
	s_mov_b32 m0, s70
	v_lshl_add_u64 v[170:171], s[14:15], 0, v[154:155]
	s_add_u32 s24, s14, 0x40000
	ds_read_b128 v[180:183], v175 offset:16384
	ds_read_b128 v[184:187], v175 offset:17408
	ds_read_b128 v[188:191], v175 offset:18432
	ds_read_b128 v[204:207], v175 offset:19456
	ds_read_b128 v[208:211], v175 offset:20480
	ds_read_b128 v[218:221], v175 offset:21504
	ds_read_b128 v[222:225], v175 offset:22528
	ds_read_b128 v[226:229], v175 offset:23552
	global_load_lds_dwordx4 v[170:171], off
	v_lshl_add_u64 v[230:231], s[14:15], 0, v[158:159]
	s_mov_b32 m0, s71
	s_addc_u32 s25, s15, 0
	global_load_lds_dwordx4 v[230:231], off
	v_lshl_add_u64 v[232:233], s[24:25], 0, v[154:155]
	s_mov_b32 m0, s79
	v_lshl_add_u64 v[234:235], s[16:17], 0, v[156:157]
	global_load_lds_dwordx4 v[232:233], off
	v_lshl_add_u64 v[232:233], s[24:25], 0, v[158:159]
	s_mov_b32 m0, s60
	s_nop 0
	global_load_lds_dwordx4 v[232:233], off
	v_lshl_add_u64 v[232:233], s[16:17], 0, v[152:153]
	s_mov_b32 m0, s61
	s_nop 0
	global_load_lds_dwordx4 v[232:233], off
	s_mov_b32 m0, s75
	s_nop 0
	global_load_lds_dwordx4 v[234:235], off
	s_waitcnt vmcnt(8)
	s_waitcnt lgkmcnt(0)
	s_barrier
; #define PG8_STAGE(bufoff, gbase, voff) do { _Pragma("unroll") for (int _i = 0; _i < 2; ++_i) \
;         __builtin_amdgcn_global_load_lds((const unsigned*)((const char*)(gbase) + (voff)[_i]), (PG8_LAS unsigned*)(lds + (bufoff) + ldsw + _i * 8192), 16, 0, 0); } while (0)
; #define PG8_LDA(dst, b, h) do { _Pragma("unroll") for (int m = 0; m < 4; ++m) _Pragma("unroll") for (int k = 0; k < 2; ++k) dst[m][k] = *(const PG8_LAS bf16x8*)(lds + PG8_SA(b, h) + aoff + m * 2048 + k * 1024); } while (0)
; #define PG8_LDB(dst, b, h) do { _Pragma("unroll") for (int n = 0; n < 2; ++n) _Pragma("unroll") for (int k = 0; k < 2; ++k) dst[n][k] = *(const PG8_LAS bf16x8*)(lds + PG8_SB(b, h) + boff + n * 2048 + k * 1024); } while (0)
; #define PG8_MMA(ai, bj, At, Bt) do { __builtin_amdgcn_s_setprio(1); _Pragma("unroll") for (int m = 0; m < 4; ++m) _Pragma("unroll") for (int n = 0; n < 2; ++n) _Pragma("unroll") for (int k = 0; k < 2; ++k) \
;         acc[ai][bj][m][n] = __builtin_amdgcn_mfma_f32_16x16x32_bf16(Bt[n][k], At[m][k], acc[ai][bj][m][n], 0, 0, 0); __builtin_amdgcn_s_setprio(0); } while (0)
; #define PG8_WAIT_V(n) asm volatile("s_waitcnt vmcnt(" #n ")" ::: "memory")
; #define PG8_WAIT_L(n) asm volatile("s_waitcnt lgkmcnt(" #n ")" ::: "memory")
; #define PG8_BAR __builtin_amdgcn_s_barrier()
; #define PG8_SCHED __builtin_amdgcn_sched_barrier(0)
; template <class Epi, class Sched, bool ALIGN_EPI = false, bool SP2 = false>
; __device__ __forceinline__ void gemm_phase(PG8_LAS unsigned char* lds, const Gemm g, const Sched& S, const Epi& E) {
;     ...
;             PG8_WAIT_V(8); PG8_WAIT_L(0); PG8_BAR; PG8_MMA(0, 0, At, B0); PG8_MMA(0, 1, At, B1); PG8_BAR; PG8_SCHED;
;             PG8_LDA(At, 0, 1); PG8_STAGE(PG8_SB(0, 0), b2, voffB); PG8_STAGE(PG8_SB(0, 1), b2 + hstepB, voffB); PG8_STAGE(PG8_SA(0, 0), a2, voffA);
;             PG8_WAIT_V(8); PG8_WAIT_L(0); PG8_BAR; PG8_MMA(1, 0, At, B0); PG8_MMA(1, 1, At, B1); PG8_BAR; PG8_SCHED;
;             PG8_LDB(B0, 1, 0); PG8_LDB(B1, 1, 1); PG8_SCHED; PG8_LDA(At, 1, 0); PG8_STAGE(PG8_SA(0, 1), a2 + hstepA, voffA);
;             PG8_WAIT_V(8); PG8_WAIT_L(0); PG8_BAR; PG8_MMA(0, 0, At, B0); PG8_MMA(0, 1, At, B1); PG8_BAR; PG8_SCHED;
	s_setprio 1
	s_waitcnt lgkmcnt(0)
	s_nop 0
	v_mfma_f32_16x16x32_bf16 v[28:31], v[128:131], v[180:183], v[28:31]
	v_mfma_f32_16x16x32_bf16 v[24:27], v[136:139], v[180:183], v[24:27]
	v_mfma_f32_16x16x32_bf16 v[20:23], v[128:131], v[188:191], v[20:23]
	v_mfma_f32_16x16x32_bf16 v[16:19], v[136:139], v[188:191], v[16:19]
	v_mfma_f32_16x16x32_bf16 v[12:15], v[128:131], v[208:211], v[12:15]
	v_mfma_f32_16x16x32_bf16 v[8:11], v[136:139], v[208:211], v[8:11]
	v_mfma_f32_16x16x32_bf16 v[4:7], v[128:131], v[222:225], v[4:7]
	v_mfma_f32_16x16x32_bf16 v[0:3], v[136:139], v[222:225], v[0:3]
	v_mfma_f32_16x16x32_bf16 v[28:31], v[132:135], v[184:187], v[28:31]
	v_mfma_f32_16x16x32_bf16 v[24:27], v[140:143], v[184:187], v[24:27]
	v_mfma_f32_16x16x32_bf16 v[20:23], v[132:135], v[204:207], v[20:23]
	v_mfma_f32_16x16x32_bf16 v[16:19], v[140:143], v[204:207], v[16:19]
	v_mfma_f32_16x16x32_bf16 v[12:15], v[132:135], v[218:221], v[12:15]
	v_mfma_f32_16x16x32_bf16 v[8:11], v[140:143], v[218:221], v[8:11]
	v_mfma_f32_16x16x32_bf16 v[4:7], v[132:135], v[226:229], v[4:7]
	v_mfma_f32_16x16x32_bf16 v[0:3], v[140:143], v[226:229], v[0:3]
	s_setprio 0
	s_setprio 1
	v_mfma_f32_16x16x32_bf16 v[92:95], v[144:147], v[180:183], v[92:95]
	v_mfma_f32_16x16x32_bf16 v[88:91], v[166:169], v[180:183], v[88:91]
	v_mfma_f32_16x16x32_bf16 v[84:87], v[144:147], v[188:191], v[84:87]
	v_mfma_f32_16x16x32_bf16 v[80:83], v[166:169], v[188:191], v[80:83]
	v_mfma_f32_16x16x32_bf16 v[76:79], v[144:147], v[208:211], v[76:79]
	v_mfma_f32_16x16x32_bf16 v[72:75], v[166:169], v[208:211], v[72:75]
	v_mfma_f32_16x16x32_bf16 v[68:71], v[144:147], v[222:225], v[68:71]
	v_mfma_f32_16x16x32_bf16 v[64:67], v[166:169], v[222:225], v[64:67]
	v_mfma_f32_16x16x32_bf16 v[92:95], v[148:151], v[184:187], v[92:95]
	v_mfma_f32_16x16x32_bf16 v[88:91], v[176:179], v[184:187], v[88:91]
	v_mfma_f32_16x16x32_bf16 v[84:87], v[148:151], v[204:207], v[84:87]
	v_mfma_f32_16x16x32_bf16 v[80:83], v[176:179], v[204:207], v[80:83]
	v_mfma_f32_16x16x32_bf16 v[76:79], v[148:151], v[218:221], v[76:79]
	v_mfma_f32_16x16x32_bf16 v[72:75], v[176:179], v[218:221], v[72:75]
	v_mfma_f32_16x16x32_bf16 v[68:71], v[148:151], v[226:229], v[68:71]
	v_mfma_f32_16x16x32_bf16 v[64:67], v[176:179], v[226:229], v[64:67]
	s_setprio 0
	s_barrier
	v_add_u32_e32 v140, s68, v173
	v_add_u32_e32 v176, s1, v173
	ds_read_b128 v[128:131], v140
	ds_read_b128 v[132:135], v140 offset:1024
	ds_read_b128 v[136:139], v140 offset:2048
	ds_read_b128 v[140:143], v140 offset:3072
	ds_read_b128 v[144:147], v176
	ds_read_b128 v[148:151], v176 offset:1024
	ds_read_b128 v[166:169], v176 offset:2048
	ds_read_b128 v[176:179], v176 offset:3072
	s_add_u32 s16, s16, 0x40000
	s_addc_u32 s17, s17, 0
	s_mov_b32 m0, s4
	v_lshl_add_u64 v[236:237], s[16:17], 0, v[152:153]
	ds_read_b128 v[180:183], v175 offset:32768
	ds_read_b128 v[184:187], v175 offset:33792
	ds_read_b128 v[188:191], v175 offset:34816
	ds_read_b128 v[204:207], v175 offset:35840
	ds_read_b128 v[208:211], v175 offset:36864
	ds_read_b128 v[218:221], v175 offset:37888
	ds_read_b128 v[222:225], v175 offset:38912
	ds_read_b128 v[226:229], v175 offset:39936
	global_load_lds_dwordx4 v[236:237], off
	v_lshl_add_u64 v[236:237], s[16:17], 0, v[156:157]
	s_mov_b32 m0, s5
	s_nop 0
	global_load_lds_dwordx4 v[236:237], off
	s_waitcnt vmcnt(8)
	s_waitcnt lgkmcnt(0)
	s_barrier
	s_setprio 1
	s_waitcnt lgkmcnt(0)
	s_nop 0
	v_mfma_f32_16x16x32_bf16 v[60:63], v[128:131], v[180:183], v[60:63]
	v_mfma_f32_16x16x32_bf16 v[56:59], v[136:139], v[180:183], v[56:59]
	v_mfma_f32_16x16x32_bf16 v[52:55], v[128:131], v[188:191], v[52:55]
	v_mfma_f32_16x16x32_bf16 v[48:51], v[136:139], v[188:191], v[48:51]
	v_mfma_f32_16x16x32_bf16 v[44:47], v[128:131], v[208:211], v[44:47]
	v_mfma_f32_16x16x32_bf16 v[40:43], v[136:139], v[208:211], v[40:43]
	v_mfma_f32_16x16x32_bf16 v[36:39], v[128:131], v[222:225], v[36:39]
	v_mfma_f32_16x16x32_bf16 v[32:35], v[136:139], v[222:225], v[32:35]
	v_mfma_f32_16x16x32_bf16 v[60:63], v[132:135], v[184:187], v[60:63]
	v_mfma_f32_16x16x32_bf16 v[56:59], v[140:143], v[184:187], v[56:59]
	v_mfma_f32_16x16x32_bf16 v[52:55], v[132:135], v[204:207], v[52:55]
	v_mfma_f32_16x16x32_bf16 v[48:51], v[140:143], v[204:207], v[48:51]
	v_mfma_f32_16x16x32_bf16 v[44:47], v[132:135], v[218:221], v[44:47]
	v_mfma_f32_16x16x32_bf16 v[40:43], v[140:143], v[218:221], v[40:43]
	v_mfma_f32_16x16x32_bf16 v[36:39], v[132:135], v[226:229], v[36:39]
	v_mfma_f32_16x16x32_bf16 v[32:35], v[140:143], v[226:229], v[32:35]
	s_setprio 0
	s_setprio 1
	v_mfma_f32_16x16x32_bf16 v[124:127], v[144:147], v[180:183], v[124:127]
	v_mfma_f32_16x16x32_bf16 v[120:123], v[166:169], v[180:183], v[120:123]
	v_mfma_f32_16x16x32_bf16 v[116:119], v[144:147], v[188:191], v[116:119]
	v_mfma_f32_16x16x32_bf16 v[112:115], v[166:169], v[188:191], v[112:115]
	v_mfma_f32_16x16x32_bf16 v[108:111], v[144:147], v[208:211], v[108:111]
	v_mfma_f32_16x16x32_bf16 v[104:107], v[166:169], v[208:211], v[104:107]
	v_mfma_f32_16x16x32_bf16 v[100:103], v[144:147], v[222:225], v[100:103]
	v_mfma_f32_16x16x32_bf16 v[96:99], v[166:169], v[222:225], v[96:99]
	v_mfma_f32_16x16x32_bf16 v[124:127], v[148:151], v[184:187], v[124:127]
	v_mfma_f32_16x16x32_bf16 v[120:123], v[176:179], v[184:187], v[120:123]
	v_mfma_f32_16x16x32_bf16 v[116:119], v[148:151], v[204:207], v[116:119]
	v_mfma_f32_16x16x32_bf16 v[112:115], v[176:179], v[204:207], v[112:115]
	v_mfma_f32_16x16x32_bf16 v[108:111], v[148:151], v[218:221], v[108:111]
	v_mfma_f32_16x16x32_bf16 v[104:107], v[176:179], v[218:221], v[104:107]
	v_mfma_f32_16x16x32_bf16 v[100:103], v[148:151], v[226:229], v[100:103]
	v_mfma_f32_16x16x32_bf16 v[96:99], v[176:179], v[226:229], v[96:99]
	s_setprio 0
	s_barrier
; #define PG8_STAGE(bufoff, gbase, voff) do { _Pragma("unroll") for (int _i = 0; _i < 2; ++_i) \
;         __builtin_amdgcn_global_load_lds((const unsigned*)((const char*)(gbase) + (voff)[_i]), (PG8_LAS unsigned*)(lds + (bufoff) + ldsw + _i * 8192), 16, 0, 0); } while (0)
; #define PG8_LDA(dst, b, h) do { _Pragma("unroll") for (int m = 0; m < 4; ++m) _Pragma("unroll") for (int k = 0; k < 2; ++k) dst[m][k] = *(const PG8_LAS bf16x8*)(lds + PG8_SA(b, h) + aoff + m * 2048 + k * 1024); } while (0)
; #define PG8_MMA(ai, bj, At, Bt) do { __builtin_amdgcn_s_setprio(1); _Pragma("unroll") for (int m = 0; m < 4; ++m) _Pragma("unroll") for (int n = 0; n < 2; ++n) _Pragma("unroll") for (int k = 0; k < 2; ++k) \
;         acc[ai][bj][m][n] = __builtin_amdgcn_mfma_f32_16x16x32_bf16(Bt[n][k], At[m][k], acc[ai][bj][m][n], 0, 0, 0); __builtin_amdgcn_s_setprio(0); } while (0)
; #define PG8_WAIT_V(n) asm volatile("s_waitcnt vmcnt(" #n ")" ::: "memory")
; #define PG8_WAIT_L(n) asm volatile("s_waitcnt lgkmcnt(" #n ")" ::: "memory")
; #define PG8_BAR __builtin_amdgcn_s_barrier()
; #define PG8_SCHED __builtin_amdgcn_sched_barrier(0)
; template <class Epi, class Sched, bool ALIGN_EPI = false, bool SP2 = false>
; __device__ __forceinline__ void gemm_phase(PG8_LAS unsigned char* lds, const Gemm g, const Sched& S, const Epi& E) {
;     ...
;             PG8_LDA(At, 1, 1); PG8_STAGE(PG8_SB(1, 0), b3, voffB); PG8_STAGE(PG8_SB(1, 1), b3 + hstepB, voffB); PG8_STAGE(PG8_SA(1, 0), a3, voffA);
;             PG8_WAIT_V(8); PG8_WAIT_L(0); PG8_BAR; PG8_MMA(1, 0, At, B0); PG8_MMA(1, 1, At, B1); PG8_BAR; PG8_SCHED;
;     ...
;         if constexpr (ALIGN_EPI) { if (wr == 0) PG8_BAR; }
;         if constexpr (!Epi::AFTER_DRAIN) { E(acc, cur, wr, wc, fr, fq); S.done(cur); }
	s_mov_b32 m0, s84
	v_lshl_add_u64 v[170:171], v[170:171], 0, s[76:77]
	s_add_u32 s14, s14, 0x40080
	ds_read_b128 v[180:183], v175 offset:49152
	ds_read_b128 v[184:187], v175 offset:50176
	ds_read_b128 v[188:191], v175 offset:51200
	ds_read_b128 v[204:207], v175 offset:52224
	ds_read_b128 v[208:211], v175 offset:53248
	ds_read_b128 v[218:221], v175 offset:54272
	ds_read_b128 v[222:225], v175 offset:55296
	ds_read_b128 v[226:229], v175 offset:56320
	global_load_lds_dwordx4 v[170:171], off
	v_lshl_add_u64 v[170:171], v[230:231], 0, s[76:77]
	s_mov_b32 m0, s64
	s_addc_u32 s15, s15, 0
	global_load_lds_dwordx4 v[170:171], off
	v_lshl_add_u64 v[170:171], s[14:15], 0, v[154:155]
	s_mov_b32 m0, s48
	s_nop 0
	global_load_lds_dwordx4 v[170:171], off
	v_lshl_add_u64 v[170:171], s[14:15], 0, v[158:159]
	s_mov_b32 m0, s49
	s_nop 0
	global_load_lds_dwordx4 v[170:171], off
	v_lshl_add_u64 v[170:171], v[232:233], 0, s[76:77]
	s_mov_b32 m0, s65
	s_nop 0
	global_load_lds_dwordx4 v[170:171], off
	v_lshl_add_u64 v[170:171], v[234:235], 0, s[76:77]
	s_mov_b32 m0, s0
	s_nop 0
	global_load_lds_dwordx4 v[170:171], off
	s_waitcnt vmcnt(8)
	s_waitcnt lgkmcnt(0)
	s_barrier
	s_setprio 1
	s_waitcnt lgkmcnt(0)
	v_mfma_f32_16x16x32_bf16 v[28:31], v[128:131], v[180:183], v[28:31]
	v_mfma_f32_16x16x32_bf16 v[24:27], v[136:139], v[180:183], v[24:27]
	v_mfma_f32_16x16x32_bf16 v[20:23], v[128:131], v[188:191], v[20:23]
	v_mfma_f32_16x16x32_bf16 v[16:19], v[136:139], v[188:191], v[16:19]
	v_mfma_f32_16x16x32_bf16 v[12:15], v[128:131], v[208:211], v[12:15]
	v_mfma_f32_16x16x32_bf16 v[8:11], v[136:139], v[208:211], v[8:11]
	v_mfma_f32_16x16x32_bf16 v[4:7], v[128:131], v[222:225], v[4:7]
	v_mfma_f32_16x16x32_bf16 v[0:3], v[136:139], v[222:225], v[0:3]
	v_mfma_f32_16x16x32_bf16 v[28:31], v[132:135], v[184:187], v[28:31]
	v_mfma_f32_16x16x32_bf16 v[24:27], v[140:143], v[184:187], v[24:27]
	v_mfma_f32_16x16x32_bf16 v[20:23], v[132:135], v[204:207], v[20:23]
	v_mfma_f32_16x16x32_bf16 v[16:19], v[140:143], v[204:207], v[16:19]
	v_mfma_f32_16x16x32_bf16 v[12:15], v[132:135], v[218:221], v[12:15]
	v_mfma_f32_16x16x32_bf16 v[8:11], v[140:143], v[218:221], v[8:11]
	v_mfma_f32_16x16x32_bf16 v[4:7], v[132:135], v[226:229], v[4:7]
	v_mfma_f32_16x16x32_bf16 v[0:3], v[140:143], v[226:229], v[0:3]
	s_setprio 0
	s_setprio 1
	v_mfma_f32_16x16x32_bf16 v[92:95], v[144:147], v[180:183], v[92:95]
	v_mfma_f32_16x16x32_bf16 v[88:91], v[166:169], v[180:183], v[88:91]
	v_mfma_f32_16x16x32_bf16 v[84:87], v[144:147], v[188:191], v[84:87]
	v_mfma_f32_16x16x32_bf16 v[80:83], v[166:169], v[188:191], v[80:83]
	v_mfma_f32_16x16x32_bf16 v[76:79], v[144:147], v[208:211], v[76:79]
	v_mfma_f32_16x16x32_bf16 v[72:75], v[166:169], v[208:211], v[72:75]
	v_mfma_f32_16x16x32_bf16 v[68:71], v[144:147], v[222:225], v[68:71]
	v_mfma_f32_16x16x32_bf16 v[64:67], v[166:169], v[222:225], v[64:67]
	v_mfma_f32_16x16x32_bf16 v[92:95], v[148:151], v[184:187], v[92:95]
	v_mfma_f32_16x16x32_bf16 v[88:91], v[176:179], v[184:187], v[88:91]
	v_mfma_f32_16x16x32_bf16 v[84:87], v[148:151], v[204:207], v[84:87]
	v_mfma_f32_16x16x32_bf16 v[80:83], v[176:179], v[204:207], v[80:83]
	v_mfma_f32_16x16x32_bf16 v[76:79], v[148:151], v[218:221], v[76:79]
	v_mfma_f32_16x16x32_bf16 v[72:75], v[176:179], v[218:221], v[72:75]
	v_mfma_f32_16x16x32_bf16 v[68:71], v[148:151], v[226:229], v[68:71]
	v_mfma_f32_16x16x32_bf16 v[64:67], v[176:179], v[226:229], v[64:67]
	s_setprio 0
	s_barrier
	s_add_i32 s22, s22, 2
	s_add_u32 s20, s20, 0x100
	s_addc_u32 s21, s21, 0
	s_add_u32 s12, s12, 0x100
	s_addc_u32 s13, s13, 0
	s_cmp_gt_u32 s22, 13
	s_cbranch_scc0 .LBB0_380
	s_and_b64 vcc, exec, s[36:37]
	s_cbranch_vccz .LBB0_383
	s_barrier

; #define PG8_STAGE(bufoff, gbase, voff) do { _Pragma("unroll") for (int _i = 0; _i < 2; ++_i) \
;         __builtin_amdgcn_global_load_lds((const unsigned*)((const char*)(gbase) + (voff)[_i]), (PG8_LAS unsigned*)(lds + (bufoff) + ldsw + _i * 8192), 16, 0, 0); } while (0)
; #define PG8_LDA(dst, b, h) do { _Pragma("unroll") for (int m = 0; m < 4; ++m) _Pragma("unroll") for (int k = 0; k < 2; ++k) dst[m][k] = *(const PG8_LAS bf16x8*)(lds + PG8_SA(b, h) + aoff + m * 2048 + k * 1024); } while (0)
; #define PG8_LDB(dst, b, h) do { _Pragma("unroll") for (int n = 0; n < 2; ++n) _Pragma("unroll") for (int k = 0; k < 2; ++k) dst[n][k] = *(const PG8_LAS bf16x8*)(lds + PG8_SB(b, h) + boff + n * 2048 + k * 1024); } while (0)
; #define PG8_MMA(ai, bj, At, Bt) do { __builtin_amdgcn_s_setprio(1); _Pragma("unroll") for (int m = 0; m < 4; ++m) _Pragma("unroll") for (int n = 0; n < 2; ++n) _Pragma("unroll") for (int k = 0; k < 2; ++k) \
;         acc[ai][bj][m][n] = __builtin_amdgcn_mfma_f32_16x16x32_bf16(Bt[n][k], At[m][k], acc[ai][bj][m][n], 0, 0, 0); __builtin_amdgcn_s_setprio(0); } while (0)
; #define PG8_WAIT_V(n) asm volatile("s_waitcnt vmcnt(" #n ")" ::: "memory")
; #define PG8_BAR __builtin_amdgcn_s_barrier()
; template <class Epi, class Sched, bool ALIGN_EPI = false, bool SP2 = false>
; __device__ __forceinline__ void gemm_phase(PG8_LAS unsigned char* lds, const Gemm g, const Sched& S, const Epi& E) {
;     ...
;         for (int t = 0; t < nt; t += 2) {
;             const bool last = (t == nt - 2);
;             const char* a1 = cA + (size_t)(t + 1) * kstep;
;             const char* a2 = last ? nA : cA + (size_t)(t + 2) * kstep; const char* b2 = last ? nB : cB + (size_t)(t + 2) * kstep;
;             const char* a3 = a2 + kstep; const char* b3 = b2 + kstep;
;             if (last && has_next) S.a_ready(nxt);
;             if constexpr (SP2) {
;             PG8_LDB(B0, 0, 0); PG8_LDB(B1, 0, 1); PG8_SCHED; PG8_LDA(At, 0, 0); PG8_STAGE(PG8_SA(1, 1), a1 + hstepA, voffA);
;             PG8_WAIT_V(8); PG8_WAIT_L(0); PG8_BAR; PG8_MMA(0, 0, At, B0); PG8_MMA(0, 1, At, B1); PG8_BAR; PG8_SCHED;
;             PG8_LDA(At, 0, 1); PG8_STAGE(PG8_SB(0, 0), b2, voffB); PG8_STAGE(PG8_SB(0, 1), b2 + hstepB, voffB); PG8_STAGE(PG8_SA(0, 0), a2, voffA);
;             PG8_WAIT_V(8); PG8_WAIT_L(0); PG8_BAR; PG8_MMA(1, 0, At, B0); PG8_MMA(1, 1, At, B1); PG8_BAR; PG8_SCHED;
.LBB0_431:
	s_add_i32 s44, s12, 2
	v_add_u32_e32 v154, s23, v140
	v_add_u32_e32 v170, s26, v140
	s_add_u32 s2, s10, 0xfcb80080
	ds_read_b128 v[142:145], v154
	ds_read_b128 v[146:149], v154 offset:1024
	ds_read_b128 v[150:153], v154 offset:2048
	ds_read_b128 v[154:157], v154 offset:3072
	ds_read_b128 v[158:161], v170
	ds_read_b128 v[162:165], v170 offset:1024
	ds_read_b128 v[166:169], v170 offset:2048
	ds_read_b128 v[170:173], v170 offset:3072
	s_addc_u32 s13, s11, -1
	s_cmp_lg_u32 s43, s12
	s_cselect_b32 s2, s2, 0
	s_cselect_b32 s13, s13, 0
	s_add_u32 s14, s6, s2
	s_addc_u32 s15, s7, s13
	s_add_u32 s12, s8, s2
	s_addc_u32 s13, s9, s13
	v_lshl_add_u64 v[190:191], v[138:139], 0, s[10:11]
	s_add_i32 m0, s29, 0xc000
	ds_read_b128 v[174:177], v141
	ds_read_b128 v[178:181], v141 offset:1024
	ds_read_b128 v[182:185], v141 offset:2048
	ds_read_b128 v[186:189], v141 offset:3072
	ds_read_b128 v[204:207], v141 offset:4096
	ds_read_b128 v[208:211], v141 offset:5120
	ds_read_b128 v[218:221], v141 offset:6144
	ds_read_b128 v[222:225], v141 offset:7168
	global_load_lds_dwordx4 v[190:191], off
	v_lshl_add_u64 v[190:191], v[136:137], 0, s[10:11]
	s_add_i32 m0, s29, 0xe000
	s_nop 0
	global_load_lds_dwordx4 v[190:191], off
	s_waitcnt vmcnt(8)
	s_waitcnt lgkmcnt(0)
	s_barrier
	s_setprio 1
	s_waitcnt lgkmcnt(0)
	s_nop 0
	v_mfma_f32_16x16x32_bf16 v[124:127], v[142:145], v[174:177], v[124:127]
	v_mfma_f32_16x16x32_bf16 v[120:123], v[150:153], v[174:177], v[120:123]
	v_mfma_f32_16x16x32_bf16 v[116:119], v[142:145], v[182:185], v[116:119]
	v_mfma_f32_16x16x32_bf16 v[112:115], v[150:153], v[182:185], v[112:115]
	v_mfma_f32_16x16x32_bf16 v[104:107], v[142:145], v[204:207], v[104:107]
	v_mfma_f32_16x16x32_bf16 v[96:99], v[150:153], v[204:207], v[96:99]
	v_mfma_f32_16x16x32_bf16 v[88:91], v[142:145], v[218:221], v[88:91]
	v_mfma_f32_16x16x32_bf16 v[80:83], v[150:153], v[218:221], v[80:83]
	v_mfma_f32_16x16x32_bf16 v[124:127], v[146:149], v[178:181], v[124:127]
	v_mfma_f32_16x16x32_bf16 v[120:123], v[154:157], v[178:181], v[120:123]
	v_mfma_f32_16x16x32_bf16 v[116:119], v[146:149], v[186:189], v[116:119]
	v_mfma_f32_16x16x32_bf16 v[112:115], v[154:157], v[186:189], v[112:115]
	v_mfma_f32_16x16x32_bf16 v[104:107], v[146:149], v[208:211], v[104:107]
	v_mfma_f32_16x16x32_bf16 v[96:99], v[154:157], v[208:211], v[96:99]
	v_mfma_f32_16x16x32_bf16 v[88:91], v[146:149], v[222:225], v[88:91]
	v_mfma_f32_16x16x32_bf16 v[80:83], v[154:157], v[222:225], v[80:83]
	s_setprio 0
	s_setprio 1
	v_mfma_f32_16x16x32_bf16 v[108:111], v[158:161], v[174:177], v[108:111]
	v_mfma_f32_16x16x32_bf16 v[100:103], v[166:169], v[174:177], v[100:103]
	v_mfma_f32_16x16x32_bf16 v[92:95], v[158:161], v[182:185], v[92:95]
	v_mfma_f32_16x16x32_bf16 v[84:87], v[166:169], v[182:185], v[84:87]
	v_mfma_f32_16x16x32_bf16 v[76:79], v[158:161], v[204:207], v[76:79]
	v_mfma_f32_16x16x32_bf16 v[72:75], v[166:169], v[204:207], v[72:75]
	v_mfma_f32_16x16x32_bf16 v[68:71], v[158:161], v[218:221], v[68:71]
	v_mfma_f32_16x16x32_bf16 v[64:67], v[166:169], v[218:221], v[64:67]
	v_mfma_f32_16x16x32_bf16 v[108:111], v[162:165], v[178:181], v[108:111]
	v_mfma_f32_16x16x32_bf16 v[100:103], v[170:173], v[178:181], v[100:103]
	v_mfma_f32_16x16x32_bf16 v[92:95], v[162:165], v[186:189], v[92:95]
	v_mfma_f32_16x16x32_bf16 v[84:87], v[170:173], v[186:189], v[84:87]
	v_mfma_f32_16x16x32_bf16 v[76:79], v[162:165], v[208:211], v[76:79]
	v_mfma_f32_16x16x32_bf16 v[72:75], v[170:173], v[208:211], v[72:75]
	v_mfma_f32_16x16x32_bf16 v[68:71], v[162:165], v[222:225], v[68:71]
	v_mfma_f32_16x16x32_bf16 v[64:67], v[170:173], v[222:225], v[64:67]
	s_setprio 0
	s_barrier
	s_mov_b32 m0, s24
	v_lshl_add_u64 v[190:191], s[12:13], 0, v[192:193]
	s_add_u32 s48, s12, 0x40000
	ds_read_b128 v[174:177], v141 offset:16384
	ds_read_b128 v[178:181], v141 offset:17408
	ds_read_b128 v[182:185], v141 offset:18432
	ds_read_b128 v[186:189], v141 offset:19456
	ds_read_b128 v[204:207], v141 offset:20480
	ds_read_b128 v[208:211], v141 offset:21504
	ds_read_b128 v[218:221], v141 offset:22528
	ds_read_b128 v[222:225], v141 offset:23552
	global_load_lds_dwordx4 v[190:191], off
	v_lshl_add_u64 v[226:227], s[12:13], 0, v[130:131]
	s_mov_b32 m0, s25
	s_addc_u32 s49, s13, 0
	global_load_lds_dwordx4 v[226:227], off
	v_lshl_add_u64 v[228:229], s[48:49], 0, v[192:193]
	s_mov_b32 m0, s27
	v_lshl_add_u64 v[230:231], s[14:15], 0, v[132:133]
	global_load_lds_dwordx4 v[228:229], off
	v_lshl_add_u64 v[228:229], s[48:49], 0, v[130:131]
	s_mov_b32 m0, s28
	s_nop 0
	global_load_lds_dwordx4 v[228:229], off
	v_lshl_add_u64 v[228:229], s[14:15], 0, v[134:135]
	s_mov_b32 m0, s29
	s_nop 0
	global_load_lds_dwordx4 v[228:229], off
	s_mov_b32 m0, s30
	s_nop 0
	global_load_lds_dwordx4 v[230:231], off
	s_waitcnt vmcnt(8)
	s_waitcnt lgkmcnt(0)
	s_barrier
; #define PG8_STAGE(bufoff, gbase, voff) do { _Pragma("unroll") for (int _i = 0; _i < 2; ++_i) \
;         __builtin_amdgcn_global_load_lds((const unsigned*)((const char*)(gbase) + (voff)[_i]), (PG8_LAS unsigned*)(lds + (bufoff) + ldsw + _i * 8192), 16, 0, 0); } while (0)
; #define PG8_LDA(dst, b, h) do { _Pragma("unroll") for (int m = 0; m < 4; ++m) _Pragma("unroll") for (int k = 0; k < 2; ++k) dst[m][k] = *(const PG8_LAS bf16x8*)(lds + PG8_SA(b, h) + aoff + m * 2048 + k * 1024); } while (0)
; #define PG8_LDB(dst, b, h) do { _Pragma("unroll") for (int n = 0; n < 2; ++n) _Pragma("unroll") for (int k = 0; k < 2; ++k) dst[n][k] = *(const PG8_LAS bf16x8*)(lds + PG8_SB(b, h) + boff + n * 2048 + k * 1024); } while (0)
; #define PG8_MMA(ai, bj, At, Bt) do { __builtin_amdgcn_s_setprio(1); _Pragma("unroll") for (int m = 0; m < 4; ++m) _Pragma("unroll") for (int n = 0; n < 2; ++n) _Pragma("unroll") for (int k = 0; k < 2; ++k) \
;         acc[ai][bj][m][n] = __builtin_amdgcn_mfma_f32_16x16x32_bf16(Bt[n][k], At[m][k], acc[ai][bj][m][n], 0, 0, 0); __builtin_amdgcn_s_setprio(0); } while (0)
; #define PG8_WAIT_V(n) asm volatile("s_waitcnt vmcnt(" #n ")" ::: "memory")
; #define PG8_WAIT_L(n) asm volatile("s_waitcnt lgkmcnt(" #n ")" ::: "memory")
; #define PG8_BAR __builtin_amdgcn_s_barrier()
; #define PG8_SCHED __builtin_amdgcn_sched_barrier(0)
; template <class Epi, class Sched, bool ALIGN_EPI = false, bool SP2 = false>
; __device__ __forceinline__ void gemm_phase(PG8_LAS unsigned char* lds, const Gemm g, const Sched& S, const Epi& E) {
;     ...
;             PG8_WAIT_V(8); PG8_WAIT_L(0); PG8_BAR; PG8_MMA(0, 0, At, B0); PG8_MMA(0, 1, At, B1); PG8_BAR; PG8_SCHED;
;             PG8_LDA(At, 0, 1); PG8_STAGE(PG8_SB(0, 0), b2, voffB); PG8_STAGE(PG8_SB(0, 1), b2 + hstepB, voffB); PG8_STAGE(PG8_SA(0, 0), a2, voffA);
;             PG8_WAIT_V(8); PG8_WAIT_L(0); PG8_BAR; PG8_MMA(1, 0, At, B0); PG8_MMA(1, 1, At, B1); PG8_BAR; PG8_SCHED;
;             PG8_LDB(B0, 1, 0); PG8_LDB(B1, 1, 1); PG8_SCHED; PG8_LDA(At, 1, 0); PG8_STAGE(PG8_SA(0, 1), a2 + hstepA, voffA);
;             PG8_WAIT_V(8); PG8_WAIT_L(0); PG8_BAR; PG8_MMA(0, 0, At, B0); PG8_MMA(0, 1, At, B1); PG8_BAR; PG8_SCHED;
	s_setprio 1
	s_waitcnt lgkmcnt(0)
	s_nop 0
	v_mfma_f32_16x16x32_bf16 v[60:63], v[142:145], v[174:177], v[60:63]
	v_mfma_f32_16x16x32_bf16 v[56:59], v[150:153], v[174:177], v[56:59]
	v_mfma_f32_16x16x32_bf16 v[52:55], v[142:145], v[182:185], v[52:55]
	v_mfma_f32_16x16x32_bf16 v[48:51], v[150:153], v[182:185], v[48:51]
	v_mfma_f32_16x16x32_bf16 v[40:43], v[142:145], v[204:207], v[40:43]
	v_mfma_f32_16x16x32_bf16 v[32:35], v[150:153], v[204:207], v[32:35]
	v_mfma_f32_16x16x32_bf16 v[24:27], v[142:145], v[218:221], v[24:27]
	v_mfma_f32_16x16x32_bf16 v[16:19], v[150:153], v[218:221], v[16:19]
	v_mfma_f32_16x16x32_bf16 v[60:63], v[146:149], v[178:181], v[60:63]
	v_mfma_f32_16x16x32_bf16 v[56:59], v[154:157], v[178:181], v[56:59]
	v_mfma_f32_16x16x32_bf16 v[52:55], v[146:149], v[186:189], v[52:55]
	v_mfma_f32_16x16x32_bf16 v[48:51], v[154:157], v[186:189], v[48:51]
	v_mfma_f32_16x16x32_bf16 v[40:43], v[146:149], v[208:211], v[40:43]
	v_mfma_f32_16x16x32_bf16 v[32:35], v[154:157], v[208:211], v[32:35]
	v_mfma_f32_16x16x32_bf16 v[24:27], v[146:149], v[222:225], v[24:27]
	v_mfma_f32_16x16x32_bf16 v[16:19], v[154:157], v[222:225], v[16:19]
	s_setprio 0
	s_setprio 1
	v_mfma_f32_16x16x32_bf16 v[44:47], v[158:161], v[174:177], v[44:47]
	v_mfma_f32_16x16x32_bf16 v[36:39], v[166:169], v[174:177], v[36:39]
	v_mfma_f32_16x16x32_bf16 v[28:31], v[158:161], v[182:185], v[28:31]
	v_mfma_f32_16x16x32_bf16 v[20:23], v[166:169], v[182:185], v[20:23]
	v_mfma_f32_16x16x32_bf16 v[12:15], v[158:161], v[204:207], v[12:15]
	v_mfma_f32_16x16x32_bf16 v[8:11], v[166:169], v[204:207], v[8:11]
	v_mfma_f32_16x16x32_bf16 v[4:7], v[158:161], v[218:221], v[4:7]
	v_mfma_f32_16x16x32_bf16 v[0:3], v[166:169], v[218:221], v[0:3]
	v_mfma_f32_16x16x32_bf16 v[44:47], v[162:165], v[178:181], v[44:47]
	v_mfma_f32_16x16x32_bf16 v[36:39], v[170:173], v[178:181], v[36:39]
	v_mfma_f32_16x16x32_bf16 v[28:31], v[162:165], v[186:189], v[28:31]
	v_mfma_f32_16x16x32_bf16 v[20:23], v[170:173], v[186:189], v[20:23]
	v_mfma_f32_16x16x32_bf16 v[12:15], v[162:165], v[208:211], v[12:15]
	v_mfma_f32_16x16x32_bf16 v[8:11], v[170:173], v[208:211], v[8:11]
	v_mfma_f32_16x16x32_bf16 v[4:7], v[162:165], v[222:225], v[4:7]
	v_mfma_f32_16x16x32_bf16 v[0:3], v[170:173], v[222:225], v[0:3]
	s_setprio 0
	s_barrier
	v_add_u32_e32 v154, s35, v140
	v_add_u32_e32 v170, s40, v140
	ds_read_b128 v[142:145], v154
	ds_read_b128 v[146:149], v154 offset:1024
	ds_read_b128 v[150:153], v154 offset:2048
	ds_read_b128 v[154:157], v154 offset:3072
	ds_read_b128 v[158:161], v170
	ds_read_b128 v[162:165], v170 offset:1024
	ds_read_b128 v[166:169], v170 offset:2048
	ds_read_b128 v[170:173], v170 offset:3072
	s_add_u32 s14, s14, 0x80000
	s_addc_u32 s15, s15, 0
	s_mov_b32 m0, s31
	v_lshl_add_u64 v[232:233], s[14:15], 0, v[134:135]
	ds_read_b128 v[174:177], v141 offset:32768
	ds_read_b128 v[178:181], v141 offset:33792
	ds_read_b128 v[182:185], v141 offset:34816
	ds_read_b128 v[186:189], v141 offset:35840
	ds_read_b128 v[204:207], v141 offset:36864
	ds_read_b128 v[208:211], v141 offset:37888
	ds_read_b128 v[218:221], v141 offset:38912
	ds_read_b128 v[222:225], v141 offset:39936
	global_load_lds_dwordx4 v[232:233], off
	v_lshl_add_u64 v[232:233], s[14:15], 0, v[132:133]
	s_mov_b32 m0, s34
	s_nop 0
	global_load_lds_dwordx4 v[232:233], off
	s_waitcnt vmcnt(8)
	s_waitcnt lgkmcnt(0)
	s_barrier
	s_setprio 1
	s_waitcnt lgkmcnt(0)
	s_nop 0
	v_mfma_f32_16x16x32_bf16 v[124:127], v[142:145], v[174:177], v[124:127]
	v_mfma_f32_16x16x32_bf16 v[120:123], v[150:153], v[174:177], v[120:123]
	v_mfma_f32_16x16x32_bf16 v[116:119], v[142:145], v[182:185], v[116:119]
	v_mfma_f32_16x16x32_bf16 v[112:115], v[150:153], v[182:185], v[112:115]
	v_mfma_f32_16x16x32_bf16 v[104:107], v[142:145], v[204:207], v[104:107]
	v_mfma_f32_16x16x32_bf16 v[96:99], v[150:153], v[204:207], v[96:99]
	v_mfma_f32_16x16x32_bf16 v[88:91], v[142:145], v[218:221], v[88:91]
	v_mfma_f32_16x16x32_bf16 v[80:83], v[150:153], v[218:221], v[80:83]
	v_mfma_f32_16x16x32_bf16 v[124:127], v[146:149], v[178:181], v[124:127]
	v_mfma_f32_16x16x32_bf16 v[120:123], v[154:157], v[178:181], v[120:123]
	v_mfma_f32_16x16x32_bf16 v[116:119], v[146:149], v[186:189], v[116:119]
	v_mfma_f32_16x16x32_bf16 v[112:115], v[154:157], v[186:189], v[112:115]
	v_mfma_f32_16x16x32_bf16 v[104:107], v[146:149], v[208:211], v[104:107]
	v_mfma_f32_16x16x32_bf16 v[96:99], v[154:157], v[208:211], v[96:99]
	v_mfma_f32_16x16x32_bf16 v[88:91], v[146:149], v[222:225], v[88:91]
	v_mfma_f32_16x16x32_bf16 v[80:83], v[154:157], v[222:225], v[80:83]
	s_setprio 0
	s_setprio 1
	v_mfma_f32_16x16x32_bf16 v[108:111], v[158:161], v[174:177], v[108:111]
	v_mfma_f32_16x16x32_bf16 v[100:103], v[166:169], v[174:177], v[100:103]
	v_mfma_f32_16x16x32_bf16 v[92:95], v[158:161], v[182:185], v[92:95]
	v_mfma_f32_16x16x32_bf16 v[84:87], v[166:169], v[182:185], v[84:87]
	v_mfma_f32_16x16x32_bf16 v[76:79], v[158:161], v[204:207], v[76:79]
	v_mfma_f32_16x16x32_bf16 v[72:75], v[166:169], v[204:207], v[72:75]
	v_mfma_f32_16x16x32_bf16 v[68:71], v[158:161], v[218:221], v[68:71]
	v_mfma_f32_16x16x32_bf16 v[64:67], v[166:169], v[218:221], v[64:67]
	v_mfma_f32_16x16x32_bf16 v[108:111], v[162:165], v[178:181], v[108:111]
	v_mfma_f32_16x16x32_bf16 v[100:103], v[170:173], v[178:181], v[100:103]
	v_mfma_f32_16x16x32_bf16 v[92:95], v[162:165], v[186:189], v[92:95]
	v_mfma_f32_16x16x32_bf16 v[84:87], v[170:173], v[186:189], v[84:87]
	v_mfma_f32_16x16x32_bf16 v[76:79], v[162:165], v[208:211], v[76:79]
	v_mfma_f32_16x16x32_bf16 v[72:75], v[170:173], v[208:211], v[72:75]
	v_mfma_f32_16x16x32_bf16 v[68:71], v[162:165], v[222:225], v[68:71]
	v_mfma_f32_16x16x32_bf16 v[64:67], v[170:173], v[222:225], v[64:67]
	s_setprio 0
	s_barrier
; #define PG8_STAGE(bufoff, gbase, voff) do { _Pragma("unroll") for (int _i = 0; _i < 2; ++_i) \
;         __builtin_amdgcn_global_load_lds((const unsigned*)((const char*)(gbase) + (voff)[_i]), (PG8_LAS unsigned*)(lds + (bufoff) + ldsw + _i * 8192), 16, 0, 0); } while (0)
; #define PG8_LDA(dst, b, h) do { _Pragma("unroll") for (int m = 0; m < 4; ++m) _Pragma("unroll") for (int k = 0; k < 2; ++k) dst[m][k] = *(const PG8_LAS bf16x8*)(lds + PG8_SA(b, h) + aoff + m * 2048 + k * 1024); } while (0)
; #define PG8_MMA(ai, bj, At, Bt) do { __builtin_amdgcn_s_setprio(1); _Pragma("unroll") for (int m = 0; m < 4; ++m) _Pragma("unroll") for (int n = 0; n < 2; ++n) _Pragma("unroll") for (int k = 0; k < 2; ++k) \
;         acc[ai][bj][m][n] = __builtin_amdgcn_mfma_f32_16x16x32_bf16(Bt[n][k], At[m][k], acc[ai][bj][m][n], 0, 0, 0); __builtin_amdgcn_s_setprio(0); } while (0)
; #define PG8_WAIT_V(n) asm volatile("s_waitcnt vmcnt(" #n ")" ::: "memory")
; #define PG8_WAIT_L(n) asm volatile("s_waitcnt lgkmcnt(" #n ")" ::: "memory")
; #define PG8_BAR __builtin_amdgcn_s_barrier()
; #define PG8_SCHED __builtin_amdgcn_sched_barrier(0)
; template <class Epi, class Sched, bool ALIGN_EPI = false, bool SP2 = false>
; __device__ __forceinline__ void gemm_phase(PG8_LAS unsigned char* lds, const Gemm g, const Sched& S, const Epi& E) {
;     ...
;             PG8_LDA(At, 1, 1); PG8_STAGE(PG8_SB(1, 0), b3, voffB); PG8_STAGE(PG8_SB(1, 1), b3 + hstepB, voffB); PG8_STAGE(PG8_SA(1, 0), a3, voffA);
;             PG8_WAIT_V(8); PG8_WAIT_L(0); PG8_BAR; PG8_MMA(1, 0, At, B0); PG8_MMA(1, 1, At, B1); PG8_BAR; PG8_SCHED;
	s_mov_b32 m0, s36
	v_lshl_add_u64 v[190:191], v[190:191], 0, s[76:77]
	s_add_u32 s12, s12, 0x40080
	ds_read_b128 v[174:177], v141 offset:49152
	ds_read_b128 v[178:181], v141 offset:50176
	ds_read_b128 v[182:185], v141 offset:51200
	ds_read_b128 v[186:189], v141 offset:52224
	ds_read_b128 v[204:207], v141 offset:53248
	ds_read_b128 v[208:211], v141 offset:54272
	ds_read_b128 v[218:221], v141 offset:55296
	ds_read_b128 v[222:225], v141 offset:56320
	global_load_lds_dwordx4 v[190:191], off
	v_lshl_add_u64 v[190:191], v[226:227], 0, s[76:77]
	s_mov_b32 m0, s37
	s_addc_u32 s13, s13, 0
	global_load_lds_dwordx4 v[190:191], off
	v_lshl_add_u64 v[190:191], s[12:13], 0, v[192:193]
	s_mov_b32 m0, s41
	s_nop 0
	global_load_lds_dwordx4 v[190:191], off
	v_lshl_add_u64 v[190:191], s[12:13], 0, v[130:131]
	s_mov_b32 m0, s42
	s_nop 0
	global_load_lds_dwordx4 v[190:191], off
	v_lshl_add_u64 v[190:191], v[228:229], 0, s[76:77]
	s_mov_b32 m0, s38
	s_nop 0
	global_load_lds_dwordx4 v[190:191], off
	v_lshl_add_u64 v[190:191], v[230:231], 0, s[76:77]
	s_mov_b32 m0, s39
	s_nop 0
	global_load_lds_dwordx4 v[190:191], off
	s_waitcnt vmcnt(8)
	s_waitcnt lgkmcnt(0)
	s_barrier
	s_setprio 1
	s_waitcnt lgkmcnt(0)
	v_mfma_f32_16x16x32_bf16 v[60:63], v[142:145], v[174:177], v[60:63]
	v_mfma_f32_16x16x32_bf16 v[56:59], v[150:153], v[174:177], v[56:59]
	v_mfma_f32_16x16x32_bf16 v[52:55], v[142:145], v[182:185], v[52:55]
	v_mfma_f32_16x16x32_bf16 v[48:51], v[150:153], v[182:185], v[48:51]
	v_mfma_f32_16x16x32_bf16 v[40:43], v[142:145], v[204:207], v[40:43]
	v_mfma_f32_16x16x32_bf16 v[32:35], v[150:153], v[204:207], v[32:35]
	v_mfma_f32_16x16x32_bf16 v[24:27], v[142:145], v[218:221], v[24:27]
	v_mfma_f32_16x16x32_bf16 v[16:19], v[150:153], v[218:221], v[16:19]
	v_mfma_f32_16x16x32_bf16 v[60:63], v[146:149], v[178:181], v[60:63]
	v_mfma_f32_16x16x32_bf16 v[56:59], v[154:157], v[178:181], v[56:59]
	v_mfma_f32_16x16x32_bf16 v[52:55], v[146:149], v[186:189], v[52:55]
	v_mfma_f32_16x16x32_bf16 v[48:51], v[154:157], v[186:189], v[48:51]
	v_mfma_f32_16x16x32_bf16 v[40:43], v[146:149], v[208:211], v[40:43]
	v_mfma_f32_16x16x32_bf16 v[32:35], v[154:157], v[208:211], v[32:35]
	v_mfma_f32_16x16x32_bf16 v[24:27], v[146:149], v[222:225], v[24:27]
	v_mfma_f32_16x16x32_bf16 v[16:19], v[154:157], v[222:225], v[16:19]
	s_setprio 0
	s_setprio 1
	v_mfma_f32_16x16x32_bf16 v[44:47], v[158:161], v[174:177], v[44:47]
	v_mfma_f32_16x16x32_bf16 v[36:39], v[166:169], v[174:177], v[36:39]
	v_mfma_f32_16x16x32_bf16 v[28:31], v[158:161], v[182:185], v[28:31]
	v_mfma_f32_16x16x32_bf16 v[20:23], v[166:169], v[182:185], v[20:23]
	v_mfma_f32_16x16x32_bf16 v[12:15], v[158:161], v[204:207], v[12:15]
	v_mfma_f32_16x16x32_bf16 v[8:11], v[166:169], v[204:207], v[8:11]
	v_mfma_f32_16x16x32_bf16 v[4:7], v[158:161], v[218:221], v[4:7]
	v_mfma_f32_16x16x32_bf16 v[0:3], v[166:169], v[218:221], v[0:3]
	v_mfma_f32_16x16x32_bf16 v[44:47], v[162:165], v[178:181], v[44:47]
	v_mfma_f32_16x16x32_bf16 v[36:39], v[170:173], v[178:181], v[36:39]
	v_mfma_f32_16x16x32_bf16 v[28:31], v[162:165], v[186:189], v[28:31]
	v_mfma_f32_16x16x32_bf16 v[20:23], v[170:173], v[186:189], v[20:23]
	v_mfma_f32_16x16x32_bf16 v[12:15], v[162:165], v[208:211], v[12:15]
	v_mfma_f32_16x16x32_bf16 v[8:11], v[170:173], v[208:211], v[8:11]
	v_mfma_f32_16x16x32_bf16 v[4:7], v[162:165], v[222:225], v[4:7]
	v_mfma_f32_16x16x32_bf16 v[0:3], v[170:173], v[222:225], v[0:3]
	s_setprio 0
	s_barrier
	s_add_u32 s10, s10, 0x100
	s_addc_u32 s11, s11, 0
	s_cmp_ge_i32 s44, s1
	s_mov_b32 s12, s44
	s_cbranch_scc0 .LBB0_431
; __device__ __forceinline__ v4u pack8(const f32x4 a, const f32x4 b) { v4u w; w.x = cvt_pk_bf16(a[0], a[1]); w.y = cvt_pk_bf16(a[2], a[3]); w.z = cvt_pk_bf16(b[0], b[1]); w.w = cvt_pk_bf16(b[2], b[3]); return w; }
;     __device__ __forceinline__ void operator()(const f32x4 (&acc)[2][2][4][2], const pg8::Unit& u, int wr, int wc, int fr, int fq) const {
;         const int hd = u.pm >> 3, b = (u.pm >> 2) & 1, q = u.pm & 3;
;         const int rowb = modeB ? q * 256 : b * 1024 + hd * 256, colb = modeB ? hd * 256 : q * 256; bf16* Ob = O + (modeB ? (size_t)b * 1024 * 1024 : 0);
; #pragma unroll
;         for (int ai = 0; ai < 2; ++ai)
; #pragma unroll
;             for (int m = 0; m < 4; ++m) { const int row = rowb + ai * 128 + wr * 64 + m * 16 + fr;
; #pragma unroll
;                 for (int bj = 0; bj < 2; ++bj) *(v4u*)(Ob + (size_t)row * 1024 + colb + bj * 128 + wc * 32 + 8 * fq) = pack8(acc[ai][bj][m][0] * scale, acc[ai][bj][m][1] * scale); }
	s_mov_b32 s2, 0x3d800000
	v_pk_mul_f32 v[126:127], v[126:127], s[2:3] op_sel_hi:[1,0]
	v_pk_mul_f32 v[124:125], v[124:125], s[2:3] op_sel_hi:[1,0]
	v_pk_mul_f32 v[122:123], v[122:123], s[2:3] op_sel_hi:[1,0]
	v_pk_mul_f32 v[120:121], v[120:121], s[2:3] op_sel_hi:[1,0]
	v_pk_mul_f32 v[136:137], v[110:111], s[2:3] op_sel_hi:[1,0]
	v_pk_mul_f32 v[138:139], v[108:109], s[2:3] op_sel_hi:[1,0]
	v_pk_mul_f32 v[140:141], v[102:103], s[2:3] op_sel_hi:[1,0]
	v_pk_mul_f32 v[142:143], v[100:101], s[2:3] op_sel_hi:[1,0]
	v_pk_mul_f32 v[100:101], v[118:119], s[2:3] op_sel_hi:[1,0]
	v_pk_mul_f32 v[102:103], v[116:117], s[2:3] op_sel_hi:[1,0]
	v_pk_mul_f32 v[108:109], v[114:115], s[2:3] op_sel_hi:[1,0]
	v_pk_mul_f32 v[110:111], v[112:113], s[2:3] op_sel_hi:[1,0]
	v_pk_mul_f32 v[112:113], v[94:95], s[2:3] op_sel_hi:[1,0]
	v_pk_mul_f32 v[114:115], v[92:93], s[2:3] op_sel_hi:[1,0]
	v_pk_mul_f32 v[116:117], v[86:87], s[2:3] op_sel_hi:[1,0]
	v_pk_mul_f32 v[118:119], v[84:85], s[2:3] op_sel_hi:[1,0]
	v_pk_mul_f32 v[84:85], v[106:107], s[2:3] op_sel_hi:[1,0]
	v_pk_mul_f32 v[86:87], v[104:105], s[2:3] op_sel_hi:[1,0]
	v_pk_mul_f32 v[92:93], v[98:99], s[2:3] op_sel_hi:[1,0]
	v_pk_mul_f32 v[94:95], v[96:97], s[2:3] op_sel_hi:[1,0]
	v_pk_mul_f32 v[96:97], v[78:79], s[2:3] op_sel_hi:[1,0]
	v_pk_mul_f32 v[98:99], v[76:77], s[2:3] op_sel_hi:[1,0]
	v_pk_mul_f32 v[104:105], v[74:75], s[2:3] op_sel_hi:[1,0]
	v_pk_mul_f32 v[106:107], v[72:73], s[2:3] op_sel_hi:[1,0]
	v_pk_mul_f32 v[72:73], v[90:91], s[2:3] op_sel_hi:[1,0]
	v_pk_mul_f32 v[74:75], v[88:89], s[2:3] op_sel_hi:[1,0]
	v_pk_mul_f32 v[76:77], v[82:83], s[2:3] op_sel_hi:[1,0]
	v_pk_mul_f32 v[78:79], v[80:81], s[2:3] op_sel_hi:[1,0]
	v_pk_mul_f32 v[70:71], v[70:71], s[2:3] op_sel_hi:[1,0]
	v_pk_mul_f32 v[68:69], v[68:69], s[2:3] op_sel_hi:[1,0]
	v_pk_mul_f32 v[66:67], v[66:67], s[2:3] op_sel_hi:[1,0]
	v_pk_mul_f32 v[64:65], v[64:65], s[2:3] op_sel_hi:[1,0]
	v_pk_mul_f32 v[62:63], v[62:63], s[2:3] op_sel_hi:[1,0]
	v_pk_mul_f32 v[60:61], v[60:61], s[2:3] op_sel_hi:[1,0]
	v_pk_mul_f32 v[58:59], v[58:59], s[2:3] op_sel_hi:[1,0]
	v_pk_mul_f32 v[56:57], v[56:57], s[2:3] op_sel_hi:[1,0]
	v_pk_mul_f32 v[80:81], v[46:47], s[2:3] op_sel_hi:[1,0]
	v_pk_mul_f32 v[82:83], v[44:45], s[2:3] op_sel_hi:[1,0]
	v_pk_mul_f32 v[88:89], v[38:39], s[2:3] op_sel_hi:[1,0]
	v_pk_mul_f32 v[90:91], v[36:37], s[2:3] op_sel_hi:[1,0]
	v_pk_mul_f32 v[36:37], v[54:55], s[2:3] op_sel_hi:[1,0]
	v_pk_mul_f32 v[38:39], v[52:53], s[2:3] op_sel_hi:[1,0]
	v_pk_mul_f32 v[44:45], v[50:51], s[2:3] op_sel_hi:[1,0]
	v_pk_mul_f32 v[46:47], v[48:49], s[2:3] op_sel_hi:[1,0]
	v_pk_mul_f32 v[48:49], v[30:31], s[2:3] op_sel_hi:[1,0]
	v_pk_mul_f32 v[50:51], v[28:29], s[2:3] op_sel_hi:[1,0]
	v_pk_mul_f32 v[52:53], v[22:23], s[2:3] op_sel_hi:[1,0]
	v_pk_mul_f32 v[54:55], v[20:21], s[2:3] op_sel_hi:[1,0]
	v_pk_mul_f32 v[20:21], v[42:43], s[2:3] op_sel_hi:[1,0]
	v_pk_mul_f32 v[22:23], v[40:41], s[2:3] op_sel_hi:[1,0]
	v_pk_mul_f32 v[28:29], v[34:35], s[2:3] op_sel_hi:[1,0]
	v_pk_mul_f32 v[30:31], v[32:33], s[2:3] op_sel_hi:[1,0]
	v_pk_mul_f32 v[32:33], v[14:15], s[2:3] op_sel_hi:[1,0]
	v_pk_mul_f32 v[34:35], v[12:13], s[2:3] op_sel_hi:[1,0]
	v_pk_mul_f32 v[40:41], v[10:11], s[2:3] op_sel_hi:[1,0]
	v_pk_mul_f32 v[42:43], v[8:9], s[2:3] op_sel_hi:[1,0]
	v_pk_mul_f32 v[8:9], v[26:27], s[2:3] op_sel_hi:[1,0]
	v_pk_mul_f32 v[10:11], v[24:25], s[2:3] op_sel_hi:[1,0]
	v_pk_mul_f32 v[12:13], v[18:19], s[2:3] op_sel_hi:[1,0]
	v_pk_mul_f32 v[14:15], v[16:17], s[2:3] op_sel_hi:[1,0]
	v_pk_mul_f32 v[6:7], v[6:7], s[2:3] op_sel_hi:[1,0]
	v_pk_mul_f32 v[4:5], v[4:5], s[2:3] op_sel_hi:[1,0]
	v_pk_mul_f32 v[2:3], v[2:3], s[2:3] op_sel_hi:[1,0]
	v_pk_mul_f32 v[0:1], v[0:1], s[2:3] op_sel_hi:[1,0]

; #define PG8_STAGE(bufoff, gbase, voff) do { _Pragma("unroll") for (int _i = 0; _i < 2; ++_i) \
;         __builtin_amdgcn_global_load_lds((const unsigned*)((const char*)(gbase) + (voff)[_i]), (PG8_LAS unsigned*)(lds + (bufoff) + ldsw + _i * 8192), 16, 0, 0); } while (0)
; #define PG8_LDA(dst, b, h) do { _Pragma("unroll") for (int m = 0; m < 4; ++m) _Pragma("unroll") for (int k = 0; k < 2; ++k) dst[m][k] = *(const PG8_LAS bf16x8*)(lds + PG8_SA(b, h) + aoff + m * 2048 + k * 1024); } while (0)
; #define PG8_LDB(dst, b, h) do { _Pragma("unroll") for (int n = 0; n < 2; ++n) _Pragma("unroll") for (int k = 0; k < 2; ++k) dst[n][k] = *(const PG8_LAS bf16x8*)(lds + PG8_SB(b, h) + boff + n * 2048 + k * 1024); } while (0)
; #define PG8_MMA(ai, bj, At, Bt) do { __builtin_amdgcn_s_setprio(1); _Pragma("unroll") for (int m = 0; m < 4; ++m) _Pragma("unroll") for (int n = 0; n < 2; ++n) _Pragma("unroll") for (int k = 0; k < 2; ++k) \
;         acc[ai][bj][m][n] = __builtin_amdgcn_mfma_f32_16x16x32_bf16(Bt[n][k], At[m][k], acc[ai][bj][m][n], 0, 0, 0); __builtin_amdgcn_s_setprio(0); } while (0)
; #define PG8_WAIT_V(n) asm volatile("s_waitcnt vmcnt(" #n ")" ::: "memory")
; #define PG8_BAR __builtin_amdgcn_s_barrier()
; template <class Epi, class Sched, bool ALIGN_EPI = false, bool SP2 = false>
; __device__ __forceinline__ void gemm_phase(PG8_LAS unsigned char* lds, const Gemm g, const Sched& S, const Epi& E) {
;     ...
;         for (int t = 0; t < nt; t += 2) {
;             const bool last = (t == nt - 2);
;             const char* a1 = cA + (size_t)(t + 1) * kstep;
;             const char* a2 = last ? nA : cA + (size_t)(t + 2) * kstep; const char* b2 = last ? nB : cB + (size_t)(t + 2) * kstep;
;             const char* a3 = a2 + kstep; const char* b3 = b2 + kstep;
;             if (last && has_next) S.a_ready(nxt);
;             if constexpr (SP2) {
;             PG8_LDB(B0, 0, 0); PG8_LDB(B1, 0, 1); PG8_SCHED; PG8_LDA(At, 0, 0); PG8_STAGE(PG8_SA(1, 1), a1 + hstepA, voffA);
;             PG8_WAIT_V(8); PG8_WAIT_L(0); PG8_BAR; PG8_MMA(0, 0, At, B0); PG8_MMA(0, 1, At, B1); PG8_BAR; PG8_SCHED;
;             PG8_LDA(At, 0, 1); PG8_STAGE(PG8_SB(0, 0), b2, voffB); PG8_STAGE(PG8_SB(0, 1), b2 + hstepB, voffB); PG8_STAGE(PG8_SA(0, 0), a2, voffA);
;             PG8_WAIT_V(8); PG8_WAIT_L(0); PG8_BAR; PG8_MMA(1, 0, At, B0); PG8_MMA(1, 1, At, B1); PG8_BAR; PG8_SCHED;
.LBB0_441:
	s_add_i32 s16, s12, 2
	v_add_u32_e32 v154, s19, v140
	v_add_u32_e32 v170, s24, v140
	s_add_u32 s2, s10, 0xfdfc0080
	ds_read_b128 v[142:145], v154
	ds_read_b128 v[146:149], v154 offset:1024
	ds_read_b128 v[150:153], v154 offset:2048
	ds_read_b128 v[154:157], v154 offset:3072
	ds_read_b128 v[158:161], v170
	ds_read_b128 v[162:165], v170 offset:1024
	ds_read_b128 v[166:169], v170 offset:2048
	ds_read_b128 v[170:173], v170 offset:3072
	s_addc_u32 s13, s11, -1
	s_cmp_lg_u32 s17, s12
	s_cselect_b32 s2, s2, 0
	s_cselect_b32 s13, s13, 0
	s_add_u32 s14, s6, s2
	s_addc_u32 s15, s7, s13
	s_add_u32 s12, s8, s2
	s_addc_u32 s13, s9, s13
	v_lshl_add_u64 v[190:191], v[138:139], 0, s[10:11]
	s_add_i32 m0, s27, 0xc000
	ds_read_b128 v[174:177], v141
	ds_read_b128 v[178:181], v141 offset:1024
	ds_read_b128 v[182:185], v141 offset:2048
	ds_read_b128 v[186:189], v141 offset:3072
	ds_read_b128 v[204:207], v141 offset:4096
	ds_read_b128 v[208:211], v141 offset:5120
	ds_read_b128 v[218:221], v141 offset:6144
	ds_read_b128 v[222:225], v141 offset:7168
	global_load_lds_dwordx4 v[190:191], off
	v_lshl_add_u64 v[190:191], v[136:137], 0, s[10:11]
	s_add_i32 m0, s27, 0xe000
	s_nop 0
	global_load_lds_dwordx4 v[190:191], off
	s_waitcnt vmcnt(8)
	s_waitcnt lgkmcnt(0)
	s_barrier
	s_setprio 1
	s_waitcnt lgkmcnt(0)
	s_nop 0
	v_mfma_f32_16x16x32_bf16 v[120:123], v[142:145], v[174:177], v[120:123]
	v_mfma_f32_16x16x32_bf16 v[124:127], v[150:153], v[174:177], v[124:127]
	v_mfma_f32_16x16x32_bf16 v[108:111], v[142:145], v[182:185], v[108:111]
	v_mfma_f32_16x16x32_bf16 v[104:107], v[150:153], v[182:185], v[104:107]
	v_mfma_f32_16x16x32_bf16 v[92:95], v[142:145], v[204:207], v[92:95]
	v_mfma_f32_16x16x32_bf16 v[88:91], v[150:153], v[204:207], v[88:91]
	v_mfma_f32_16x16x32_bf16 v[76:79], v[142:145], v[218:221], v[76:79]
	v_mfma_f32_16x16x32_bf16 v[72:75], v[150:153], v[218:221], v[72:75]
	v_mfma_f32_16x16x32_bf16 v[120:123], v[146:149], v[178:181], v[120:123]
	v_mfma_f32_16x16x32_bf16 v[124:127], v[154:157], v[178:181], v[124:127]
	v_mfma_f32_16x16x32_bf16 v[108:111], v[146:149], v[186:189], v[108:111]
	v_mfma_f32_16x16x32_bf16 v[104:107], v[154:157], v[186:189], v[104:107]
	v_mfma_f32_16x16x32_bf16 v[92:95], v[146:149], v[208:211], v[92:95]
	v_mfma_f32_16x16x32_bf16 v[88:91], v[154:157], v[208:211], v[88:91]
	v_mfma_f32_16x16x32_bf16 v[76:79], v[146:149], v[222:225], v[76:79]
	v_mfma_f32_16x16x32_bf16 v[72:75], v[154:157], v[222:225], v[72:75]
	s_setprio 0
	s_setprio 1
	v_mfma_f32_16x16x32_bf16 v[116:119], v[158:161], v[174:177], v[116:119]
	v_mfma_f32_16x16x32_bf16 v[112:115], v[166:169], v[174:177], v[112:115]
	v_mfma_f32_16x16x32_bf16 v[100:103], v[158:161], v[182:185], v[100:103]
	v_mfma_f32_16x16x32_bf16 v[96:99], v[166:169], v[182:185], v[96:99]
	v_mfma_f32_16x16x32_bf16 v[84:87], v[158:161], v[204:207], v[84:87]
	v_mfma_f32_16x16x32_bf16 v[80:83], v[166:169], v[204:207], v[80:83]
	v_mfma_f32_16x16x32_bf16 v[68:71], v[158:161], v[218:221], v[68:71]
	v_mfma_f32_16x16x32_bf16 v[64:67], v[166:169], v[218:221], v[64:67]
	v_mfma_f32_16x16x32_bf16 v[116:119], v[162:165], v[178:181], v[116:119]
	v_mfma_f32_16x16x32_bf16 v[112:115], v[170:173], v[178:181], v[112:115]
	v_mfma_f32_16x16x32_bf16 v[100:103], v[162:165], v[186:189], v[100:103]
	v_mfma_f32_16x16x32_bf16 v[96:99], v[170:173], v[186:189], v[96:99]
	v_mfma_f32_16x16x32_bf16 v[84:87], v[162:165], v[208:211], v[84:87]
	v_mfma_f32_16x16x32_bf16 v[80:83], v[170:173], v[208:211], v[80:83]
	v_mfma_f32_16x16x32_bf16 v[68:71], v[162:165], v[222:225], v[68:71]
	v_mfma_f32_16x16x32_bf16 v[64:67], v[170:173], v[222:225], v[64:67]
	s_setprio 0
	s_barrier
	v_lshl_add_u64 v[190:191], s[12:13], 0, v[134:135]
	s_mov_b32 m0, s22
	v_lshl_add_u64 v[226:227], v[190:191], 0, s[84:85]
	ds_read_b128 v[174:177], v141 offset:16384
	ds_read_b128 v[178:181], v141 offset:17408
	ds_read_b128 v[182:185], v141 offset:18432
	ds_read_b128 v[186:189], v141 offset:19456
	ds_read_b128 v[204:207], v141 offset:20480
	ds_read_b128 v[208:211], v141 offset:21504
	ds_read_b128 v[218:221], v141 offset:22528
	ds_read_b128 v[222:225], v141 offset:23552
	global_load_lds_dwordx4 v[226:227], off
	v_lshl_add_u64 v[226:227], s[12:13], 0, v[130:131]
	s_add_u32 s42, s12, 0x80800
	v_lshl_add_u64 v[228:229], v[226:227], 0, s[84:85]
	s_mov_b32 m0, s23
	s_addc_u32 s43, s13, 0
	global_load_lds_dwordx4 v[228:229], off
	v_lshl_add_u64 v[228:229], s[42:43], 0, v[134:135]
	s_mov_b32 m0, s25
	v_lshl_add_u64 v[230:231], s[14:15], 0, v[132:133]
	global_load_lds_dwordx4 v[228:229], off
	v_lshl_add_u64 v[228:229], s[42:43], 0, v[130:131]
	s_mov_b32 m0, s26
	s_nop 0
	global_load_lds_dwordx4 v[228:229], off
	v_lshl_add_u64 v[228:229], s[14:15], 0, v[192:193]
	s_mov_b32 m0, s27
	s_nop 0
	global_load_lds_dwordx4 v[228:229], off
	s_mov_b32 m0, s28
	s_nop 0
	global_load_lds_dwordx4 v[230:231], off
	s_waitcnt vmcnt(8)
	s_waitcnt lgkmcnt(0)
	s_barrier
; #define PG8_STAGE(bufoff, gbase, voff) do { _Pragma("unroll") for (int _i = 0; _i < 2; ++_i) \
;         __builtin_amdgcn_global_load_lds((const unsigned*)((const char*)(gbase) + (voff)[_i]), (PG8_LAS unsigned*)(lds + (bufoff) + ldsw + _i * 8192), 16, 0, 0); } while (0)
; #define PG8_LDA(dst, b, h) do { _Pragma("unroll") for (int m = 0; m < 4; ++m) _Pragma("unroll") for (int k = 0; k < 2; ++k) dst[m][k] = *(const PG8_LAS bf16x8*)(lds + PG8_SA(b, h) + aoff + m * 2048 + k * 1024); } while (0)
; #define PG8_LDB(dst, b, h) do { _Pragma("unroll") for (int n = 0; n < 2; ++n) _Pragma("unroll") for (int k = 0; k < 2; ++k) dst[n][k] = *(const PG8_LAS bf16x8*)(lds + PG8_SB(b, h) + boff + n * 2048 + k * 1024); } while (0)
; #define PG8_MMA(ai, bj, At, Bt) do { __builtin_amdgcn_s_setprio(1); _Pragma("unroll") for (int m = 0; m < 4; ++m) _Pragma("unroll") for (int n = 0; n < 2; ++n) _Pragma("unroll") for (int k = 0; k < 2; ++k) \
;         acc[ai][bj][m][n] = __builtin_amdgcn_mfma_f32_16x16x32_bf16(Bt[n][k], At[m][k], acc[ai][bj][m][n], 0, 0, 0); __builtin_amdgcn_s_setprio(0); } while (0)
; #define PG8_WAIT_V(n) asm volatile("s_waitcnt vmcnt(" #n ")" ::: "memory")
; #define PG8_WAIT_L(n) asm volatile("s_waitcnt lgkmcnt(" #n ")" ::: "memory")
; #define PG8_BAR __builtin_amdgcn_s_barrier()
; #define PG8_SCHED __builtin_amdgcn_sched_barrier(0)
; template <class Epi, class Sched, bool ALIGN_EPI = false, bool SP2 = false>
; __device__ __forceinline__ void gemm_phase(PG8_LAS unsigned char* lds, const Gemm g, const Sched& S, const Epi& E) {
;     ...
;             if constexpr (SP2) {
;             PG8_LDB(B0, 0, 0); PG8_LDB(B1, 0, 1); PG8_SCHED; PG8_LDA(At, 0, 0); PG8_STAGE(PG8_SA(1, 1), a1 + hstepA, voffA);
;             PG8_WAIT_V(8); PG8_WAIT_L(0); PG8_BAR; PG8_MMA(0, 0, At, B0); PG8_MMA(0, 1, At, B1); PG8_BAR; PG8_SCHED;
;             PG8_LDA(At, 0, 1); PG8_STAGE(PG8_SB(0, 0), b2, voffB); PG8_STAGE(PG8_SB(0, 1), b2 + hstepB, voffB); PG8_STAGE(PG8_SA(0, 0), a2, voffA);
;             PG8_WAIT_V(8); PG8_WAIT_L(0); PG8_BAR; PG8_MMA(1, 0, At, B0); PG8_MMA(1, 1, At, B1); PG8_BAR; PG8_SCHED;
;             PG8_LDB(B0, 1, 0); PG8_LDB(B1, 1, 1); PG8_SCHED; PG8_LDA(At, 1, 0); PG8_STAGE(PG8_SA(0, 1), a2 + hstepA, voffA);
;             PG8_WAIT_V(8); PG8_WAIT_L(0); PG8_BAR; PG8_MMA(0, 0, At, B0); PG8_MMA(0, 1, At, B1); PG8_BAR; PG8_SCHED;
	s_setprio 1
	s_waitcnt lgkmcnt(0)
	s_nop 0
	v_mfma_f32_16x16x32_bf16 v[60:63], v[142:145], v[174:177], v[60:63]
	v_mfma_f32_16x16x32_bf16 v[56:59], v[150:153], v[174:177], v[56:59]
	v_mfma_f32_16x16x32_bf16 v[44:47], v[142:145], v[182:185], v[44:47]
	v_mfma_f32_16x16x32_bf16 v[40:43], v[150:153], v[182:185], v[40:43]
	v_mfma_f32_16x16x32_bf16 v[28:31], v[142:145], v[204:207], v[28:31]
	v_mfma_f32_16x16x32_bf16 v[24:27], v[150:153], v[204:207], v[24:27]
	v_mfma_f32_16x16x32_bf16 v[12:15], v[142:145], v[218:221], v[12:15]
	v_mfma_f32_16x16x32_bf16 v[8:11], v[150:153], v[218:221], v[8:11]
	v_mfma_f32_16x16x32_bf16 v[60:63], v[146:149], v[178:181], v[60:63]
	v_mfma_f32_16x16x32_bf16 v[56:59], v[154:157], v[178:181], v[56:59]
	v_mfma_f32_16x16x32_bf16 v[44:47], v[146:149], v[186:189], v[44:47]
	v_mfma_f32_16x16x32_bf16 v[40:43], v[154:157], v[186:189], v[40:43]
	v_mfma_f32_16x16x32_bf16 v[28:31], v[146:149], v[208:211], v[28:31]
	v_mfma_f32_16x16x32_bf16 v[24:27], v[154:157], v[208:211], v[24:27]
	v_mfma_f32_16x16x32_bf16 v[12:15], v[146:149], v[222:225], v[12:15]
	v_mfma_f32_16x16x32_bf16 v[8:11], v[154:157], v[222:225], v[8:11]
	s_setprio 0
	s_setprio 1
	v_mfma_f32_16x16x32_bf16 v[52:55], v[158:161], v[174:177], v[52:55]
	v_mfma_f32_16x16x32_bf16 v[48:51], v[166:169], v[174:177], v[48:51]
	v_mfma_f32_16x16x32_bf16 v[36:39], v[158:161], v[182:185], v[36:39]
	v_mfma_f32_16x16x32_bf16 v[32:35], v[166:169], v[182:185], v[32:35]
	v_mfma_f32_16x16x32_bf16 v[20:23], v[158:161], v[204:207], v[20:23]
	v_mfma_f32_16x16x32_bf16 v[16:19], v[166:169], v[204:207], v[16:19]
	v_mfma_f32_16x16x32_bf16 v[4:7], v[158:161], v[218:221], v[4:7]
	v_mfma_f32_16x16x32_bf16 v[0:3], v[166:169], v[218:221], v[0:3]
	v_mfma_f32_16x16x32_bf16 v[52:55], v[162:165], v[178:181], v[52:55]
	v_mfma_f32_16x16x32_bf16 v[48:51], v[170:173], v[178:181], v[48:51]
	v_mfma_f32_16x16x32_bf16 v[36:39], v[162:165], v[186:189], v[36:39]
	v_mfma_f32_16x16x32_bf16 v[32:35], v[170:173], v[186:189], v[32:35]
	v_mfma_f32_16x16x32_bf16 v[20:23], v[162:165], v[208:211], v[20:23]
	v_mfma_f32_16x16x32_bf16 v[16:19], v[170:173], v[208:211], v[16:19]
	v_mfma_f32_16x16x32_bf16 v[4:7], v[162:165], v[222:225], v[4:7]
	v_mfma_f32_16x16x32_bf16 v[0:3], v[170:173], v[222:225], v[0:3]
	s_setprio 0
	s_barrier
	v_add_u32_e32 v154, s31, v140
	v_add_u32_e32 v170, s38, v140
	ds_read_b128 v[142:145], v154
	ds_read_b128 v[146:149], v154 offset:1024
	ds_read_b128 v[150:153], v154 offset:2048
	ds_read_b128 v[154:157], v154 offset:3072
	ds_read_b128 v[158:161], v170
	ds_read_b128 v[162:165], v170 offset:1024
	ds_read_b128 v[166:169], v170 offset:2048
	ds_read_b128 v[170:173], v170 offset:3072
	s_add_u32 s14, s14, 0x40000
	s_addc_u32 s15, s15, 0
	s_mov_b32 m0, s29
	v_lshl_add_u64 v[232:233], s[14:15], 0, v[192:193]
	ds_read_b128 v[174:177], v141 offset:32768
	ds_read_b128 v[178:181], v141 offset:33792
	ds_read_b128 v[182:185], v141 offset:34816
	ds_read_b128 v[186:189], v141 offset:35840
	ds_read_b128 v[204:207], v141 offset:36864
	ds_read_b128 v[208:211], v141 offset:37888
	ds_read_b128 v[218:221], v141 offset:38912
	ds_read_b128 v[222:225], v141 offset:39936
	global_load_lds_dwordx4 v[232:233], off
	v_lshl_add_u64 v[232:233], s[14:15], 0, v[132:133]
	s_mov_b32 m0, s30
	s_nop 0
	global_load_lds_dwordx4 v[232:233], off
	s_waitcnt vmcnt(8)
	s_waitcnt lgkmcnt(0)
	s_barrier
	s_setprio 1
	s_waitcnt lgkmcnt(0)
	s_nop 0
	v_mfma_f32_16x16x32_bf16 v[120:123], v[142:145], v[174:177], v[120:123]
	v_mfma_f32_16x16x32_bf16 v[124:127], v[150:153], v[174:177], v[124:127]
	v_mfma_f32_16x16x32_bf16 v[108:111], v[142:145], v[182:185], v[108:111]
	v_mfma_f32_16x16x32_bf16 v[104:107], v[150:153], v[182:185], v[104:107]
	v_mfma_f32_16x16x32_bf16 v[92:95], v[142:145], v[204:207], v[92:95]
	v_mfma_f32_16x16x32_bf16 v[88:91], v[150:153], v[204:207], v[88:91]
	v_mfma_f32_16x16x32_bf16 v[76:79], v[142:145], v[218:221], v[76:79]
	v_mfma_f32_16x16x32_bf16 v[72:75], v[150:153], v[218:221], v[72:75]
	v_mfma_f32_16x16x32_bf16 v[120:123], v[146:149], v[178:181], v[120:123]
	v_mfma_f32_16x16x32_bf16 v[124:127], v[154:157], v[178:181], v[124:127]
	v_mfma_f32_16x16x32_bf16 v[108:111], v[146:149], v[186:189], v[108:111]
	v_mfma_f32_16x16x32_bf16 v[104:107], v[154:157], v[186:189], v[104:107]
	v_mfma_f32_16x16x32_bf16 v[92:95], v[146:149], v[208:211], v[92:95]
	v_mfma_f32_16x16x32_bf16 v[88:91], v[154:157], v[208:211], v[88:91]
	v_mfma_f32_16x16x32_bf16 v[76:79], v[146:149], v[222:225], v[76:79]
	v_mfma_f32_16x16x32_bf16 v[72:75], v[154:157], v[222:225], v[72:75]
	s_setprio 0
	s_setprio 1
	v_mfma_f32_16x16x32_bf16 v[116:119], v[158:161], v[174:177], v[116:119]
	v_mfma_f32_16x16x32_bf16 v[112:115], v[166:169], v[174:177], v[112:115]
	v_mfma_f32_16x16x32_bf16 v[100:103], v[158:161], v[182:185], v[100:103]
	v_mfma_f32_16x16x32_bf16 v[96:99], v[166:169], v[182:185], v[96:99]
	v_mfma_f32_16x16x32_bf16 v[84:87], v[158:161], v[204:207], v[84:87]
	v_mfma_f32_16x16x32_bf16 v[80:83], v[166:169], v[204:207], v[80:83]
	v_mfma_f32_16x16x32_bf16 v[68:71], v[158:161], v[218:221], v[68:71]
	v_mfma_f32_16x16x32_bf16 v[64:67], v[166:169], v[218:221], v[64:67]
	v_mfma_f32_16x16x32_bf16 v[116:119], v[162:165], v[178:181], v[116:119]
	v_mfma_f32_16x16x32_bf16 v[112:115], v[170:173], v[178:181], v[112:115]
	v_mfma_f32_16x16x32_bf16 v[100:103], v[162:165], v[186:189], v[100:103]
	v_mfma_f32_16x16x32_bf16 v[96:99], v[170:173], v[186:189], v[96:99]
	v_mfma_f32_16x16x32_bf16 v[84:87], v[162:165], v[208:211], v[84:87]
	v_mfma_f32_16x16x32_bf16 v[80:83], v[170:173], v[208:211], v[80:83]
	v_mfma_f32_16x16x32_bf16 v[68:71], v[162:165], v[222:225], v[68:71]
	v_mfma_f32_16x16x32_bf16 v[64:67], v[170:173], v[222:225], v[64:67]
	s_setprio 0
	s_barrier
; #define PG8_STAGE(bufoff, gbase, voff) do { _Pragma("unroll") for (int _i = 0; _i < 2; ++_i) \
;         __builtin_amdgcn_global_load_lds((const unsigned*)((const char*)(gbase) + (voff)[_i]), (PG8_LAS unsigned*)(lds + (bufoff) + ldsw + _i * 8192), 16, 0, 0); } while (0)
; #define PG8_LDA(dst, b, h) do { _Pragma("unroll") for (int m = 0; m < 4; ++m) _Pragma("unroll") for (int k = 0; k < 2; ++k) dst[m][k] = *(const PG8_LAS bf16x8*)(lds + PG8_SA(b, h) + aoff + m * 2048 + k * 1024); } while (0)
; #define PG8_LDB(dst, b, h) do { _Pragma("unroll") for (int n = 0; n < 2; ++n) _Pragma("unroll") for (int k = 0; k < 2; ++k) dst[n][k] = *(const PG8_LAS bf16x8*)(lds + PG8_SB(b, h) + boff + n * 2048 + k * 1024); } while (0)
; #define PG8_MMA(ai, bj, At, Bt) do { __builtin_amdgcn_s_setprio(1); _Pragma("unroll") for (int m = 0; m < 4; ++m) _Pragma("unroll") for (int n = 0; n < 2; ++n) _Pragma("unroll") for (int k = 0; k < 2; ++k) \
;         acc[ai][bj][m][n] = __builtin_amdgcn_mfma_f32_16x16x32_bf16(Bt[n][k], At[m][k], acc[ai][bj][m][n], 0, 0, 0); __builtin_amdgcn_s_setprio(0); } while (0)
; template <class Epi, class Sched, bool ALIGN_EPI = false, bool SP2 = false>
; __device__ __forceinline__ void gemm_phase(PG8_LAS unsigned char* lds, const Gemm g, const Sched& S, const Epi& E) {
;     ...
;             if constexpr (SP2) {
;             PG8_LDB(B0, 0, 0); PG8_LDB(B1, 0, 1); PG8_SCHED; PG8_LDA(At, 0, 0); PG8_STAGE(PG8_SA(1, 1), a1 + hstepA, voffA);
;             PG8_WAIT_V(8); PG8_WAIT_L(0); PG8_BAR; PG8_MMA(0, 0, At, B0); PG8_MMA(0, 1, At, B1); PG8_BAR; PG8_SCHED;
;             PG8_LDA(At, 0, 1); PG8_STAGE(PG8_SB(0, 0), b2, voffB); PG8_STAGE(PG8_SB(0, 1), b2 + hstepB, voffB); PG8_STAGE(PG8_SA(0, 0), a2, voffA);
;             PG8_WAIT_V(8); PG8_WAIT_L(0); PG8_BAR; PG8_MMA(1, 0, At, B0); PG8_MMA(1, 1, At, B1); PG8_BAR; PG8_SCHED;
;             PG8_LDB(B0, 1, 0); PG8_LDB(B1, 1, 1); PG8_SCHED; PG8_LDA(At, 1, 0); PG8_STAGE(PG8_SA(0, 1), a2 + hstepA, voffA);
;             PG8_WAIT_V(8); PG8_WAIT_L(0); PG8_BAR; PG8_MMA(0, 0, At, B0); PG8_MMA(0, 1, At, B1); PG8_BAR; PG8_SCHED;
;             PG8_LDA(At, 1, 1); PG8_STAGE(PG8_SB(1, 0), b3, voffB); PG8_STAGE(PG8_SB(1, 1), b3 + hstepB, voffB); PG8_STAGE(PG8_SA(1, 0), a3, voffA);
;             PG8_WAIT_V(8); PG8_WAIT_L(0); PG8_BAR; PG8_MMA(1, 0, At, B0); PG8_MMA(1, 1, At, B1); PG8_BAR; PG8_SCHED;
	s_mov_b32 m0, s34
	v_lshl_add_u64 v[190:191], v[190:191], 0, s[90:91]
	s_add_u32 s12, s12, 0x80880
	ds_read_b128 v[174:177], v141 offset:49152
	ds_read_b128 v[178:181], v141 offset:50176
	ds_read_b128 v[182:185], v141 offset:51200
	ds_read_b128 v[186:189], v141 offset:52224
	ds_read_b128 v[204:207], v141 offset:53248
	ds_read_b128 v[208:211], v141 offset:54272
	ds_read_b128 v[218:221], v141 offset:55296
	ds_read_b128 v[222:225], v141 offset:56320
	global_load_lds_dwordx4 v[190:191], off
	v_lshl_add_u64 v[190:191], v[226:227], 0, s[90:91]
	s_mov_b32 m0, s35
	s_addc_u32 s13, s13, 0
	global_load_lds_dwordx4 v[190:191], off
	v_lshl_add_u64 v[190:191], s[12:13], 0, v[134:135]
	s_mov_b32 m0, s39
	s_nop 0
	global_load_lds_dwordx4 v[190:191], off
	v_lshl_add_u64 v[190:191], s[12:13], 0, v[130:131]
	s_mov_b32 m0, s40
	s_nop 0
	global_load_lds_dwordx4 v[190:191], off
	v_lshl_add_u64 v[190:191], v[228:229], 0, s[76:77]
	s_mov_b32 m0, s36
	s_nop 0
	global_load_lds_dwordx4 v[190:191], off
	v_lshl_add_u64 v[190:191], v[230:231], 0, s[76:77]
	s_mov_b32 m0, s37
	s_nop 0
	global_load_lds_dwordx4 v[190:191], off
	s_waitcnt vmcnt(8)
	s_waitcnt lgkmcnt(0)
	s_barrier
	s_setprio 1
	s_waitcnt lgkmcnt(0)
	v_mfma_f32_16x16x32_bf16 v[60:63], v[142:145], v[174:177], v[60:63]
	v_mfma_f32_16x16x32_bf16 v[56:59], v[150:153], v[174:177], v[56:59]
	v_mfma_f32_16x16x32_bf16 v[44:47], v[142:145], v[182:185], v[44:47]
	v_mfma_f32_16x16x32_bf16 v[40:43], v[150:153], v[182:185], v[40:43]
	v_mfma_f32_16x16x32_bf16 v[28:31], v[142:145], v[204:207], v[28:31]
	v_mfma_f32_16x16x32_bf16 v[24:27], v[150:153], v[204:207], v[24:27]
	v_mfma_f32_16x16x32_bf16 v[12:15], v[142:145], v[218:221], v[12:15]
	v_mfma_f32_16x16x32_bf16 v[8:11], v[150:153], v[218:221], v[8:11]
	v_mfma_f32_16x16x32_bf16 v[60:63], v[146:149], v[178:181], v[60:63]
	v_mfma_f32_16x16x32_bf16 v[56:59], v[154:157], v[178:181], v[56:59]
	v_mfma_f32_16x16x32_bf16 v[44:47], v[146:149], v[186:189], v[44:47]
	v_mfma_f32_16x16x32_bf16 v[40:43], v[154:157], v[186:189], v[40:43]
	v_mfma_f32_16x16x32_bf16 v[28:31], v[146:149], v[208:211], v[28:31]
	v_mfma_f32_16x16x32_bf16 v[24:27], v[154:157], v[208:211], v[24:27]
	v_mfma_f32_16x16x32_bf16 v[12:15], v[146:149], v[222:225], v[12:15]
	v_mfma_f32_16x16x32_bf16 v[8:11], v[154:157], v[222:225], v[8:11]
	s_setprio 0
	s_setprio 1
	v_mfma_f32_16x16x32_bf16 v[52:55], v[158:161], v[174:177], v[52:55]
	v_mfma_f32_16x16x32_bf16 v[48:51], v[166:169], v[174:177], v[48:51]
	v_mfma_f32_16x16x32_bf16 v[36:39], v[158:161], v[182:185], v[36:39]
	v_mfma_f32_16x16x32_bf16 v[32:35], v[166:169], v[182:185], v[32:35]
	v_mfma_f32_16x16x32_bf16 v[20:23], v[158:161], v[204:207], v[20:23]
	v_mfma_f32_16x16x32_bf16 v[16:19], v[166:169], v[204:207], v[16:19]
	v_mfma_f32_16x16x32_bf16 v[4:7], v[158:161], v[218:221], v[4:7]
	v_mfma_f32_16x16x32_bf16 v[0:3], v[166:169], v[218:221], v[0:3]
	v_mfma_f32_16x16x32_bf16 v[52:55], v[162:165], v[178:181], v[52:55]
	v_mfma_f32_16x16x32_bf16 v[48:51], v[170:173], v[178:181], v[48:51]
	v_mfma_f32_16x16x32_bf16 v[36:39], v[162:165], v[186:189], v[36:39]
	v_mfma_f32_16x16x32_bf16 v[32:35], v[170:173], v[186:189], v[32:35]
	v_mfma_f32_16x16x32_bf16 v[20:23], v[162:165], v[208:211], v[20:23]
	v_mfma_f32_16x16x32_bf16 v[16:19], v[170:173], v[208:211], v[16:19]
	v_mfma_f32_16x16x32_bf16 v[4:7], v[162:165], v[222:225], v[4:7]
	v_mfma_f32_16x16x32_bf16 v[0:3], v[170:173], v[222:225], v[0:3]
	s_setprio 0
	s_barrier
	s_add_u32 s10, s10, 0x100
	s_addc_u32 s11, s11, 0
	s_cmp_ge_i32 s16, s1
	s_mov_b32 s12, s16
	s_cbranch_scc0 .LBB0_441

; #define PG8_STAGE(bufoff, gbase, voff) do { _Pragma("unroll") for (int _i = 0; _i < 2; ++_i) \
;         __builtin_amdgcn_global_load_lds((const unsigned*)((const char*)(gbase) + (voff)[_i]), (PG8_LAS unsigned*)(lds + (bufoff) + ldsw + _i * 8192), 16, 0, 0); } while (0)
; #define PG8_LDA(dst, b, h) do { _Pragma("unroll") for (int m = 0; m < 4; ++m) _Pragma("unroll") for (int k = 0; k < 2; ++k) dst[m][k] = *(const PG8_LAS bf16x8*)(lds + PG8_SA(b, h) + aoff + m * 2048 + k * 1024); } while (0)
; #define PG8_LDB(dst, b, h) do { _Pragma("unroll") for (int n = 0; n < 2; ++n) _Pragma("unroll") for (int k = 0; k < 2; ++k) dst[n][k] = *(const PG8_LAS bf16x8*)(lds + PG8_SB(b, h) + boff + n * 2048 + k * 1024); } while (0)
; #define PG8_MMA(ai, bj, At, Bt) do { __builtin_amdgcn_s_setprio(1); _Pragma("unroll") for (int m = 0; m < 4; ++m) _Pragma("unroll") for (int n = 0; n < 2; ++n) _Pragma("unroll") for (int k = 0; k < 2; ++k) \
;         acc[ai][bj][m][n] = __builtin_amdgcn_mfma_f32_16x16x32_bf16(Bt[n][k], At[m][k], acc[ai][bj][m][n], 0, 0, 0); __builtin_amdgcn_s_setprio(0); } while (0)
; #define PG8_WAIT_V(n) asm volatile("s_waitcnt vmcnt(" #n ")" ::: "memory")
; #define PG8_BAR __builtin_amdgcn_s_barrier()
; template <class Epi, class Sched, bool ALIGN_EPI = false, bool SP2 = false>
; __device__ __forceinline__ void gemm_phase(PG8_LAS unsigned char* lds, const Gemm g, const Sched& S, const Epi& E) {
;     ...
;         for (int t = 0; t < nt; t += 2) {
;             const bool last = (t == nt - 2);
;             const char* a1 = cA + (size_t)(t + 1) * kstep;
;             const char* a2 = last ? nA : cA + (size_t)(t + 2) * kstep; const char* b2 = last ? nB : cB + (size_t)(t + 2) * kstep;
;             const char* a3 = a2 + kstep; const char* b3 = b2 + kstep;
;             if (last && has_next) S.a_ready(nxt);
;             if constexpr (SP2) {
;             PG8_LDB(B0, 0, 0); PG8_LDB(B1, 0, 1); PG8_SCHED; PG8_LDA(At, 0, 0); PG8_STAGE(PG8_SA(1, 1), a1 + hstepA, voffA);
;             PG8_WAIT_V(8); PG8_WAIT_L(0); PG8_BAR; PG8_MMA(0, 0, At, B0); PG8_MMA(0, 1, At, B1); PG8_BAR; PG8_SCHED;
;             PG8_LDA(At, 0, 1); PG8_STAGE(PG8_SB(0, 0), b2, voffB); PG8_STAGE(PG8_SB(0, 1), b2 + hstepB, voffB); PG8_STAGE(PG8_SA(0, 0), a2, voffA);
;             PG8_WAIT_V(8); PG8_WAIT_L(0); PG8_BAR; PG8_MMA(1, 0, At, B0); PG8_MMA(1, 1, At, B1); PG8_BAR; PG8_SCHED;
.LBB0_885:
	v_add_u32_e32 v142, s9, v145
	ds_read_b128 v[138:141], v142
	ds_read_b128 v[148:151], v142 offset:1024
	ds_read_b128 v[152:155], v142 offset:2048
	ds_read_b128 v[156:159], v142 offset:3072
	v_add_u32_e32 v142, s42, v145
	ds_read_b128 v[160:163], v142
	ds_read_b128 v[164:167], v142 offset:1024
	ds_read_b128 v[168:171], v142 offset:2048
	ds_read_b128 v[172:175], v142 offset:3072
	s_add_u32 s2, s28, 0xfffc0080
	s_addc_u32 s30, s29, -1
	s_cmp_eq_u32 s82, 12
	s_cselect_b32 s35, s21, s30
	s_cselect_b32 s34, s27, s2
	s_cselect_b32 s31, s19, s79
	s_cselect_b32 s30, s68, s78
	v_lshl_add_u64 v[142:143], s[28:29], 0, v[136:137]
	s_add_i32 m0, s45, 0xc000
	ds_read_b128 v[176:179], v147
	ds_read_b128 v[180:183], v147 offset:1024
	ds_read_b128 v[184:187], v147 offset:2048
	ds_read_b128 v[188:191], v147 offset:3072
	ds_read_b128 v[204:207], v147 offset:4096
	ds_read_b128 v[208:211], v147 offset:5120
	ds_read_b128 v[218:221], v147 offset:6144
	ds_read_b128 v[222:225], v147 offset:7168
	global_load_lds_dwordx4 v[142:143], off
	v_lshl_add_u64 v[142:143], s[28:29], 0, v[134:135]
	s_add_i32 m0, s45, 0xe000
	s_nop 0
	global_load_lds_dwordx4 v[142:143], off
	s_waitcnt vmcnt(8)
	s_waitcnt lgkmcnt(0)
	s_barrier
	s_setprio 1
	s_waitcnt lgkmcnt(0)
	s_nop 0
	v_mfma_f32_16x16x32_bf16 v[124:127], v[138:141], v[176:179], v[124:127]
	v_mfma_f32_16x16x32_bf16 v[120:123], v[152:155], v[176:179], v[120:123]
	v_mfma_f32_16x16x32_bf16 v[108:111], v[138:141], v[184:187], v[108:111]
	v_mfma_f32_16x16x32_bf16 v[104:107], v[152:155], v[184:187], v[104:107]
	v_mfma_f32_16x16x32_bf16 v[92:95], v[138:141], v[204:207], v[92:95]
	v_mfma_f32_16x16x32_bf16 v[88:91], v[152:155], v[204:207], v[88:91]
	v_mfma_f32_16x16x32_bf16 v[76:79], v[138:141], v[218:221], v[76:79]
	v_mfma_f32_16x16x32_bf16 v[72:75], v[152:155], v[218:221], v[72:75]
	v_mfma_f32_16x16x32_bf16 v[124:127], v[148:151], v[180:183], v[124:127]
	v_mfma_f32_16x16x32_bf16 v[120:123], v[156:159], v[180:183], v[120:123]
	v_mfma_f32_16x16x32_bf16 v[108:111], v[148:151], v[188:191], v[108:111]
	v_mfma_f32_16x16x32_bf16 v[104:107], v[156:159], v[188:191], v[104:107]
	v_mfma_f32_16x16x32_bf16 v[92:95], v[148:151], v[208:211], v[92:95]
	v_mfma_f32_16x16x32_bf16 v[88:91], v[156:159], v[208:211], v[88:91]
	v_mfma_f32_16x16x32_bf16 v[76:79], v[148:151], v[222:225], v[76:79]
	v_mfma_f32_16x16x32_bf16 v[72:75], v[156:159], v[222:225], v[72:75]
	s_setprio 0
	s_setprio 1
	v_mfma_f32_16x16x32_bf16 v[116:119], v[160:163], v[176:179], v[116:119]
	v_mfma_f32_16x16x32_bf16 v[112:115], v[168:171], v[176:179], v[112:115]
	v_mfma_f32_16x16x32_bf16 v[100:103], v[160:163], v[184:187], v[100:103]
	v_mfma_f32_16x16x32_bf16 v[96:99], v[168:171], v[184:187], v[96:99]
	v_mfma_f32_16x16x32_bf16 v[84:87], v[160:163], v[204:207], v[84:87]
	v_mfma_f32_16x16x32_bf16 v[80:83], v[168:171], v[204:207], v[80:83]
	v_mfma_f32_16x16x32_bf16 v[68:71], v[160:163], v[218:221], v[68:71]
	v_mfma_f32_16x16x32_bf16 v[64:67], v[168:171], v[218:221], v[64:67]
	v_mfma_f32_16x16x32_bf16 v[116:119], v[164:167], v[180:183], v[116:119]
	v_mfma_f32_16x16x32_bf16 v[112:115], v[172:175], v[180:183], v[112:115]
	v_mfma_f32_16x16x32_bf16 v[100:103], v[164:167], v[188:191], v[100:103]
	v_mfma_f32_16x16x32_bf16 v[96:99], v[172:175], v[188:191], v[96:99]
	v_mfma_f32_16x16x32_bf16 v[84:87], v[164:167], v[208:211], v[84:87]
	v_mfma_f32_16x16x32_bf16 v[80:83], v[172:175], v[208:211], v[80:83]
	v_mfma_f32_16x16x32_bf16 v[68:71], v[164:167], v[222:225], v[68:71]
	v_mfma_f32_16x16x32_bf16 v[64:67], v[172:175], v[222:225], v[64:67]
	s_setprio 0
	s_barrier
	s_mov_b32 m0, s40
	v_lshl_add_u64 v[142:143], s[30:31], 0, v[192:193]
	s_add_u32 s84, s30, 0x40000
	ds_read_b128 v[176:179], v147 offset:16384
	ds_read_b128 v[180:183], v147 offset:17408
	ds_read_b128 v[184:187], v147 offset:18432
	ds_read_b128 v[188:191], v147 offset:19456
	ds_read_b128 v[204:207], v147 offset:20480
	ds_read_b128 v[208:211], v147 offset:21504
	ds_read_b128 v[218:221], v147 offset:22528
	ds_read_b128 v[222:225], v147 offset:23552
	global_load_lds_dwordx4 v[142:143], off
	v_lshl_add_u64 v[226:227], s[30:31], 0, v[132:133]
	s_mov_b32 m0, s41
	s_addc_u32 s85, s31, 0
	global_load_lds_dwordx4 v[226:227], off
	v_lshl_add_u64 v[228:229], s[84:85], 0, v[192:193]
	s_mov_b32 m0, s43
	v_lshl_add_u64 v[230:231], s[34:35], 0, v[130:131]
	global_load_lds_dwordx4 v[228:229], off
	v_lshl_add_u64 v[228:229], s[84:85], 0, v[132:133]
	s_mov_b32 m0, s44
	s_nop 0
	global_load_lds_dwordx4 v[228:229], off
	v_lshl_add_u64 v[228:229], s[34:35], 0, v[128:129]
	s_mov_b32 m0, s45
	s_nop 0
	global_load_lds_dwordx4 v[228:229], off
	s_mov_b32 m0, s48
	s_nop 0
	global_load_lds_dwordx4 v[230:231], off
	s_waitcnt vmcnt(8)
	s_waitcnt lgkmcnt(0)
	s_barrier
; #define PG8_STAGE(bufoff, gbase, voff) do { _Pragma("unroll") for (int _i = 0; _i < 2; ++_i) \
;         __builtin_amdgcn_global_load_lds((const unsigned*)((const char*)(gbase) + (voff)[_i]), (PG8_LAS unsigned*)(lds + (bufoff) + ldsw + _i * 8192), 16, 0, 0); } while (0)
; #define PG8_LDA(dst, b, h) do { _Pragma("unroll") for (int m = 0; m < 4; ++m) _Pragma("unroll") for (int k = 0; k < 2; ++k) dst[m][k] = *(const PG8_LAS bf16x8*)(lds + PG8_SA(b, h) + aoff + m * 2048 + k * 1024); } while (0)
; #define PG8_LDB(dst, b, h) do { _Pragma("unroll") for (int n = 0; n < 2; ++n) _Pragma("unroll") for (int k = 0; k < 2; ++k) dst[n][k] = *(const PG8_LAS bf16x8*)(lds + PG8_SB(b, h) + boff + n * 2048 + k * 1024); } while (0)
; #define PG8_MMA(ai, bj, At, Bt) do { __builtin_amdgcn_s_setprio(1); _Pragma("unroll") for (int m = 0; m < 4; ++m) _Pragma("unroll") for (int n = 0; n < 2; ++n) _Pragma("unroll") for (int k = 0; k < 2; ++k) \
;         acc[ai][bj][m][n] = __builtin_amdgcn_mfma_f32_16x16x32_bf16(Bt[n][k], At[m][k], acc[ai][bj][m][n], 0, 0, 0); __builtin_amdgcn_s_setprio(0); } while (0)
; #define PG8_WAIT_V(n) asm volatile("s_waitcnt vmcnt(" #n ")" ::: "memory")
; #define PG8_WAIT_L(n) asm volatile("s_waitcnt lgkmcnt(" #n ")" ::: "memory")
; #define PG8_BAR __builtin_amdgcn_s_barrier()
; #define PG8_SCHED __builtin_amdgcn_sched_barrier(0)
; template <class Epi, class Sched, bool ALIGN_EPI = false, bool SP2 = false>
; __device__ __forceinline__ void gemm_phase(PG8_LAS unsigned char* lds, const Gemm g, const Sched& S, const Epi& E) {
;     ...
;             if constexpr (SP2) {
;             PG8_LDB(B0, 0, 0); PG8_LDB(B1, 0, 1); PG8_SCHED; PG8_LDA(At, 0, 0); PG8_STAGE(PG8_SA(1, 1), a1 + hstepA, voffA);
;             PG8_WAIT_V(8); PG8_WAIT_L(0); PG8_BAR; PG8_MMA(0, 0, At, B0); PG8_MMA(0, 1, At, B1); PG8_BAR; PG8_SCHED;
;             PG8_LDA(At, 0, 1); PG8_STAGE(PG8_SB(0, 0), b2, voffB); PG8_STAGE(PG8_SB(0, 1), b2 + hstepB, voffB); PG8_STAGE(PG8_SA(0, 0), a2, voffA);
;             PG8_WAIT_V(8); PG8_WAIT_L(0); PG8_BAR; PG8_MMA(1, 0, At, B0); PG8_MMA(1, 1, At, B1); PG8_BAR; PG8_SCHED;
;             PG8_LDB(B0, 1, 0); PG8_LDB(B1, 1, 1); PG8_SCHED; PG8_LDA(At, 1, 0); PG8_STAGE(PG8_SA(0, 1), a2 + hstepA, voffA);
;             PG8_WAIT_V(8); PG8_WAIT_L(0); PG8_BAR; PG8_MMA(0, 0, At, B0); PG8_MMA(0, 1, At, B1); PG8_BAR; PG8_SCHED;
	s_setprio 1
	s_waitcnt lgkmcnt(0)
	s_nop 0
	v_mfma_f32_16x16x32_bf16 v[60:63], v[138:141], v[176:179], v[60:63]
	v_mfma_f32_16x16x32_bf16 v[56:59], v[152:155], v[176:179], v[56:59]
	v_mfma_f32_16x16x32_bf16 v[44:47], v[138:141], v[184:187], v[44:47]
	v_mfma_f32_16x16x32_bf16 v[40:43], v[152:155], v[184:187], v[40:43]
	v_mfma_f32_16x16x32_bf16 v[28:31], v[138:141], v[204:207], v[28:31]
	v_mfma_f32_16x16x32_bf16 v[24:27], v[152:155], v[204:207], v[24:27]
	v_mfma_f32_16x16x32_bf16 v[12:15], v[138:141], v[218:221], v[12:15]
	v_mfma_f32_16x16x32_bf16 v[8:11], v[152:155], v[218:221], v[8:11]
	v_mfma_f32_16x16x32_bf16 v[60:63], v[148:151], v[180:183], v[60:63]
	v_mfma_f32_16x16x32_bf16 v[56:59], v[156:159], v[180:183], v[56:59]
	v_mfma_f32_16x16x32_bf16 v[44:47], v[148:151], v[188:191], v[44:47]
	v_mfma_f32_16x16x32_bf16 v[40:43], v[156:159], v[188:191], v[40:43]
	v_mfma_f32_16x16x32_bf16 v[28:31], v[148:151], v[208:211], v[28:31]
	v_mfma_f32_16x16x32_bf16 v[24:27], v[156:159], v[208:211], v[24:27]
	v_mfma_f32_16x16x32_bf16 v[12:15], v[148:151], v[222:225], v[12:15]
	v_mfma_f32_16x16x32_bf16 v[8:11], v[156:159], v[222:225], v[8:11]
	s_setprio 0
	s_setprio 1
	v_mfma_f32_16x16x32_bf16 v[52:55], v[160:163], v[176:179], v[52:55]
	v_mfma_f32_16x16x32_bf16 v[48:51], v[168:171], v[176:179], v[48:51]
	v_mfma_f32_16x16x32_bf16 v[36:39], v[160:163], v[184:187], v[36:39]
	v_mfma_f32_16x16x32_bf16 v[32:35], v[168:171], v[184:187], v[32:35]
	v_mfma_f32_16x16x32_bf16 v[20:23], v[160:163], v[204:207], v[20:23]
	v_mfma_f32_16x16x32_bf16 v[16:19], v[168:171], v[204:207], v[16:19]
	v_mfma_f32_16x16x32_bf16 v[4:7], v[160:163], v[218:221], v[4:7]
	v_mfma_f32_16x16x32_bf16 v[0:3], v[168:171], v[218:221], v[0:3]
	v_mfma_f32_16x16x32_bf16 v[52:55], v[164:167], v[180:183], v[52:55]
	v_mfma_f32_16x16x32_bf16 v[48:51], v[172:175], v[180:183], v[48:51]
	v_mfma_f32_16x16x32_bf16 v[36:39], v[164:167], v[188:191], v[36:39]
	v_mfma_f32_16x16x32_bf16 v[32:35], v[172:175], v[188:191], v[32:35]
	v_mfma_f32_16x16x32_bf16 v[20:23], v[164:167], v[208:211], v[20:23]
	v_mfma_f32_16x16x32_bf16 v[16:19], v[172:175], v[208:211], v[16:19]
	v_mfma_f32_16x16x32_bf16 v[4:7], v[164:167], v[222:225], v[4:7]
	v_mfma_f32_16x16x32_bf16 v[0:3], v[172:175], v[222:225], v[0:3]
	s_setprio 0
	s_barrier
	v_add_u32_e32 v156, s60, v145
	v_add_u32_e32 v172, s67, v145
	ds_read_b128 v[138:141], v156
	ds_read_b128 v[148:151], v156 offset:1024
	ds_read_b128 v[152:155], v156 offset:2048
	ds_read_b128 v[156:159], v156 offset:3072
	ds_read_b128 v[160:163], v172
	ds_read_b128 v[164:167], v172 offset:1024
	ds_read_b128 v[168:171], v172 offset:2048
	ds_read_b128 v[172:175], v172 offset:3072
	s_add_u32 s34, s34, 0x40000
	s_addc_u32 s35, s35, 0
	s_mov_b32 m0, s49
	v_lshl_add_u64 v[232:233], s[34:35], 0, v[128:129]
	ds_read_b128 v[176:179], v147 offset:32768
	ds_read_b128 v[180:183], v147 offset:33792
	ds_read_b128 v[184:187], v147 offset:34816
	ds_read_b128 v[188:191], v147 offset:35840
	ds_read_b128 v[204:207], v147 offset:36864
	ds_read_b128 v[208:211], v147 offset:37888
	ds_read_b128 v[218:221], v147 offset:38912
	ds_read_b128 v[222:225], v147 offset:39936
	global_load_lds_dwordx4 v[232:233], off
	v_lshl_add_u64 v[232:233], s[34:35], 0, v[130:131]
	s_mov_b32 m0, s50
	s_nop 0
	global_load_lds_dwordx4 v[232:233], off
	s_waitcnt vmcnt(8)
	s_waitcnt lgkmcnt(0)
	s_barrier
	s_setprio 1
	s_waitcnt lgkmcnt(0)
	s_nop 0
	v_mfma_f32_16x16x32_bf16 v[124:127], v[138:141], v[176:179], v[124:127]
	v_mfma_f32_16x16x32_bf16 v[120:123], v[152:155], v[176:179], v[120:123]
	v_mfma_f32_16x16x32_bf16 v[108:111], v[138:141], v[184:187], v[108:111]
	v_mfma_f32_16x16x32_bf16 v[104:107], v[152:155], v[184:187], v[104:107]
	v_mfma_f32_16x16x32_bf16 v[92:95], v[138:141], v[204:207], v[92:95]
	v_mfma_f32_16x16x32_bf16 v[88:91], v[152:155], v[204:207], v[88:91]
	v_mfma_f32_16x16x32_bf16 v[76:79], v[138:141], v[218:221], v[76:79]
	v_mfma_f32_16x16x32_bf16 v[72:75], v[152:155], v[218:221], v[72:75]
	v_mfma_f32_16x16x32_bf16 v[124:127], v[148:151], v[180:183], v[124:127]
	v_mfma_f32_16x16x32_bf16 v[120:123], v[156:159], v[180:183], v[120:123]
	v_mfma_f32_16x16x32_bf16 v[108:111], v[148:151], v[188:191], v[108:111]
	v_mfma_f32_16x16x32_bf16 v[104:107], v[156:159], v[188:191], v[104:107]
	v_mfma_f32_16x16x32_bf16 v[92:95], v[148:151], v[208:211], v[92:95]
	v_mfma_f32_16x16x32_bf16 v[88:91], v[156:159], v[208:211], v[88:91]
	v_mfma_f32_16x16x32_bf16 v[76:79], v[148:151], v[222:225], v[76:79]
	v_mfma_f32_16x16x32_bf16 v[72:75], v[156:159], v[222:225], v[72:75]
	s_setprio 0
	s_setprio 1
	v_mfma_f32_16x16x32_bf16 v[116:119], v[160:163], v[176:179], v[116:119]
	v_mfma_f32_16x16x32_bf16 v[112:115], v[168:171], v[176:179], v[112:115]
	v_mfma_f32_16x16x32_bf16 v[100:103], v[160:163], v[184:187], v[100:103]
	v_mfma_f32_16x16x32_bf16 v[96:99], v[168:171], v[184:187], v[96:99]
	v_mfma_f32_16x16x32_bf16 v[84:87], v[160:163], v[204:207], v[84:87]
	v_mfma_f32_16x16x32_bf16 v[80:83], v[168:171], v[204:207], v[80:83]
	v_mfma_f32_16x16x32_bf16 v[68:71], v[160:163], v[218:221], v[68:71]
	v_mfma_f32_16x16x32_bf16 v[64:67], v[168:171], v[218:221], v[64:67]
	v_mfma_f32_16x16x32_bf16 v[116:119], v[164:167], v[180:183], v[116:119]
	v_mfma_f32_16x16x32_bf16 v[112:115], v[172:175], v[180:183], v[112:115]
	v_mfma_f32_16x16x32_bf16 v[100:103], v[164:167], v[188:191], v[100:103]
	v_mfma_f32_16x16x32_bf16 v[96:99], v[172:175], v[188:191], v[96:99]
	v_mfma_f32_16x16x32_bf16 v[84:87], v[164:167], v[208:211], v[84:87]
	v_mfma_f32_16x16x32_bf16 v[80:83], v[172:175], v[208:211], v[80:83]
	v_mfma_f32_16x16x32_bf16 v[68:71], v[164:167], v[222:225], v[68:71]
	v_mfma_f32_16x16x32_bf16 v[64:67], v[172:175], v[222:225], v[64:67]
	s_setprio 0
	s_barrier
; #define PG8_STAGE(bufoff, gbase, voff) do { _Pragma("unroll") for (int _i = 0; _i < 2; ++_i) \
;         __builtin_amdgcn_global_load_lds((const unsigned*)((const char*)(gbase) + (voff)[_i]), (PG8_LAS unsigned*)(lds + (bufoff) + ldsw + _i * 8192), 16, 0, 0); } while (0)
; #define PG8_LDA(dst, b, h) do { _Pragma("unroll") for (int m = 0; m < 4; ++m) _Pragma("unroll") for (int k = 0; k < 2; ++k) dst[m][k] = *(const PG8_LAS bf16x8*)(lds + PG8_SA(b, h) + aoff + m * 2048 + k * 1024); } while (0)
; #define PG8_MMA(ai, bj, At, Bt) do { __builtin_amdgcn_s_setprio(1); _Pragma("unroll") for (int m = 0; m < 4; ++m) _Pragma("unroll") for (int n = 0; n < 2; ++n) _Pragma("unroll") for (int k = 0; k < 2; ++k) \
;         acc[ai][bj][m][n] = __builtin_amdgcn_mfma_f32_16x16x32_bf16(Bt[n][k], At[m][k], acc[ai][bj][m][n], 0, 0, 0); __builtin_amdgcn_s_setprio(0); } while (0)
; #define PG8_WAIT_V(n) asm volatile("s_waitcnt vmcnt(" #n ")" ::: "memory")
; #define PG8_WAIT_L(n) asm volatile("s_waitcnt lgkmcnt(" #n ")" ::: "memory")
; #define PG8_BAR __builtin_amdgcn_s_barrier()
; #define PG8_SCHED __builtin_amdgcn_sched_barrier(0)
; template <class Epi, class Sched, bool ALIGN_EPI = false, bool SP2 = false>
; __device__ __forceinline__ void gemm_phase(PG8_LAS unsigned char* lds, const Gemm g, const Sched& S, const Epi& E) {
;     ...
;             PG8_LDA(At, 1, 1); PG8_STAGE(PG8_SB(1, 0), b3, voffB); PG8_STAGE(PG8_SB(1, 1), b3 + hstepB, voffB); PG8_STAGE(PG8_SA(1, 0), a3, voffA);
;             PG8_WAIT_V(8); PG8_WAIT_L(0); PG8_BAR; PG8_MMA(1, 0, At, B0); PG8_MMA(1, 1, At, B1); PG8_BAR; PG8_SCHED;
;     ...
;         if constexpr (ALIGN_EPI) { if (wr == 0) PG8_BAR; }
;     __device__ __forceinline__ void operator()(const f32x4 (&acc)[2][2][4][2], const pg8::Unit& u, int wr, int wc, int fr, int fq) const {
;         const int row0 = u.pm * 256 + wr * 64 + fr, col0 = u.pn * 256 + wc * 32 + 8 * fq;
; #pragma unroll
;         for (int ai = 0; ai < 2; ++ai)
; #pragma unroll
;             for (int m = 0; m < 4; ++m) {
;                 const int row = row0 + ai * 128 + m * 16; float ss = 0.f;
; #pragma unroll
;                 for (int bj = 0; bj < 2; ++bj) {
;                     const size_t off = (size_t)row * DM + col0 + bj * 128;
;                     const v4u b = *(const v4u*)(xb + off);
	s_mov_b32 m0, s61
	v_lshl_add_u64 v[142:143], v[142:143], 0, s[76:77]
	s_add_u32 s30, s30, 0x40080
	ds_read_b128 v[176:179], v147 offset:49152
	ds_read_b128 v[180:183], v147 offset:50176
	ds_read_b128 v[184:187], v147 offset:51200
	ds_read_b128 v[188:191], v147 offset:52224
	ds_read_b128 v[204:207], v147 offset:53248
	ds_read_b128 v[208:211], v147 offset:54272
	ds_read_b128 v[218:221], v147 offset:55296
	ds_read_b128 v[222:225], v147 offset:56320
	global_load_lds_dwordx4 v[142:143], off
	v_lshl_add_u64 v[142:143], v[226:227], 0, s[76:77]
	s_mov_b32 m0, s64
	s_addc_u32 s31, s31, 0
	global_load_lds_dwordx4 v[142:143], off
	v_lshl_add_u64 v[142:143], s[30:31], 0, v[192:193]
	s_mov_b32 m0, s70
	s_nop 0
	global_load_lds_dwordx4 v[142:143], off
	v_lshl_add_u64 v[142:143], s[30:31], 0, v[132:133]
	s_mov_b32 m0, s71
	s_nop 0
	global_load_lds_dwordx4 v[142:143], off
	v_lshl_add_u64 v[142:143], v[228:229], 0, s[76:77]
	s_mov_b32 m0, s65
	s_nop 0
	global_load_lds_dwordx4 v[142:143], off
	v_lshl_add_u64 v[142:143], v[230:231], 0, s[76:77]
	s_mov_b32 m0, s66
	s_nop 0
	global_load_lds_dwordx4 v[142:143], off
	s_waitcnt vmcnt(8)
	s_waitcnt lgkmcnt(0)
	s_barrier
	s_setprio 1
	s_waitcnt lgkmcnt(0)
	v_mfma_f32_16x16x32_bf16 v[60:63], v[138:141], v[176:179], v[60:63]
	v_mfma_f32_16x16x32_bf16 v[56:59], v[152:155], v[176:179], v[56:59]
	v_mfma_f32_16x16x32_bf16 v[44:47], v[138:141], v[184:187], v[44:47]
	v_mfma_f32_16x16x32_bf16 v[40:43], v[152:155], v[184:187], v[40:43]
	v_mfma_f32_16x16x32_bf16 v[28:31], v[138:141], v[204:207], v[28:31]
	v_mfma_f32_16x16x32_bf16 v[24:27], v[152:155], v[204:207], v[24:27]
	v_mfma_f32_16x16x32_bf16 v[12:15], v[138:141], v[218:221], v[12:15]
	v_mfma_f32_16x16x32_bf16 v[8:11], v[152:155], v[218:221], v[8:11]
	v_mfma_f32_16x16x32_bf16 v[60:63], v[148:151], v[180:183], v[60:63]
	v_mfma_f32_16x16x32_bf16 v[56:59], v[156:159], v[180:183], v[56:59]
	v_mfma_f32_16x16x32_bf16 v[44:47], v[148:151], v[188:191], v[44:47]
	v_mfma_f32_16x16x32_bf16 v[40:43], v[156:159], v[188:191], v[40:43]
	v_mfma_f32_16x16x32_bf16 v[28:31], v[148:151], v[208:211], v[28:31]
	v_mfma_f32_16x16x32_bf16 v[24:27], v[156:159], v[208:211], v[24:27]
	v_mfma_f32_16x16x32_bf16 v[12:15], v[148:151], v[222:225], v[12:15]
	v_mfma_f32_16x16x32_bf16 v[8:11], v[156:159], v[222:225], v[8:11]
	s_setprio 0
	s_setprio 1
	v_mfma_f32_16x16x32_bf16 v[52:55], v[160:163], v[176:179], v[52:55]
	v_mfma_f32_16x16x32_bf16 v[48:51], v[168:171], v[176:179], v[48:51]
	v_mfma_f32_16x16x32_bf16 v[36:39], v[160:163], v[184:187], v[36:39]
	v_mfma_f32_16x16x32_bf16 v[32:35], v[168:171], v[184:187], v[32:35]
	v_mfma_f32_16x16x32_bf16 v[20:23], v[160:163], v[204:207], v[20:23]
	v_mfma_f32_16x16x32_bf16 v[16:19], v[168:171], v[204:207], v[16:19]
	v_mfma_f32_16x16x32_bf16 v[4:7], v[160:163], v[218:221], v[4:7]
	v_mfma_f32_16x16x32_bf16 v[0:3], v[168:171], v[218:221], v[0:3]
	v_mfma_f32_16x16x32_bf16 v[52:55], v[164:167], v[180:183], v[52:55]
	v_mfma_f32_16x16x32_bf16 v[48:51], v[172:175], v[180:183], v[48:51]
	v_mfma_f32_16x16x32_bf16 v[36:39], v[164:167], v[188:191], v[36:39]
	v_mfma_f32_16x16x32_bf16 v[32:35], v[172:175], v[188:191], v[32:35]
	v_mfma_f32_16x16x32_bf16 v[20:23], v[164:167], v[208:211], v[20:23]
	v_mfma_f32_16x16x32_bf16 v[16:19], v[172:175], v[208:211], v[16:19]
	v_mfma_f32_16x16x32_bf16 v[4:7], v[164:167], v[222:225], v[4:7]
	v_mfma_f32_16x16x32_bf16 v[0:3], v[172:175], v[222:225], v[0:3]
	s_setprio 0
	s_barrier
	s_add_i32 s82, s82, 2
	s_add_u32 s78, s78, 0x100
	s_addc_u32 s79, s79, 0
	s_add_u32 s28, s28, 0x100
	s_addc_u32 s29, s29, 0
	s_cmp_gt_u32 s82, 13
	s_cbranch_scc0 .LBB0_885
	v_lshl_add_u32 v159, s26, 8, v144
	v_lshl_or_b32 v158, s8, 8, v146
	v_lshlrev_b32_e32 v159, 11, v159
	v_lshl_add_u32 v159, v158, 1, v159
	v_add_u32_e32 v218, 0x8000, v159
	v_add_u32_e32 v219, 0x10000, v159
	v_add_u32_e32 v240, 0x18000, v159
	v_add_u32_e32 v241, 0x40000, v159
	v_add_u32_e32 v245, 0x48000, v159
	v_add_u32_e32 v246, 0x50000, v159
	v_add_u32_e32 v247, 0x58000, v159
	global_load_dwordx4 v[160:163], v159, s[12:13]
	global_load_dwordx4 v[164:167], v159, s[12:13] offset:256
	global_load_dwordx4 v[168:171], v218, s[12:13]
	global_load_dwordx4 v[172:175], v218, s[12:13] offset:256
	global_load_dwordx4 v[176:179], v219, s[12:13]
	global_load_dwordx4 v[180:183], v219, s[12:13] offset:256
	global_load_dwordx4 v[184:187], v240, s[12:13]
	global_load_dwordx4 v[188:191], v240, s[12:13] offset:256
	global_load_dwordx4 v[204:207], v241, s[12:13]
	global_load_dwordx4 v[208:211], v241, s[12:13] offset:256
	global_load_dwordx4 v[220:223], v245, s[12:13]
	global_load_dwordx4 v[224:227], v245, s[12:13] offset:256
	global_load_dwordx4 v[228:231], v246, s[12:13]
	global_load_dwordx4 v[232:235], v246, s[12:13] offset:256
	global_load_dwordx4 v[236:239], v247, s[12:13]
	global_load_dwordx4 v[248:251], v247, s[12:13] offset:256
	s_and_b64 vcc, exec, s[16:17]
	s_cbranch_vccz .LBB0_888
	s_barrier

; #define PG8_STAGE(bufoff, gbase, voff) do { _Pragma("unroll") for (int _i = 0; _i < 2; ++_i) \
;         __builtin_amdgcn_global_load_lds((const unsigned*)((const char*)(gbase) + (voff)[_i]), (PG8_LAS unsigned*)(lds + (bufoff) + ldsw + _i * 8192), 16, 0, 0); } while (0)
; #define PG8_LDA(dst, b, h) do { _Pragma("unroll") for (int m = 0; m < 4; ++m) _Pragma("unroll") for (int k = 0; k < 2; ++k) dst[m][k] = *(const PG8_LAS bf16x8*)(lds + PG8_SA(b, h) + aoff + m * 2048 + k * 1024); } while (0)
; #define PG8_LDB(dst, b, h) do { _Pragma("unroll") for (int n = 0; n < 2; ++n) _Pragma("unroll") for (int k = 0; k < 2; ++k) dst[n][k] = *(const PG8_LAS bf16x8*)(lds + PG8_SB(b, h) + boff + n * 2048 + k * 1024); } while (0)
; #define PG8_MMA(ai, bj, At, Bt) do { __builtin_amdgcn_s_setprio(1); _Pragma("unroll") for (int m = 0; m < 4; ++m) _Pragma("unroll") for (int n = 0; n < 2; ++n) _Pragma("unroll") for (int k = 0; k < 2; ++k) \
;         acc[ai][bj][m][n] = __builtin_amdgcn_mfma_f32_16x16x32_bf16(Bt[n][k], At[m][k], acc[ai][bj][m][n], 0, 0, 0); __builtin_amdgcn_s_setprio(0); } while (0)
; #define PG8_WAIT_V(n) asm volatile("s_waitcnt vmcnt(" #n ")" ::: "memory")
; #define PG8_BAR __builtin_amdgcn_s_barrier()
; template <class Epi, class Sched, bool ALIGN_EPI = false, bool SP2 = false>
; __device__ __forceinline__ void gemm_phase(PG8_LAS unsigned char* lds, const Gemm g, const Sched& S, const Epi& E) {
;     ...
;         for (int t = 0; t < nt; t += 2) {
;             const bool last = (t == nt - 2);
;             const char* a1 = cA + (size_t)(t + 1) * kstep;
;             const char* a2 = last ? nA : cA + (size_t)(t + 2) * kstep; const char* b2 = last ? nB : cB + (size_t)(t + 2) * kstep;
;             const char* a3 = a2 + kstep; const char* b3 = b2 + kstep;
;             if (last && has_next) S.a_ready(nxt);
;             if constexpr (SP2) {
;             PG8_LDB(B0, 0, 0); PG8_LDB(B1, 0, 1); PG8_SCHED; PG8_LDA(At, 0, 0); PG8_STAGE(PG8_SA(1, 1), a1 + hstepA, voffA);
;             PG8_WAIT_V(8); PG8_WAIT_L(0); PG8_BAR; PG8_MMA(0, 0, At, B0); PG8_MMA(0, 1, At, B1); PG8_BAR; PG8_SCHED;
;             PG8_LDA(At, 0, 1); PG8_STAGE(PG8_SB(0, 0), b2, voffB); PG8_STAGE(PG8_SB(0, 1), b2 + hstepB, voffB); PG8_STAGE(PG8_SA(0, 0), a2, voffA);
;             PG8_WAIT_V(8); PG8_WAIT_L(0); PG8_BAR; PG8_MMA(1, 0, At, B0); PG8_MMA(1, 1, At, B1); PG8_BAR; PG8_SCHED;
.LBB0_995:
	v_add_u32_e32 v154, s38, v175
	v_add_u32_e32 v170, s41, v175
	ds_read_b128 v[142:145], v154
	ds_read_b128 v[146:149], v154 offset:1024
	ds_read_b128 v[150:153], v154 offset:2048
	ds_read_b128 v[154:157], v154 offset:3072
	ds_read_b128 v[158:161], v170
	ds_read_b128 v[162:165], v170 offset:1024
	ds_read_b128 v[166:169], v170 offset:2048
	ds_read_b128 v[170:173], v170 offset:3072
	s_add_u32 s2, s26, 0xfffc0080
	s_addc_u32 s28, s27, -1
	s_cmp_eq_u32 s82, 12
	s_cselect_b32 s31, s17, s28
	s_cselect_b32 s30, s23, s2
	s_cselect_b32 s29, s15, s79
	s_cselect_b32 s28, s25, s78
	v_lshl_add_u64 v[246:247], s[26:27], 0, v[140:141]
	s_add_i32 m0, s44, 0xc000
	ds_read_b128 v[208:211], v207
	ds_read_b128 v[218:221], v207 offset:1024
	ds_read_b128 v[222:225], v207 offset:2048
	ds_read_b128 v[226:229], v207 offset:3072
	ds_read_b128 v[230:233], v207 offset:4096
	ds_read_b128 v[234:237], v207 offset:5120
	ds_read_b128 v[238:241], v207 offset:6144
	ds_read_b128 v[242:245], v207 offset:7168
	global_load_lds_dwordx4 v[246:247], off
	v_lshl_add_u64 v[246:247], s[26:27], 0, v[138:139]
	s_add_i32 m0, s44, 0xe000
	s_nop 0
	global_load_lds_dwordx4 v[246:247], off
	s_waitcnt vmcnt(8)
	s_waitcnt lgkmcnt(0)
	s_barrier
	s_setprio 1
	s_waitcnt lgkmcnt(0)
	v_mfma_f32_16x16x32_bf16 v[124:127], v[142:145], v[208:211], v[124:127]
	v_mfma_f32_16x16x32_bf16 v[120:123], v[150:153], v[208:211], v[120:123]
	v_mfma_f32_16x16x32_bf16 v[108:111], v[142:145], v[222:225], v[108:111]
	v_mfma_f32_16x16x32_bf16 v[104:107], v[150:153], v[222:225], v[104:107]
	v_mfma_f32_16x16x32_bf16 v[92:95], v[142:145], v[230:233], v[92:95]
	v_mfma_f32_16x16x32_bf16 v[88:91], v[150:153], v[230:233], v[88:91]
	v_mfma_f32_16x16x32_bf16 v[76:79], v[142:145], v[238:241], v[76:79]
	v_mfma_f32_16x16x32_bf16 v[72:75], v[150:153], v[238:241], v[72:75]
	v_mfma_f32_16x16x32_bf16 v[124:127], v[146:149], v[218:221], v[124:127]
	v_mfma_f32_16x16x32_bf16 v[120:123], v[154:157], v[218:221], v[120:123]
	v_mfma_f32_16x16x32_bf16 v[108:111], v[146:149], v[226:229], v[108:111]
	v_mfma_f32_16x16x32_bf16 v[104:107], v[154:157], v[226:229], v[104:107]
	v_mfma_f32_16x16x32_bf16 v[92:95], v[146:149], v[234:237], v[92:95]
	v_mfma_f32_16x16x32_bf16 v[88:91], v[154:157], v[234:237], v[88:91]
	v_mfma_f32_16x16x32_bf16 v[76:79], v[146:149], v[242:245], v[76:79]
	v_mfma_f32_16x16x32_bf16 v[72:75], v[154:157], v[242:245], v[72:75]
	s_setprio 0
	s_setprio 1
	v_mfma_f32_16x16x32_bf16 v[116:119], v[158:161], v[208:211], v[116:119]
	v_mfma_f32_16x16x32_bf16 v[112:115], v[166:169], v[208:211], v[112:115]
	v_mfma_f32_16x16x32_bf16 v[100:103], v[158:161], v[222:225], v[100:103]
	v_mfma_f32_16x16x32_bf16 v[96:99], v[166:169], v[222:225], v[96:99]
	v_mfma_f32_16x16x32_bf16 v[84:87], v[158:161], v[230:233], v[84:87]
	v_mfma_f32_16x16x32_bf16 v[80:83], v[166:169], v[230:233], v[80:83]
	v_mfma_f32_16x16x32_bf16 v[68:71], v[158:161], v[238:241], v[68:71]
	v_mfma_f32_16x16x32_bf16 v[64:67], v[166:169], v[238:241], v[64:67]
	v_mfma_f32_16x16x32_bf16 v[116:119], v[162:165], v[218:221], v[116:119]
	v_mfma_f32_16x16x32_bf16 v[112:115], v[170:173], v[218:221], v[112:115]
	v_mfma_f32_16x16x32_bf16 v[100:103], v[162:165], v[226:229], v[100:103]
	v_mfma_f32_16x16x32_bf16 v[96:99], v[170:173], v[226:229], v[96:99]
	v_mfma_f32_16x16x32_bf16 v[84:87], v[162:165], v[234:237], v[84:87]
	v_mfma_f32_16x16x32_bf16 v[80:83], v[170:173], v[234:237], v[80:83]
	v_mfma_f32_16x16x32_bf16 v[68:71], v[162:165], v[242:245], v[68:71]
	v_mfma_f32_16x16x32_bf16 v[64:67], v[170:173], v[242:245], v[64:67]
	s_setprio 0
	s_barrier
	s_mov_b32 m0, s39
	v_lshl_add_u64 v[246:247], s[28:29], 0, v[130:131]
	s_add_u32 s84, s28, 0x40000
	ds_read_b128 v[208:211], v207 offset:16384
	ds_read_b128 v[218:221], v207 offset:17408
	ds_read_b128 v[222:225], v207 offset:18432
	ds_read_b128 v[226:229], v207 offset:19456
	ds_read_b128 v[230:233], v207 offset:20480
	ds_read_b128 v[234:237], v207 offset:21504
	ds_read_b128 v[238:241], v207 offset:22528
	ds_read_b128 v[242:245], v207 offset:23552
	global_load_lds_dwordx4 v[246:247], off
	v_lshl_add_u64 v[248:249], s[28:29], 0, v[134:135]
	s_mov_b32 m0, s40
	s_addc_u32 s85, s29, 0
	global_load_lds_dwordx4 v[248:249], off
	v_lshl_add_u64 v[250:251], s[84:85], 0, v[130:131]
	s_mov_b32 m0, s42
	v_lshl_add_u64 v[252:253], s[30:31], 0, v[132:133]
	global_load_lds_dwordx4 v[250:251], off
	v_lshl_add_u64 v[250:251], s[84:85], 0, v[134:135]
	s_mov_b32 m0, s43
	s_nop 0
	global_load_lds_dwordx4 v[250:251], off
	v_lshl_add_u64 v[250:251], s[30:31], 0, v[128:129]
	s_mov_b32 m0, s44
	s_nop 0
	global_load_lds_dwordx4 v[250:251], off
	s_mov_b32 m0, s45
	s_nop 0
	global_load_lds_dwordx4 v[252:253], off
	s_waitcnt vmcnt(8)
	s_waitcnt lgkmcnt(0)
	s_barrier
; #define PG8_STAGE(bufoff, gbase, voff) do { _Pragma("unroll") for (int _i = 0; _i < 2; ++_i) \
;         __builtin_amdgcn_global_load_lds((const unsigned*)((const char*)(gbase) + (voff)[_i]), (PG8_LAS unsigned*)(lds + (bufoff) + ldsw + _i * 8192), 16, 0, 0); } while (0)
; #define PG8_LDA(dst, b, h) do { _Pragma("unroll") for (int m = 0; m < 4; ++m) _Pragma("unroll") for (int k = 0; k < 2; ++k) dst[m][k] = *(const PG8_LAS bf16x8*)(lds + PG8_SA(b, h) + aoff + m * 2048 + k * 1024); } while (0)
; #define PG8_LDB(dst, b, h) do { _Pragma("unroll") for (int n = 0; n < 2; ++n) _Pragma("unroll") for (int k = 0; k < 2; ++k) dst[n][k] = *(const PG8_LAS bf16x8*)(lds + PG8_SB(b, h) + boff + n * 2048 + k * 1024); } while (0)
; #define PG8_MMA(ai, bj, At, Bt) do { __builtin_amdgcn_s_setprio(1); _Pragma("unroll") for (int m = 0; m < 4; ++m) _Pragma("unroll") for (int n = 0; n < 2; ++n) _Pragma("unroll") for (int k = 0; k < 2; ++k) \
;         acc[ai][bj][m][n] = __builtin_amdgcn_mfma_f32_16x16x32_bf16(Bt[n][k], At[m][k], acc[ai][bj][m][n], 0, 0, 0); __builtin_amdgcn_s_setprio(0); } while (0)
; #define PG8_WAIT_V(n) asm volatile("s_waitcnt vmcnt(" #n ")" ::: "memory")
; #define PG8_WAIT_L(n) asm volatile("s_waitcnt lgkmcnt(" #n ")" ::: "memory")
; #define PG8_BAR __builtin_amdgcn_s_barrier()
; #define PG8_SCHED __builtin_amdgcn_sched_barrier(0)
; template <class Epi, class Sched, bool ALIGN_EPI = false, bool SP2 = false>
; __device__ __forceinline__ void gemm_phase(PG8_LAS unsigned char* lds, const Gemm g, const Sched& S, const Epi& E) {
;     ...
;             if constexpr (SP2) {
;             PG8_LDB(B0, 0, 0); PG8_LDB(B1, 0, 1); PG8_SCHED; PG8_LDA(At, 0, 0); PG8_STAGE(PG8_SA(1, 1), a1 + hstepA, voffA);
;             PG8_WAIT_V(8); PG8_WAIT_L(0); PG8_BAR; PG8_MMA(0, 0, At, B0); PG8_MMA(0, 1, At, B1); PG8_BAR; PG8_SCHED;
;             PG8_LDA(At, 0, 1); PG8_STAGE(PG8_SB(0, 0), b2, voffB); PG8_STAGE(PG8_SB(0, 1), b2 + hstepB, voffB); PG8_STAGE(PG8_SA(0, 0), a2, voffA);
;             PG8_WAIT_V(8); PG8_WAIT_L(0); PG8_BAR; PG8_MMA(1, 0, At, B0); PG8_MMA(1, 1, At, B1); PG8_BAR; PG8_SCHED;
;             PG8_LDB(B0, 1, 0); PG8_LDB(B1, 1, 1); PG8_SCHED; PG8_LDA(At, 1, 0); PG8_STAGE(PG8_SA(0, 1), a2 + hstepA, voffA);
;             PG8_WAIT_V(8); PG8_WAIT_L(0); PG8_BAR; PG8_MMA(0, 0, At, B0); PG8_MMA(0, 1, At, B1); PG8_BAR; PG8_SCHED;
	s_setprio 1
	s_waitcnt lgkmcnt(0)
	s_nop 0
	v_mfma_f32_16x16x32_bf16 v[60:63], v[142:145], v[208:211], v[60:63]
	v_mfma_f32_16x16x32_bf16 v[56:59], v[150:153], v[208:211], v[56:59]
	v_mfma_f32_16x16x32_bf16 v[44:47], v[142:145], v[222:225], v[44:47]
	v_mfma_f32_16x16x32_bf16 v[40:43], v[150:153], v[222:225], v[40:43]
	v_mfma_f32_16x16x32_bf16 v[28:31], v[142:145], v[230:233], v[28:31]
	v_mfma_f32_16x16x32_bf16 v[24:27], v[150:153], v[230:233], v[24:27]
	v_mfma_f32_16x16x32_bf16 v[12:15], v[142:145], v[238:241], v[12:15]
	v_mfma_f32_16x16x32_bf16 v[8:11], v[150:153], v[238:241], v[8:11]
	v_mfma_f32_16x16x32_bf16 v[60:63], v[146:149], v[218:221], v[60:63]
	v_mfma_f32_16x16x32_bf16 v[56:59], v[154:157], v[218:221], v[56:59]
	v_mfma_f32_16x16x32_bf16 v[44:47], v[146:149], v[226:229], v[44:47]
	v_mfma_f32_16x16x32_bf16 v[40:43], v[154:157], v[226:229], v[40:43]
	v_mfma_f32_16x16x32_bf16 v[28:31], v[146:149], v[234:237], v[28:31]
	v_mfma_f32_16x16x32_bf16 v[24:27], v[154:157], v[234:237], v[24:27]
	v_mfma_f32_16x16x32_bf16 v[12:15], v[146:149], v[242:245], v[12:15]
	v_mfma_f32_16x16x32_bf16 v[8:11], v[154:157], v[242:245], v[8:11]
	s_setprio 0
	s_setprio 1
	v_mfma_f32_16x16x32_bf16 v[52:55], v[158:161], v[208:211], v[52:55]
	v_mfma_f32_16x16x32_bf16 v[48:51], v[166:169], v[208:211], v[48:51]
	v_mfma_f32_16x16x32_bf16 v[36:39], v[158:161], v[222:225], v[36:39]
	v_mfma_f32_16x16x32_bf16 v[32:35], v[166:169], v[222:225], v[32:35]
	v_mfma_f32_16x16x32_bf16 v[20:23], v[158:161], v[230:233], v[20:23]
	v_mfma_f32_16x16x32_bf16 v[16:19], v[166:169], v[230:233], v[16:19]
	v_mfma_f32_16x16x32_bf16 v[4:7], v[158:161], v[238:241], v[4:7]
	v_mfma_f32_16x16x32_bf16 v[0:3], v[166:169], v[238:241], v[0:3]
	v_mfma_f32_16x16x32_bf16 v[52:55], v[162:165], v[218:221], v[52:55]
	v_mfma_f32_16x16x32_bf16 v[48:51], v[170:173], v[218:221], v[48:51]
	v_mfma_f32_16x16x32_bf16 v[36:39], v[162:165], v[226:229], v[36:39]
	v_mfma_f32_16x16x32_bf16 v[32:35], v[170:173], v[226:229], v[32:35]
	v_mfma_f32_16x16x32_bf16 v[20:23], v[162:165], v[234:237], v[20:23]
	v_mfma_f32_16x16x32_bf16 v[16:19], v[170:173], v[234:237], v[16:19]
	v_mfma_f32_16x16x32_bf16 v[4:7], v[162:165], v[242:245], v[4:7]
	v_mfma_f32_16x16x32_bf16 v[0:3], v[170:173], v[242:245], v[0:3]
	s_setprio 0
	s_barrier
	v_add_u32_e32 v154, s50, v175
	v_add_u32_e32 v170, s65, v175
	ds_read_b128 v[142:145], v154
	ds_read_b128 v[146:149], v154 offset:1024
	ds_read_b128 v[150:153], v154 offset:2048
	ds_read_b128 v[154:157], v154 offset:3072
	ds_read_b128 v[158:161], v170
	ds_read_b128 v[162:165], v170 offset:1024
	ds_read_b128 v[166:169], v170 offset:2048
	ds_read_b128 v[170:173], v170 offset:3072
	s_add_u32 s30, s30, 0x40000
	s_addc_u32 s31, s31, 0
	s_mov_b32 m0, s48
	v_lshl_add_u64 v[194:195], s[30:31], 0, v[128:129]
	ds_read_b128 v[208:211], v207 offset:32768
	ds_read_b128 v[218:221], v207 offset:33792
	ds_read_b128 v[222:225], v207 offset:34816
	ds_read_b128 v[226:229], v207 offset:35840
	ds_read_b128 v[230:233], v207 offset:36864
	ds_read_b128 v[234:237], v207 offset:37888
	ds_read_b128 v[238:241], v207 offset:38912
	ds_read_b128 v[242:245], v207 offset:39936
	global_load_lds_dwordx4 v[194:195], off
	v_lshl_add_u64 v[194:195], s[30:31], 0, v[132:133]
	s_mov_b32 m0, s49
	s_nop 0
	global_load_lds_dwordx4 v[194:195], off
	s_waitcnt vmcnt(8)
	s_waitcnt lgkmcnt(0)
	s_barrier
	s_setprio 1
	s_waitcnt lgkmcnt(0)
	s_nop 0
	v_mfma_f32_16x16x32_bf16 v[124:127], v[142:145], v[208:211], v[124:127]
	v_mfma_f32_16x16x32_bf16 v[120:123], v[150:153], v[208:211], v[120:123]
	v_mfma_f32_16x16x32_bf16 v[108:111], v[142:145], v[222:225], v[108:111]
	v_mfma_f32_16x16x32_bf16 v[104:107], v[150:153], v[222:225], v[104:107]
	v_mfma_f32_16x16x32_bf16 v[92:95], v[142:145], v[230:233], v[92:95]
	v_mfma_f32_16x16x32_bf16 v[88:91], v[150:153], v[230:233], v[88:91]
	v_mfma_f32_16x16x32_bf16 v[76:79], v[142:145], v[238:241], v[76:79]
	v_mfma_f32_16x16x32_bf16 v[72:75], v[150:153], v[238:241], v[72:75]
	v_mfma_f32_16x16x32_bf16 v[124:127], v[146:149], v[218:221], v[124:127]
	v_mfma_f32_16x16x32_bf16 v[120:123], v[154:157], v[218:221], v[120:123]
	v_mfma_f32_16x16x32_bf16 v[108:111], v[146:149], v[226:229], v[108:111]
	v_mfma_f32_16x16x32_bf16 v[104:107], v[154:157], v[226:229], v[104:107]
	v_mfma_f32_16x16x32_bf16 v[92:95], v[146:149], v[234:237], v[92:95]
	v_mfma_f32_16x16x32_bf16 v[88:91], v[154:157], v[234:237], v[88:91]
	v_mfma_f32_16x16x32_bf16 v[76:79], v[146:149], v[242:245], v[76:79]
	v_mfma_f32_16x16x32_bf16 v[72:75], v[154:157], v[242:245], v[72:75]
	s_setprio 0
	s_setprio 1
	v_mfma_f32_16x16x32_bf16 v[116:119], v[158:161], v[208:211], v[116:119]
	v_mfma_f32_16x16x32_bf16 v[112:115], v[166:169], v[208:211], v[112:115]
	v_mfma_f32_16x16x32_bf16 v[100:103], v[158:161], v[222:225], v[100:103]
	v_mfma_f32_16x16x32_bf16 v[96:99], v[166:169], v[222:225], v[96:99]
	v_mfma_f32_16x16x32_bf16 v[84:87], v[158:161], v[230:233], v[84:87]
	v_mfma_f32_16x16x32_bf16 v[80:83], v[166:169], v[230:233], v[80:83]
	v_mfma_f32_16x16x32_bf16 v[68:71], v[158:161], v[238:241], v[68:71]
	v_mfma_f32_16x16x32_bf16 v[64:67], v[166:169], v[238:241], v[64:67]
	v_mfma_f32_16x16x32_bf16 v[116:119], v[162:165], v[218:221], v[116:119]
	v_mfma_f32_16x16x32_bf16 v[112:115], v[170:173], v[218:221], v[112:115]
	v_mfma_f32_16x16x32_bf16 v[100:103], v[162:165], v[226:229], v[100:103]
	v_mfma_f32_16x16x32_bf16 v[96:99], v[170:173], v[226:229], v[96:99]
	v_mfma_f32_16x16x32_bf16 v[84:87], v[162:165], v[234:237], v[84:87]
	v_mfma_f32_16x16x32_bf16 v[80:83], v[170:173], v[234:237], v[80:83]
	v_mfma_f32_16x16x32_bf16 v[68:71], v[162:165], v[242:245], v[68:71]
	v_mfma_f32_16x16x32_bf16 v[64:67], v[170:173], v[242:245], v[64:67]
	s_setprio 0
	s_barrier
; #define PG8_STAGE(bufoff, gbase, voff) do { _Pragma("unroll") for (int _i = 0; _i < 2; ++_i) \
;         __builtin_amdgcn_global_load_lds((const unsigned*)((const char*)(gbase) + (voff)[_i]), (PG8_LAS unsigned*)(lds + (bufoff) + ldsw + _i * 8192), 16, 0, 0); } while (0)
; #define PG8_LDA(dst, b, h) do { _Pragma("unroll") for (int m = 0; m < 4; ++m) _Pragma("unroll") for (int k = 0; k < 2; ++k) dst[m][k] = *(const PG8_LAS bf16x8*)(lds + PG8_SA(b, h) + aoff + m * 2048 + k * 1024); } while (0)
; #define PG8_LDB(dst, b, h) do { _Pragma("unroll") for (int n = 0; n < 2; ++n) _Pragma("unroll") for (int k = 0; k < 2; ++k) dst[n][k] = *(const PG8_LAS bf16x8*)(lds + PG8_SB(b, h) + boff + n * 2048 + k * 1024); } while (0)
; #define PG8_MMA(ai, bj, At, Bt) do { __builtin_amdgcn_s_setprio(1); _Pragma("unroll") for (int m = 0; m < 4; ++m) _Pragma("unroll") for (int n = 0; n < 2; ++n) _Pragma("unroll") for (int k = 0; k < 2; ++k) \
;         acc[ai][bj][m][n] = __builtin_amdgcn_mfma_f32_16x16x32_bf16(Bt[n][k], At[m][k], acc[ai][bj][m][n], 0, 0, 0); __builtin_amdgcn_s_setprio(0); } while (0)
; template <class Epi, class Sched, bool ALIGN_EPI = false, bool SP2 = false>
; __device__ __forceinline__ void gemm_phase(PG8_LAS unsigned char* lds, const Gemm g, const Sched& S, const Epi& E) {
;     ...
;             if constexpr (SP2) {
;             PG8_LDB(B0, 0, 0); PG8_LDB(B1, 0, 1); PG8_SCHED; PG8_LDA(At, 0, 0); PG8_STAGE(PG8_SA(1, 1), a1 + hstepA, voffA);
;             PG8_WAIT_V(8); PG8_WAIT_L(0); PG8_BAR; PG8_MMA(0, 0, At, B0); PG8_MMA(0, 1, At, B1); PG8_BAR; PG8_SCHED;
;             PG8_LDA(At, 0, 1); PG8_STAGE(PG8_SB(0, 0), b2, voffB); PG8_STAGE(PG8_SB(0, 1), b2 + hstepB, voffB); PG8_STAGE(PG8_SA(0, 0), a2, voffA);
;             PG8_WAIT_V(8); PG8_WAIT_L(0); PG8_BAR; PG8_MMA(1, 0, At, B0); PG8_MMA(1, 1, At, B1); PG8_BAR; PG8_SCHED;
;             PG8_LDB(B0, 1, 0); PG8_LDB(B1, 1, 1); PG8_SCHED; PG8_LDA(At, 1, 0); PG8_STAGE(PG8_SA(0, 1), a2 + hstepA, voffA);
;             PG8_WAIT_V(8); PG8_WAIT_L(0); PG8_BAR; PG8_MMA(0, 0, At, B0); PG8_MMA(0, 1, At, B1); PG8_BAR; PG8_SCHED;
;             PG8_LDA(At, 1, 1); PG8_STAGE(PG8_SB(1, 0), b3, voffB); PG8_STAGE(PG8_SB(1, 1), b3 + hstepB, voffB); PG8_STAGE(PG8_SA(1, 0), a3, voffA);
;             PG8_WAIT_V(8); PG8_WAIT_L(0); PG8_BAR; PG8_MMA(1, 0, At, B0); PG8_MMA(1, 1, At, B1); PG8_BAR; PG8_SCHED;
	s_mov_b32 m0, s51
	v_lshl_add_u64 v[194:195], v[246:247], 0, s[76:77]
	s_add_u32 s28, s28, 0x40080
	ds_read_b128 v[208:211], v207 offset:49152
	ds_read_b128 v[218:221], v207 offset:50176
	ds_read_b128 v[222:225], v207 offset:51200
	ds_read_b128 v[226:229], v207 offset:52224
	ds_read_b128 v[230:233], v207 offset:53248
	ds_read_b128 v[234:237], v207 offset:54272
	ds_read_b128 v[238:241], v207 offset:55296
	ds_read_b128 v[242:245], v207 offset:56320
	global_load_lds_dwordx4 v[194:195], off
	v_lshl_add_u64 v[194:195], v[248:249], 0, s[76:77]
	s_mov_b32 m0, s60
	s_addc_u32 s29, s29, 0
	global_load_lds_dwordx4 v[194:195], off
	v_lshl_add_u64 v[194:195], s[28:29], 0, v[130:131]
	s_mov_b32 m0, s66
	s_nop 0
	global_load_lds_dwordx4 v[194:195], off
	v_lshl_add_u64 v[194:195], s[28:29], 0, v[134:135]
	s_mov_b32 m0, s67
	s_nop 0
	global_load_lds_dwordx4 v[194:195], off
	v_lshl_add_u64 v[194:195], v[250:251], 0, s[76:77]
	s_mov_b32 m0, s61
	s_nop 0
	global_load_lds_dwordx4 v[194:195], off
	v_lshl_add_u64 v[194:195], v[252:253], 0, s[76:77]
	s_mov_b32 m0, s64
	s_nop 0
	global_load_lds_dwordx4 v[194:195], off
	s_waitcnt vmcnt(8)
	s_waitcnt lgkmcnt(0)
	s_barrier
	s_setprio 1
	s_waitcnt lgkmcnt(0)
	v_mfma_f32_16x16x32_bf16 v[60:63], v[142:145], v[208:211], v[60:63]
	v_mfma_f32_16x16x32_bf16 v[56:59], v[150:153], v[208:211], v[56:59]
	v_mfma_f32_16x16x32_bf16 v[44:47], v[142:145], v[222:225], v[44:47]
	v_mfma_f32_16x16x32_bf16 v[40:43], v[150:153], v[222:225], v[40:43]
	v_mfma_f32_16x16x32_bf16 v[28:31], v[142:145], v[230:233], v[28:31]
	v_mfma_f32_16x16x32_bf16 v[24:27], v[150:153], v[230:233], v[24:27]
	v_mfma_f32_16x16x32_bf16 v[12:15], v[142:145], v[238:241], v[12:15]
	v_mfma_f32_16x16x32_bf16 v[8:11], v[150:153], v[238:241], v[8:11]
	v_mfma_f32_16x16x32_bf16 v[60:63], v[146:149], v[218:221], v[60:63]
	v_mfma_f32_16x16x32_bf16 v[56:59], v[154:157], v[218:221], v[56:59]
	v_mfma_f32_16x16x32_bf16 v[44:47], v[146:149], v[226:229], v[44:47]
	v_mfma_f32_16x16x32_bf16 v[40:43], v[154:157], v[226:229], v[40:43]
	v_mfma_f32_16x16x32_bf16 v[28:31], v[146:149], v[234:237], v[28:31]
	v_mfma_f32_16x16x32_bf16 v[24:27], v[154:157], v[234:237], v[24:27]
	v_mfma_f32_16x16x32_bf16 v[12:15], v[146:149], v[242:245], v[12:15]
	v_mfma_f32_16x16x32_bf16 v[8:11], v[154:157], v[242:245], v[8:11]
	s_setprio 0
	s_setprio 1
	v_mfma_f32_16x16x32_bf16 v[52:55], v[158:161], v[208:211], v[52:55]
	v_mfma_f32_16x16x32_bf16 v[48:51], v[166:169], v[208:211], v[48:51]
	v_mfma_f32_16x16x32_bf16 v[36:39], v[158:161], v[222:225], v[36:39]
	v_mfma_f32_16x16x32_bf16 v[32:35], v[166:169], v[222:225], v[32:35]
	v_mfma_f32_16x16x32_bf16 v[20:23], v[158:161], v[230:233], v[20:23]
	v_mfma_f32_16x16x32_bf16 v[16:19], v[166:169], v[230:233], v[16:19]
	v_mfma_f32_16x16x32_bf16 v[4:7], v[158:161], v[238:241], v[4:7]
	v_mfma_f32_16x16x32_bf16 v[0:3], v[166:169], v[238:241], v[0:3]
	v_mfma_f32_16x16x32_bf16 v[52:55], v[162:165], v[218:221], v[52:55]
	v_mfma_f32_16x16x32_bf16 v[48:51], v[170:173], v[218:221], v[48:51]
	v_mfma_f32_16x16x32_bf16 v[36:39], v[162:165], v[226:229], v[36:39]
	v_mfma_f32_16x16x32_bf16 v[32:35], v[170:173], v[226:229], v[32:35]
	v_mfma_f32_16x16x32_bf16 v[20:23], v[162:165], v[234:237], v[20:23]
	v_mfma_f32_16x16x32_bf16 v[16:19], v[170:173], v[234:237], v[16:19]
	v_mfma_f32_16x16x32_bf16 v[4:7], v[162:165], v[242:245], v[4:7]
	v_mfma_f32_16x16x32_bf16 v[0:3], v[170:173], v[242:245], v[0:3]
	s_setprio 0
	s_barrier
	s_add_i32 s82, s82, 2
	s_add_u32 s78, s78, 0x100
	s_addc_u32 s79, s79, 0
	s_add_u32 s26, s26, 0x100
	s_addc_u32 s27, s27, 0
	s_cmp_gt_u32 s82, 13
	s_cbranch_scc0 .LBB0_995
	s_and_b64 vcc, exec, s[12:13]
	s_cbranch_vccz .LBB0_998
	s_barrier

; #define PG8_STAGE(bufoff, gbase, voff) do { _Pragma("unroll") for (int _i = 0; _i < 2; ++_i) \
;         __builtin_amdgcn_global_load_lds((const unsigned*)((const char*)(gbase) + (voff)[_i]), (PG8_LAS unsigned*)(lds + (bufoff) + ldsw + _i * 8192), 16, 0, 0); } while (0)
; #define PG8_LDA(dst, b, h) do { _Pragma("unroll") for (int m = 0; m < 4; ++m) _Pragma("unroll") for (int k = 0; k < 2; ++k) dst[m][k] = *(const PG8_LAS bf16x8*)(lds + PG8_SA(b, h) + aoff + m * 2048 + k * 1024); } while (0)
; #define PG8_LDB(dst, b, h) do { _Pragma("unroll") for (int n = 0; n < 2; ++n) _Pragma("unroll") for (int k = 0; k < 2; ++k) dst[n][k] = *(const PG8_LAS bf16x8*)(lds + PG8_SB(b, h) + boff + n * 2048 + k * 1024); } while (0)
; #define PG8_MMA(ai, bj, At, Bt) do { __builtin_amdgcn_s_setprio(1); _Pragma("unroll") for (int m = 0; m < 4; ++m) _Pragma("unroll") for (int n = 0; n < 2; ++n) _Pragma("unroll") for (int k = 0; k < 2; ++k) \
;         acc[ai][bj][m][n] = __builtin_amdgcn_mfma_f32_16x16x32_bf16(Bt[n][k], At[m][k], acc[ai][bj][m][n], 0, 0, 0); __builtin_amdgcn_s_setprio(0); } while (0)
; #define PG8_WAIT_V(n) asm volatile("s_waitcnt vmcnt(" #n ")" ::: "memory")
; #define PG8_BAR __builtin_amdgcn_s_barrier()
; template <class Epi, class Sched, bool ALIGN_EPI = false, bool SP2 = false>
; __device__ __forceinline__ void gemm_phase(PG8_LAS unsigned char* lds, const Gemm g, const Sched& S, const Epi& E) {
;     ...
;         for (int t = 0; t < nt; t += 2) {
;             const bool last = (t == nt - 2);
;             const char* a1 = cA + (size_t)(t + 1) * kstep;
;             const char* a2 = last ? nA : cA + (size_t)(t + 2) * kstep; const char* b2 = last ? nB : cB + (size_t)(t + 2) * kstep;
;             const char* a3 = a2 + kstep; const char* b3 = b2 + kstep;
;             if (last && has_next) S.a_ready(nxt);
;             if constexpr (SP2) {
;             PG8_LDB(B0, 0, 0); PG8_LDB(B1, 0, 1); PG8_SCHED; PG8_LDA(At, 0, 0); PG8_STAGE(PG8_SA(1, 1), a1 + hstepA, voffA);
;             PG8_WAIT_V(8); PG8_WAIT_L(0); PG8_BAR; PG8_MMA(0, 0, At, B0); PG8_MMA(0, 1, At, B1); PG8_BAR; PG8_SCHED;
;             PG8_LDA(At, 0, 1); PG8_STAGE(PG8_SB(0, 0), b2, voffB); PG8_STAGE(PG8_SB(0, 1), b2 + hstepB, voffB); PG8_STAGE(PG8_SA(0, 0), a2, voffA);
;             PG8_WAIT_V(8); PG8_WAIT_L(0); PG8_BAR; PG8_MMA(1, 0, At, B0); PG8_MMA(1, 1, At, B1); PG8_BAR; PG8_SCHED;
.LBB0_1121:
	v_add_u32_e32 v142, s9, v145
	ds_read_b128 v[138:141], v142
	ds_read_b128 v[148:151], v142 offset:1024
	ds_read_b128 v[152:155], v142 offset:2048
	ds_read_b128 v[156:159], v142 offset:3072
	v_add_u32_e32 v142, s42, v145
	ds_read_b128 v[160:163], v142
	ds_read_b128 v[164:167], v142 offset:1024
	ds_read_b128 v[168:171], v142 offset:2048
	ds_read_b128 v[172:175], v142 offset:3072
	s_add_u32 s2, s28, 0xfffc0080
	s_addc_u32 s30, s29, -1
	s_cmp_eq_u32 s82, 12
	s_cselect_b32 s35, s21, s30
	s_cselect_b32 s34, s27, s2
	s_cselect_b32 s31, s19, s79
	s_cselect_b32 s30, s68, s78
	v_lshl_add_u64 v[142:143], s[28:29], 0, v[136:137]
	s_add_i32 m0, s45, 0xc000
	ds_read_b128 v[176:179], v147
	ds_read_b128 v[180:183], v147 offset:1024
	ds_read_b128 v[184:187], v147 offset:2048
	ds_read_b128 v[188:191], v147 offset:3072
	ds_read_b128 v[204:207], v147 offset:4096
	ds_read_b128 v[208:211], v147 offset:5120
	ds_read_b128 v[218:221], v147 offset:6144
	ds_read_b128 v[222:225], v147 offset:7168
	global_load_lds_dwordx4 v[142:143], off
	v_lshl_add_u64 v[142:143], s[28:29], 0, v[134:135]
	s_add_i32 m0, s45, 0xe000
	s_nop 0
	global_load_lds_dwordx4 v[142:143], off
	s_waitcnt vmcnt(8)
	s_waitcnt lgkmcnt(0)
	s_barrier
	s_setprio 1
	s_waitcnt lgkmcnt(0)
	s_nop 0
	v_mfma_f32_16x16x32_bf16 v[124:127], v[138:141], v[176:179], v[124:127]
	v_mfma_f32_16x16x32_bf16 v[120:123], v[152:155], v[176:179], v[120:123]
	v_mfma_f32_16x16x32_bf16 v[108:111], v[138:141], v[184:187], v[108:111]
	v_mfma_f32_16x16x32_bf16 v[104:107], v[152:155], v[184:187], v[104:107]
	v_mfma_f32_16x16x32_bf16 v[92:95], v[138:141], v[204:207], v[92:95]
	v_mfma_f32_16x16x32_bf16 v[88:91], v[152:155], v[204:207], v[88:91]
	v_mfma_f32_16x16x32_bf16 v[76:79], v[138:141], v[218:221], v[76:79]
	v_mfma_f32_16x16x32_bf16 v[72:75], v[152:155], v[218:221], v[72:75]
	v_mfma_f32_16x16x32_bf16 v[124:127], v[148:151], v[180:183], v[124:127]
	v_mfma_f32_16x16x32_bf16 v[120:123], v[156:159], v[180:183], v[120:123]
	v_mfma_f32_16x16x32_bf16 v[108:111], v[148:151], v[188:191], v[108:111]
	v_mfma_f32_16x16x32_bf16 v[104:107], v[156:159], v[188:191], v[104:107]
	v_mfma_f32_16x16x32_bf16 v[92:95], v[148:151], v[208:211], v[92:95]
	v_mfma_f32_16x16x32_bf16 v[88:91], v[156:159], v[208:211], v[88:91]
	v_mfma_f32_16x16x32_bf16 v[76:79], v[148:151], v[222:225], v[76:79]
	v_mfma_f32_16x16x32_bf16 v[72:75], v[156:159], v[222:225], v[72:75]
	s_setprio 0
	s_setprio 1
	v_mfma_f32_16x16x32_bf16 v[116:119], v[160:163], v[176:179], v[116:119]
	v_mfma_f32_16x16x32_bf16 v[112:115], v[168:171], v[176:179], v[112:115]
	v_mfma_f32_16x16x32_bf16 v[100:103], v[160:163], v[184:187], v[100:103]
	v_mfma_f32_16x16x32_bf16 v[96:99], v[168:171], v[184:187], v[96:99]
	v_mfma_f32_16x16x32_bf16 v[84:87], v[160:163], v[204:207], v[84:87]
	v_mfma_f32_16x16x32_bf16 v[80:83], v[168:171], v[204:207], v[80:83]
	v_mfma_f32_16x16x32_bf16 v[68:71], v[160:163], v[218:221], v[68:71]
	v_mfma_f32_16x16x32_bf16 v[64:67], v[168:171], v[218:221], v[64:67]
	v_mfma_f32_16x16x32_bf16 v[116:119], v[164:167], v[180:183], v[116:119]
	v_mfma_f32_16x16x32_bf16 v[112:115], v[172:175], v[180:183], v[112:115]
	v_mfma_f32_16x16x32_bf16 v[100:103], v[164:167], v[188:191], v[100:103]
	v_mfma_f32_16x16x32_bf16 v[96:99], v[172:175], v[188:191], v[96:99]
	v_mfma_f32_16x16x32_bf16 v[84:87], v[164:167], v[208:211], v[84:87]
	v_mfma_f32_16x16x32_bf16 v[80:83], v[172:175], v[208:211], v[80:83]
	v_mfma_f32_16x16x32_bf16 v[68:71], v[164:167], v[222:225], v[68:71]
	v_mfma_f32_16x16x32_bf16 v[64:67], v[172:175], v[222:225], v[64:67]
	s_setprio 0
	s_barrier
	s_mov_b32 m0, s40
	v_lshl_add_u64 v[142:143], s[30:31], 0, v[192:193]
	s_add_u32 s84, s30, 0x40000
	ds_read_b128 v[176:179], v147 offset:16384
	ds_read_b128 v[180:183], v147 offset:17408
	ds_read_b128 v[184:187], v147 offset:18432
	ds_read_b128 v[188:191], v147 offset:19456
	ds_read_b128 v[204:207], v147 offset:20480
	ds_read_b128 v[208:211], v147 offset:21504
	ds_read_b128 v[218:221], v147 offset:22528
	ds_read_b128 v[222:225], v147 offset:23552
	global_load_lds_dwordx4 v[142:143], off
	v_lshl_add_u64 v[194:195], s[30:31], 0, v[132:133]
	s_mov_b32 m0, s41
	s_addc_u32 s85, s31, 0
	global_load_lds_dwordx4 v[194:195], off
	v_lshl_add_u64 v[226:227], s[84:85], 0, v[192:193]
	s_mov_b32 m0, s43
	v_lshl_add_u64 v[228:229], s[34:35], 0, v[130:131]
	global_load_lds_dwordx4 v[226:227], off
	v_lshl_add_u64 v[226:227], s[84:85], 0, v[132:133]
	s_mov_b32 m0, s44
	s_nop 0
	global_load_lds_dwordx4 v[226:227], off
	v_lshl_add_u64 v[226:227], s[34:35], 0, v[128:129]
	s_mov_b32 m0, s45
	s_nop 0
	global_load_lds_dwordx4 v[226:227], off
	s_mov_b32 m0, s48
	s_nop 0
	global_load_lds_dwordx4 v[228:229], off
	s_waitcnt vmcnt(8)
	s_waitcnt lgkmcnt(0)
	s_barrier
; #define PG8_STAGE(bufoff, gbase, voff) do { _Pragma("unroll") for (int _i = 0; _i < 2; ++_i) \
;         __builtin_amdgcn_global_load_lds((const unsigned*)((const char*)(gbase) + (voff)[_i]), (PG8_LAS unsigned*)(lds + (bufoff) + ldsw + _i * 8192), 16, 0, 0); } while (0)
; #define PG8_LDA(dst, b, h) do { _Pragma("unroll") for (int m = 0; m < 4; ++m) _Pragma("unroll") for (int k = 0; k < 2; ++k) dst[m][k] = *(const PG8_LAS bf16x8*)(lds + PG8_SA(b, h) + aoff + m * 2048 + k * 1024); } while (0)
; #define PG8_LDB(dst, b, h) do { _Pragma("unroll") for (int n = 0; n < 2; ++n) _Pragma("unroll") for (int k = 0; k < 2; ++k) dst[n][k] = *(const PG8_LAS bf16x8*)(lds + PG8_SB(b, h) + boff + n * 2048 + k * 1024); } while (0)
; #define PG8_MMA(ai, bj, At, Bt) do { __builtin_amdgcn_s_setprio(1); _Pragma("unroll") for (int m = 0; m < 4; ++m) _Pragma("unroll") for (int n = 0; n < 2; ++n) _Pragma("unroll") for (int k = 0; k < 2; ++k) \
;         acc[ai][bj][m][n] = __builtin_amdgcn_mfma_f32_16x16x32_bf16(Bt[n][k], At[m][k], acc[ai][bj][m][n], 0, 0, 0); __builtin_amdgcn_s_setprio(0); } while (0)
; #define PG8_WAIT_V(n) asm volatile("s_waitcnt vmcnt(" #n ")" ::: "memory")
; #define PG8_WAIT_L(n) asm volatile("s_waitcnt lgkmcnt(" #n ")" ::: "memory")
; #define PG8_BAR __builtin_amdgcn_s_barrier()
; #define PG8_SCHED __builtin_amdgcn_sched_barrier(0)
; template <class Epi, class Sched, bool ALIGN_EPI = false, bool SP2 = false>
; __device__ __forceinline__ void gemm_phase(PG8_LAS unsigned char* lds, const Gemm g, const Sched& S, const Epi& E) {
;     ...
;             if constexpr (SP2) {
;             PG8_LDB(B0, 0, 0); PG8_LDB(B1, 0, 1); PG8_SCHED; PG8_LDA(At, 0, 0); PG8_STAGE(PG8_SA(1, 1), a1 + hstepA, voffA);
;             PG8_WAIT_V(8); PG8_WAIT_L(0); PG8_BAR; PG8_MMA(0, 0, At, B0); PG8_MMA(0, 1, At, B1); PG8_BAR; PG8_SCHED;
;             PG8_LDA(At, 0, 1); PG8_STAGE(PG8_SB(0, 0), b2, voffB); PG8_STAGE(PG8_SB(0, 1), b2 + hstepB, voffB); PG8_STAGE(PG8_SA(0, 0), a2, voffA);
;             PG8_WAIT_V(8); PG8_WAIT_L(0); PG8_BAR; PG8_MMA(1, 0, At, B0); PG8_MMA(1, 1, At, B1); PG8_BAR; PG8_SCHED;
;             PG8_LDB(B0, 1, 0); PG8_LDB(B1, 1, 1); PG8_SCHED; PG8_LDA(At, 1, 0); PG8_STAGE(PG8_SA(0, 1), a2 + hstepA, voffA);
;             PG8_WAIT_V(8); PG8_WAIT_L(0); PG8_BAR; PG8_MMA(0, 0, At, B0); PG8_MMA(0, 1, At, B1); PG8_BAR; PG8_SCHED;
	s_setprio 1
	s_waitcnt lgkmcnt(0)
	s_nop 0
	v_mfma_f32_16x16x32_bf16 v[60:63], v[138:141], v[176:179], v[60:63]
	v_mfma_f32_16x16x32_bf16 v[56:59], v[152:155], v[176:179], v[56:59]
	v_mfma_f32_16x16x32_bf16 v[44:47], v[138:141], v[184:187], v[44:47]
	v_mfma_f32_16x16x32_bf16 v[40:43], v[152:155], v[184:187], v[40:43]
	v_mfma_f32_16x16x32_bf16 v[28:31], v[138:141], v[204:207], v[28:31]
	v_mfma_f32_16x16x32_bf16 v[24:27], v[152:155], v[204:207], v[24:27]
	v_mfma_f32_16x16x32_bf16 v[12:15], v[138:141], v[218:221], v[12:15]
	v_mfma_f32_16x16x32_bf16 v[8:11], v[152:155], v[218:221], v[8:11]
	v_mfma_f32_16x16x32_bf16 v[60:63], v[148:151], v[180:183], v[60:63]
	v_mfma_f32_16x16x32_bf16 v[56:59], v[156:159], v[180:183], v[56:59]
	v_mfma_f32_16x16x32_bf16 v[44:47], v[148:151], v[188:191], v[44:47]
	v_mfma_f32_16x16x32_bf16 v[40:43], v[156:159], v[188:191], v[40:43]
	v_mfma_f32_16x16x32_bf16 v[28:31], v[148:151], v[208:211], v[28:31]
	v_mfma_f32_16x16x32_bf16 v[24:27], v[156:159], v[208:211], v[24:27]
	v_mfma_f32_16x16x32_bf16 v[12:15], v[148:151], v[222:225], v[12:15]
	v_mfma_f32_16x16x32_bf16 v[8:11], v[156:159], v[222:225], v[8:11]
	s_setprio 0
	s_setprio 1
	v_mfma_f32_16x16x32_bf16 v[52:55], v[160:163], v[176:179], v[52:55]
	v_mfma_f32_16x16x32_bf16 v[48:51], v[168:171], v[176:179], v[48:51]
	v_mfma_f32_16x16x32_bf16 v[36:39], v[160:163], v[184:187], v[36:39]
	v_mfma_f32_16x16x32_bf16 v[32:35], v[168:171], v[184:187], v[32:35]
	v_mfma_f32_16x16x32_bf16 v[20:23], v[160:163], v[204:207], v[20:23]
	v_mfma_f32_16x16x32_bf16 v[16:19], v[168:171], v[204:207], v[16:19]
	v_mfma_f32_16x16x32_bf16 v[4:7], v[160:163], v[218:221], v[4:7]
	v_mfma_f32_16x16x32_bf16 v[0:3], v[168:171], v[218:221], v[0:3]
	v_mfma_f32_16x16x32_bf16 v[52:55], v[164:167], v[180:183], v[52:55]
	v_mfma_f32_16x16x32_bf16 v[48:51], v[172:175], v[180:183], v[48:51]
	v_mfma_f32_16x16x32_bf16 v[36:39], v[164:167], v[188:191], v[36:39]
	v_mfma_f32_16x16x32_bf16 v[32:35], v[172:175], v[188:191], v[32:35]
	v_mfma_f32_16x16x32_bf16 v[20:23], v[164:167], v[208:211], v[20:23]
	v_mfma_f32_16x16x32_bf16 v[16:19], v[172:175], v[208:211], v[16:19]
	v_mfma_f32_16x16x32_bf16 v[4:7], v[164:167], v[222:225], v[4:7]
	v_mfma_f32_16x16x32_bf16 v[0:3], v[172:175], v[222:225], v[0:3]
	s_setprio 0
	s_barrier
	v_add_u32_e32 v156, s60, v145
	v_add_u32_e32 v172, s67, v145
	ds_read_b128 v[138:141], v156
	ds_read_b128 v[148:151], v156 offset:1024
	ds_read_b128 v[152:155], v156 offset:2048
	ds_read_b128 v[156:159], v156 offset:3072
	ds_read_b128 v[160:163], v172
	ds_read_b128 v[164:167], v172 offset:1024
	ds_read_b128 v[168:171], v172 offset:2048
	ds_read_b128 v[172:175], v172 offset:3072
	s_add_u32 s34, s34, 0x40000
	s_addc_u32 s35, s35, 0
	s_mov_b32 m0, s49
	v_lshl_add_u64 v[230:231], s[34:35], 0, v[128:129]
	ds_read_b128 v[176:179], v147 offset:32768
	ds_read_b128 v[180:183], v147 offset:33792
	ds_read_b128 v[184:187], v147 offset:34816
	ds_read_b128 v[188:191], v147 offset:35840
	ds_read_b128 v[204:207], v147 offset:36864
	ds_read_b128 v[208:211], v147 offset:37888
	ds_read_b128 v[218:221], v147 offset:38912
	ds_read_b128 v[222:225], v147 offset:39936
	global_load_lds_dwordx4 v[230:231], off
	v_lshl_add_u64 v[230:231], s[34:35], 0, v[130:131]
	s_mov_b32 m0, s50
	s_nop 0
	global_load_lds_dwordx4 v[230:231], off
	s_waitcnt vmcnt(8)
	s_waitcnt lgkmcnt(0)
	s_barrier
	s_setprio 1
	s_waitcnt lgkmcnt(0)
	s_nop 0
	v_mfma_f32_16x16x32_bf16 v[124:127], v[138:141], v[176:179], v[124:127]
	v_mfma_f32_16x16x32_bf16 v[120:123], v[152:155], v[176:179], v[120:123]
	v_mfma_f32_16x16x32_bf16 v[108:111], v[138:141], v[184:187], v[108:111]
	v_mfma_f32_16x16x32_bf16 v[104:107], v[152:155], v[184:187], v[104:107]
	v_mfma_f32_16x16x32_bf16 v[92:95], v[138:141], v[204:207], v[92:95]
	v_mfma_f32_16x16x32_bf16 v[88:91], v[152:155], v[204:207], v[88:91]
	v_mfma_f32_16x16x32_bf16 v[76:79], v[138:141], v[218:221], v[76:79]
	v_mfma_f32_16x16x32_bf16 v[72:75], v[152:155], v[218:221], v[72:75]
	v_mfma_f32_16x16x32_bf16 v[124:127], v[148:151], v[180:183], v[124:127]
	v_mfma_f32_16x16x32_bf16 v[120:123], v[156:159], v[180:183], v[120:123]
	v_mfma_f32_16x16x32_bf16 v[108:111], v[148:151], v[188:191], v[108:111]
	v_mfma_f32_16x16x32_bf16 v[104:107], v[156:159], v[188:191], v[104:107]
	v_mfma_f32_16x16x32_bf16 v[92:95], v[148:151], v[208:211], v[92:95]
	v_mfma_f32_16x16x32_bf16 v[88:91], v[156:159], v[208:211], v[88:91]
	v_mfma_f32_16x16x32_bf16 v[76:79], v[148:151], v[222:225], v[76:79]
	v_mfma_f32_16x16x32_bf16 v[72:75], v[156:159], v[222:225], v[72:75]
	s_setprio 0
	s_setprio 1
	v_mfma_f32_16x16x32_bf16 v[116:119], v[160:163], v[176:179], v[116:119]
	v_mfma_f32_16x16x32_bf16 v[112:115], v[168:171], v[176:179], v[112:115]
	v_mfma_f32_16x16x32_bf16 v[100:103], v[160:163], v[184:187], v[100:103]
	v_mfma_f32_16x16x32_bf16 v[96:99], v[168:171], v[184:187], v[96:99]
	v_mfma_f32_16x16x32_bf16 v[84:87], v[160:163], v[204:207], v[84:87]
	v_mfma_f32_16x16x32_bf16 v[80:83], v[168:171], v[204:207], v[80:83]
	v_mfma_f32_16x16x32_bf16 v[68:71], v[160:163], v[218:221], v[68:71]
	v_mfma_f32_16x16x32_bf16 v[64:67], v[168:171], v[218:221], v[64:67]
	v_mfma_f32_16x16x32_bf16 v[116:119], v[164:167], v[180:183], v[116:119]
	v_mfma_f32_16x16x32_bf16 v[112:115], v[172:175], v[180:183], v[112:115]
	v_mfma_f32_16x16x32_bf16 v[100:103], v[164:167], v[188:191], v[100:103]
	v_mfma_f32_16x16x32_bf16 v[96:99], v[172:175], v[188:191], v[96:99]
	v_mfma_f32_16x16x32_bf16 v[84:87], v[164:167], v[208:211], v[84:87]
	v_mfma_f32_16x16x32_bf16 v[80:83], v[172:175], v[208:211], v[80:83]
	v_mfma_f32_16x16x32_bf16 v[68:71], v[164:167], v[222:225], v[68:71]
	v_mfma_f32_16x16x32_bf16 v[64:67], v[172:175], v[222:225], v[64:67]
	s_setprio 0
	s_barrier
; #define PG8_STAGE(bufoff, gbase, voff) do { _Pragma("unroll") for (int _i = 0; _i < 2; ++_i) \
;         __builtin_amdgcn_global_load_lds((const unsigned*)((const char*)(gbase) + (voff)[_i]), (PG8_LAS unsigned*)(lds + (bufoff) + ldsw + _i * 8192), 16, 0, 0); } while (0)
; #define PG8_LDA(dst, b, h) do { _Pragma("unroll") for (int m = 0; m < 4; ++m) _Pragma("unroll") for (int k = 0; k < 2; ++k) dst[m][k] = *(const PG8_LAS bf16x8*)(lds + PG8_SA(b, h) + aoff + m * 2048 + k * 1024); } while (0)
; #define PG8_MMA(ai, bj, At, Bt) do { __builtin_amdgcn_s_setprio(1); _Pragma("unroll") for (int m = 0; m < 4; ++m) _Pragma("unroll") for (int n = 0; n < 2; ++n) _Pragma("unroll") for (int k = 0; k < 2; ++k) \
;         acc[ai][bj][m][n] = __builtin_amdgcn_mfma_f32_16x16x32_bf16(Bt[n][k], At[m][k], acc[ai][bj][m][n], 0, 0, 0); __builtin_amdgcn_s_setprio(0); } while (0)
; #define PG8_WAIT_V(n) asm volatile("s_waitcnt vmcnt(" #n ")" ::: "memory")
; #define PG8_WAIT_L(n) asm volatile("s_waitcnt lgkmcnt(" #n ")" ::: "memory")
; #define PG8_BAR __builtin_amdgcn_s_barrier()
; #define PG8_SCHED __builtin_amdgcn_sched_barrier(0)
; template <class Epi, class Sched, bool ALIGN_EPI = false, bool SP2 = false>
; __device__ __forceinline__ void gemm_phase(PG8_LAS unsigned char* lds, const Gemm g, const Sched& S, const Epi& E) {
;     ...
;             PG8_LDA(At, 1, 1); PG8_STAGE(PG8_SB(1, 0), b3, voffB); PG8_STAGE(PG8_SB(1, 1), b3 + hstepB, voffB); PG8_STAGE(PG8_SA(1, 0), a3, voffA);
;             PG8_WAIT_V(8); PG8_WAIT_L(0); PG8_BAR; PG8_MMA(1, 0, At, B0); PG8_MMA(1, 1, At, B1); PG8_BAR; PG8_SCHED;
;     ...
;         if constexpr (ALIGN_EPI) { if (wr == 0) PG8_BAR; }
;     __device__ __forceinline__ void operator()(const f32x4 (&acc)[2][2][4][2], const pg8::Unit& u, int wr, int wc, int fr, int fq) const {
;         const int row0 = u.pm * 256 + wr * 64 + fr, col0 = u.pn * 256 + wc * 32 + 8 * fq;
; #pragma unroll
;         for (int ai = 0; ai < 2; ++ai)
; #pragma unroll
;             for (int m = 0; m < 4; ++m) {
;                 const int row = row0 + ai * 128 + m * 16; float ss = 0.f;
; #pragma unroll
;                 for (int bj = 0; bj < 2; ++bj) {
;                     const size_t off = (size_t)row * DM + col0 + bj * 128;
;                     const v4u b = *(const v4u*)(xb + off);
	s_mov_b32 m0, s61
	v_lshl_add_u64 v[142:143], v[142:143], 0, s[76:77]
	s_add_u32 s30, s30, 0x40080
	ds_read_b128 v[176:179], v147 offset:49152
	ds_read_b128 v[180:183], v147 offset:50176
	ds_read_b128 v[184:187], v147 offset:51200
	ds_read_b128 v[188:191], v147 offset:52224
	ds_read_b128 v[204:207], v147 offset:53248
	ds_read_b128 v[208:211], v147 offset:54272
	ds_read_b128 v[218:221], v147 offset:55296
	ds_read_b128 v[222:225], v147 offset:56320
	global_load_lds_dwordx4 v[142:143], off
	v_lshl_add_u64 v[142:143], v[194:195], 0, s[76:77]
	s_mov_b32 m0, s64
	s_addc_u32 s31, s31, 0
	global_load_lds_dwordx4 v[142:143], off
	v_lshl_add_u64 v[142:143], s[30:31], 0, v[192:193]
	s_mov_b32 m0, s70
	s_nop 0
	global_load_lds_dwordx4 v[142:143], off
	v_lshl_add_u64 v[142:143], s[30:31], 0, v[132:133]
	s_mov_b32 m0, s71
	s_nop 0
	global_load_lds_dwordx4 v[142:143], off
	v_lshl_add_u64 v[142:143], v[226:227], 0, s[76:77]
	s_mov_b32 m0, s65
	s_nop 0
	global_load_lds_dwordx4 v[142:143], off
	v_lshl_add_u64 v[142:143], v[228:229], 0, s[76:77]
	s_mov_b32 m0, s66
	s_nop 0
	global_load_lds_dwordx4 v[142:143], off
	s_waitcnt vmcnt(8)
	s_waitcnt lgkmcnt(0)
	s_barrier
	s_setprio 1
	s_waitcnt lgkmcnt(0)
	v_mfma_f32_16x16x32_bf16 v[60:63], v[138:141], v[176:179], v[60:63]
	v_mfma_f32_16x16x32_bf16 v[56:59], v[152:155], v[176:179], v[56:59]
	v_mfma_f32_16x16x32_bf16 v[44:47], v[138:141], v[184:187], v[44:47]
	v_mfma_f32_16x16x32_bf16 v[40:43], v[152:155], v[184:187], v[40:43]
	v_mfma_f32_16x16x32_bf16 v[28:31], v[138:141], v[204:207], v[28:31]
	v_mfma_f32_16x16x32_bf16 v[24:27], v[152:155], v[204:207], v[24:27]
	v_mfma_f32_16x16x32_bf16 v[12:15], v[138:141], v[218:221], v[12:15]
	v_mfma_f32_16x16x32_bf16 v[8:11], v[152:155], v[218:221], v[8:11]
	v_mfma_f32_16x16x32_bf16 v[60:63], v[148:151], v[180:183], v[60:63]
	v_mfma_f32_16x16x32_bf16 v[56:59], v[156:159], v[180:183], v[56:59]
	v_mfma_f32_16x16x32_bf16 v[44:47], v[148:151], v[188:191], v[44:47]
	v_mfma_f32_16x16x32_bf16 v[40:43], v[156:159], v[188:191], v[40:43]
	v_mfma_f32_16x16x32_bf16 v[28:31], v[148:151], v[208:211], v[28:31]
	v_mfma_f32_16x16x32_bf16 v[24:27], v[156:159], v[208:211], v[24:27]
	v_mfma_f32_16x16x32_bf16 v[12:15], v[148:151], v[222:225], v[12:15]
	v_mfma_f32_16x16x32_bf16 v[8:11], v[156:159], v[222:225], v[8:11]
	s_setprio 0
	s_setprio 1
	v_mfma_f32_16x16x32_bf16 v[52:55], v[160:163], v[176:179], v[52:55]
	v_mfma_f32_16x16x32_bf16 v[48:51], v[168:171], v[176:179], v[48:51]
	v_mfma_f32_16x16x32_bf16 v[36:39], v[160:163], v[184:187], v[36:39]
	v_mfma_f32_16x16x32_bf16 v[32:35], v[168:171], v[184:187], v[32:35]
	v_mfma_f32_16x16x32_bf16 v[20:23], v[160:163], v[204:207], v[20:23]
	v_mfma_f32_16x16x32_bf16 v[16:19], v[168:171], v[204:207], v[16:19]
	v_mfma_f32_16x16x32_bf16 v[4:7], v[160:163], v[218:221], v[4:7]
	v_mfma_f32_16x16x32_bf16 v[0:3], v[168:171], v[218:221], v[0:3]
	v_mfma_f32_16x16x32_bf16 v[52:55], v[164:167], v[180:183], v[52:55]
	v_mfma_f32_16x16x32_bf16 v[48:51], v[172:175], v[180:183], v[48:51]
	v_mfma_f32_16x16x32_bf16 v[36:39], v[164:167], v[188:191], v[36:39]
	v_mfma_f32_16x16x32_bf16 v[32:35], v[172:175], v[188:191], v[32:35]
	v_mfma_f32_16x16x32_bf16 v[20:23], v[164:167], v[208:211], v[20:23]
	v_mfma_f32_16x16x32_bf16 v[16:19], v[172:175], v[208:211], v[16:19]
	v_mfma_f32_16x16x32_bf16 v[4:7], v[164:167], v[222:225], v[4:7]
	v_mfma_f32_16x16x32_bf16 v[0:3], v[172:175], v[222:225], v[0:3]
	s_setprio 0
	s_barrier
	s_add_i32 s82, s82, 2
	s_add_u32 s78, s78, 0x100
	s_addc_u32 s79, s79, 0
	s_add_u32 s28, s28, 0x100
	s_addc_u32 s29, s29, 0
	s_cmp_gt_u32 s82, 13
	s_cbranch_scc0 .LBB0_1121
	v_lshl_add_u32 v159, s26, 8, v144
	v_lshl_or_b32 v158, s8, 8, v146
	v_lshlrev_b32_e32 v159, 11, v159
	v_lshl_add_u32 v159, v158, 1, v159
	v_add_u32_e32 v218, 0x8000, v159
	v_add_u32_e32 v219, 0x10000, v159
	v_add_u32_e32 v240, 0x18000, v159
	v_add_u32_e32 v241, 0x40000, v159
	v_add_u32_e32 v245, 0x48000, v159
	v_add_u32_e32 v246, 0x50000, v159
	v_add_u32_e32 v247, 0x58000, v159
	global_load_dwordx4 v[160:163], v159, s[12:13]
	global_load_dwordx4 v[164:167], v159, s[12:13] offset:256
	global_load_dwordx4 v[168:171], v218, s[12:13]
	global_load_dwordx4 v[172:175], v218, s[12:13] offset:256
	global_load_dwordx4 v[176:179], v219, s[12:13]
	global_load_dwordx4 v[180:183], v219, s[12:13] offset:256
	global_load_dwordx4 v[184:187], v240, s[12:13]
	global_load_dwordx4 v[188:191], v240, s[12:13] offset:256
	global_load_dwordx4 v[204:207], v241, s[12:13]
	global_load_dwordx4 v[208:211], v241, s[12:13] offset:256
	global_load_dwordx4 v[220:223], v245, s[12:13]
	global_load_dwordx4 v[224:227], v245, s[12:13] offset:256
	global_load_dwordx4 v[228:231], v246, s[12:13]
	global_load_dwordx4 v[232:235], v246, s[12:13] offset:256
	global_load_dwordx4 v[236:239], v247, s[12:13]
	global_load_dwordx4 v[248:251], v247, s[12:13] offset:256
	s_and_b64 vcc, exec, s[16:17]
	s_cbranch_vccz .LBB0_1124
	s_barrier

; #define PG8_STAGE(bufoff, gbase, voff) do { _Pragma("unroll") for (int _i = 0; _i < 2; ++_i) \
;         __builtin_amdgcn_global_load_lds((const unsigned*)((const char*)(gbase) + (voff)[_i]), (PG8_LAS unsigned*)(lds + (bufoff) + ldsw + _i * 8192), 16, 0, 0); } while (0)
; #define PG8_LDA(dst, b, h) do { _Pragma("unroll") for (int m = 0; m < 4; ++m) _Pragma("unroll") for (int k = 0; k < 2; ++k) dst[m][k] = *(const PG8_LAS bf16x8*)(lds + PG8_SA(b, h) + aoff + m * 2048 + k * 1024); } while (0)
; #define PG8_LDB(dst, b, h) do { _Pragma("unroll") for (int n = 0; n < 2; ++n) _Pragma("unroll") for (int k = 0; k < 2; ++k) dst[n][k] = *(const PG8_LAS bf16x8*)(lds + PG8_SB(b, h) + boff + n * 2048 + k * 1024); } while (0)
; #define PG8_MMA(ai, bj, At, Bt) do { __builtin_amdgcn_s_setprio(1); _Pragma("unroll") for (int m = 0; m < 4; ++m) _Pragma("unroll") for (int n = 0; n < 2; ++n) _Pragma("unroll") for (int k = 0; k < 2; ++k) \
;         acc[ai][bj][m][n] = __builtin_amdgcn_mfma_f32_16x16x32_bf16(Bt[n][k], At[m][k], acc[ai][bj][m][n], 0, 0, 0); __builtin_amdgcn_s_setprio(0); } while (0)
; #define PG8_WAIT_V(n) asm volatile("s_waitcnt vmcnt(" #n ")" ::: "memory")
; #define PG8_BAR __builtin_amdgcn_s_barrier()
; template <class Epi, class Sched, bool ALIGN_EPI = false, bool SP2 = false>
; __device__ __forceinline__ void gemm_phase(PG8_LAS unsigned char* lds, const Gemm g, const Sched& S, const Epi& E) {
;     ...
;         for (int t = 0; t < nt; t += 2) {
;             const bool last = (t == nt - 2);
;             const char* a1 = cA + (size_t)(t + 1) * kstep;
;             const char* a2 = last ? nA : cA + (size_t)(t + 2) * kstep; const char* b2 = last ? nB : cB + (size_t)(t + 2) * kstep;
;             const char* a3 = a2 + kstep; const char* b3 = b2 + kstep;
;             if (last && has_next) S.a_ready(nxt);
;             if constexpr (SP2) {
;             PG8_LDB(B0, 0, 0); PG8_LDB(B1, 0, 1); PG8_SCHED; PG8_LDA(At, 0, 0); PG8_STAGE(PG8_SA(1, 1), a1 + hstepA, voffA);
;             PG8_WAIT_V(8); PG8_WAIT_L(0); PG8_BAR; PG8_MMA(0, 0, At, B0); PG8_MMA(0, 1, At, B1); PG8_BAR; PG8_SCHED;
;             PG8_LDA(At, 0, 1); PG8_STAGE(PG8_SB(0, 0), b2, voffB); PG8_STAGE(PG8_SB(0, 1), b2 + hstepB, voffB); PG8_STAGE(PG8_SA(0, 0), a2, voffA);
;             PG8_WAIT_V(8); PG8_WAIT_L(0); PG8_BAR; PG8_MMA(1, 0, At, B0); PG8_MMA(1, 1, At, B1); PG8_BAR; PG8_SCHED;
.LBB0_1221:
	v_add_u32_e32 v156, s21, v149
	v_add_u32_e32 v172, s37, v149
	ds_read_b128 v[140:143], v156
	ds_read_b128 v[144:147], v156 offset:1024
	ds_read_b128 v[152:155], v156 offset:2048
	ds_read_b128 v[156:159], v156 offset:3072
	ds_read_b128 v[160:163], v172
	ds_read_b128 v[164:167], v172 offset:1024
	ds_read_b128 v[168:171], v172 offset:2048
	ds_read_b128 v[172:175], v172 offset:3072
	s_add_u32 s2, s22, 0xfffc0080
	s_addc_u32 s24, s23, -1
	s_cmp_eq_u32 s72, 12
	s_cselect_b32 s27, s15, s24
	s_cselect_b32 s26, s67, s2
	s_cselect_b32 s25, s13, s71
	s_cselect_b32 s24, s68, s70
	v_lshl_add_u64 v[194:195], s[22:23], 0, v[138:139]
	s_add_i32 m0, s40, 0xc000
	ds_read_b128 v[176:179], v151
	ds_read_b128 v[180:183], v151 offset:1024
	ds_read_b128 v[184:187], v151 offset:2048
	ds_read_b128 v[188:191], v151 offset:3072
	ds_read_b128 v[204:207], v151 offset:4096
	ds_read_b128 v[208:211], v151 offset:5120
	ds_read_b128 v[218:221], v151 offset:6144
	ds_read_b128 v[222:225], v151 offset:7168
	global_load_lds_dwordx4 v[194:195], off
	v_lshl_add_u64 v[194:195], s[22:23], 0, v[136:137]
	s_add_i32 m0, s40, 0xe000
	s_nop 0
	global_load_lds_dwordx4 v[194:195], off
	s_waitcnt vmcnt(8)
	s_waitcnt lgkmcnt(0)
	s_barrier
	s_setprio 1
	s_waitcnt lgkmcnt(0)
	v_mfma_f32_16x16x32_bf16 v[116:119], v[140:143], v[176:179], v[116:119]
	v_mfma_f32_16x16x32_bf16 v[112:115], v[152:155], v[176:179], v[112:115]
	v_mfma_f32_16x16x32_bf16 v[108:111], v[140:143], v[184:187], v[108:111]
	v_mfma_f32_16x16x32_bf16 v[104:107], v[152:155], v[184:187], v[104:107]
	v_mfma_f32_16x16x32_bf16 v[92:95], v[140:143], v[204:207], v[92:95]
	v_mfma_f32_16x16x32_bf16 v[88:91], v[152:155], v[204:207], v[88:91]
	v_mfma_f32_16x16x32_bf16 v[76:79], v[140:143], v[218:221], v[76:79]
	v_mfma_f32_16x16x32_bf16 v[72:75], v[152:155], v[218:221], v[72:75]
	v_mfma_f32_16x16x32_bf16 v[116:119], v[144:147], v[180:183], v[116:119]
	v_mfma_f32_16x16x32_bf16 v[112:115], v[156:159], v[180:183], v[112:115]
	v_mfma_f32_16x16x32_bf16 v[108:111], v[144:147], v[188:191], v[108:111]
	v_mfma_f32_16x16x32_bf16 v[104:107], v[156:159], v[188:191], v[104:107]
	v_mfma_f32_16x16x32_bf16 v[92:95], v[144:147], v[208:211], v[92:95]
	v_mfma_f32_16x16x32_bf16 v[88:91], v[156:159], v[208:211], v[88:91]
	v_mfma_f32_16x16x32_bf16 v[76:79], v[144:147], v[222:225], v[76:79]
	v_mfma_f32_16x16x32_bf16 v[72:75], v[156:159], v[222:225], v[72:75]
	s_setprio 0
	s_setprio 1
	v_mfma_f32_16x16x32_bf16 v[124:127], v[160:163], v[176:179], v[124:127]
	v_mfma_f32_16x16x32_bf16 v[120:123], v[168:171], v[176:179], v[120:123]
	v_mfma_f32_16x16x32_bf16 v[100:103], v[160:163], v[184:187], v[100:103]
	v_mfma_f32_16x16x32_bf16 v[96:99], v[168:171], v[184:187], v[96:99]
	v_mfma_f32_16x16x32_bf16 v[84:87], v[160:163], v[204:207], v[84:87]
	v_mfma_f32_16x16x32_bf16 v[80:83], v[168:171], v[204:207], v[80:83]
	v_mfma_f32_16x16x32_bf16 v[68:71], v[160:163], v[218:221], v[68:71]
	v_mfma_f32_16x16x32_bf16 v[64:67], v[168:171], v[218:221], v[64:67]
	v_mfma_f32_16x16x32_bf16 v[124:127], v[164:167], v[180:183], v[124:127]
	v_mfma_f32_16x16x32_bf16 v[120:123], v[172:175], v[180:183], v[120:123]
	v_mfma_f32_16x16x32_bf16 v[100:103], v[164:167], v[188:191], v[100:103]
	v_mfma_f32_16x16x32_bf16 v[96:99], v[172:175], v[188:191], v[96:99]
	v_mfma_f32_16x16x32_bf16 v[84:87], v[164:167], v[208:211], v[84:87]
	v_mfma_f32_16x16x32_bf16 v[80:83], v[172:175], v[208:211], v[80:83]
	v_mfma_f32_16x16x32_bf16 v[68:71], v[164:167], v[222:225], v[68:71]
	v_mfma_f32_16x16x32_bf16 v[64:67], v[172:175], v[222:225], v[64:67]
	s_setprio 0
	s_barrier
	s_mov_b32 m0, s35
	v_lshl_add_u64 v[194:195], s[24:25], 0, v[192:193]
	s_add_u32 s74, s24, 0x40000
	ds_read_b128 v[176:179], v151 offset:16384
	ds_read_b128 v[180:183], v151 offset:17408
	ds_read_b128 v[184:187], v151 offset:18432
	ds_read_b128 v[188:191], v151 offset:19456
	ds_read_b128 v[204:207], v151 offset:20480
	ds_read_b128 v[208:211], v151 offset:21504
	ds_read_b128 v[218:221], v151 offset:22528
	ds_read_b128 v[222:225], v151 offset:23552
	global_load_lds_dwordx4 v[194:195], off
	v_lshl_add_u64 v[226:227], s[24:25], 0, v[128:129]
	s_mov_b32 m0, s36
	s_addc_u32 s75, s25, 0
	global_load_lds_dwordx4 v[226:227], off
	v_lshl_add_u64 v[228:229], s[74:75], 0, v[192:193]
	s_mov_b32 m0, s38
	v_lshl_add_u64 v[230:231], s[26:27], 0, v[130:131]
	global_load_lds_dwordx4 v[228:229], off
	v_lshl_add_u64 v[228:229], s[74:75], 0, v[128:129]
	s_mov_b32 m0, s39
	s_nop 0
	global_load_lds_dwordx4 v[228:229], off
	v_lshl_add_u64 v[228:229], s[26:27], 0, v[132:133]
	s_mov_b32 m0, s40
	s_nop 0
	global_load_lds_dwordx4 v[228:229], off
	s_mov_b32 m0, s41
	s_nop 0
	global_load_lds_dwordx4 v[230:231], off
	s_waitcnt vmcnt(8)
	s_waitcnt lgkmcnt(0)
	s_barrier
; #define PG8_STAGE(bufoff, gbase, voff) do { _Pragma("unroll") for (int _i = 0; _i < 2; ++_i) \
;         __builtin_amdgcn_global_load_lds((const unsigned*)((const char*)(gbase) + (voff)[_i]), (PG8_LAS unsigned*)(lds + (bufoff) + ldsw + _i * 8192), 16, 0, 0); } while (0)
; #define PG8_LDA(dst, b, h) do { _Pragma("unroll") for (int m = 0; m < 4; ++m) _Pragma("unroll") for (int k = 0; k < 2; ++k) dst[m][k] = *(const PG8_LAS bf16x8*)(lds + PG8_SA(b, h) + aoff + m * 2048 + k * 1024); } while (0)
; #define PG8_LDB(dst, b, h) do { _Pragma("unroll") for (int n = 0; n < 2; ++n) _Pragma("unroll") for (int k = 0; k < 2; ++k) dst[n][k] = *(const PG8_LAS bf16x8*)(lds + PG8_SB(b, h) + boff + n * 2048 + k * 1024); } while (0)
; #define PG8_MMA(ai, bj, At, Bt) do { __builtin_amdgcn_s_setprio(1); _Pragma("unroll") for (int m = 0; m < 4; ++m) _Pragma("unroll") for (int n = 0; n < 2; ++n) _Pragma("unroll") for (int k = 0; k < 2; ++k) \
;         acc[ai][bj][m][n] = __builtin_amdgcn_mfma_f32_16x16x32_bf16(Bt[n][k], At[m][k], acc[ai][bj][m][n], 0, 0, 0); __builtin_amdgcn_s_setprio(0); } while (0)
; #define PG8_WAIT_V(n) asm volatile("s_waitcnt vmcnt(" #n ")" ::: "memory")
; #define PG8_WAIT_L(n) asm volatile("s_waitcnt lgkmcnt(" #n ")" ::: "memory")
; #define PG8_BAR __builtin_amdgcn_s_barrier()
; #define PG8_SCHED __builtin_amdgcn_sched_barrier(0)
; template <class Epi, class Sched, bool ALIGN_EPI = false, bool SP2 = false>
; __device__ __forceinline__ void gemm_phase(PG8_LAS unsigned char* lds, const Gemm g, const Sched& S, const Epi& E) {
;     ...
;             if constexpr (SP2) {
;             PG8_LDB(B0, 0, 0); PG8_LDB(B1, 0, 1); PG8_SCHED; PG8_LDA(At, 0, 0); PG8_STAGE(PG8_SA(1, 1), a1 + hstepA, voffA);
;             PG8_WAIT_V(8); PG8_WAIT_L(0); PG8_BAR; PG8_MMA(0, 0, At, B0); PG8_MMA(0, 1, At, B1); PG8_BAR; PG8_SCHED;
;             PG8_LDA(At, 0, 1); PG8_STAGE(PG8_SB(0, 0), b2, voffB); PG8_STAGE(PG8_SB(0, 1), b2 + hstepB, voffB); PG8_STAGE(PG8_SA(0, 0), a2, voffA);
;             PG8_WAIT_V(8); PG8_WAIT_L(0); PG8_BAR; PG8_MMA(1, 0, At, B0); PG8_MMA(1, 1, At, B1); PG8_BAR; PG8_SCHED;
;             PG8_LDB(B0, 1, 0); PG8_LDB(B1, 1, 1); PG8_SCHED; PG8_LDA(At, 1, 0); PG8_STAGE(PG8_SA(0, 1), a2 + hstepA, voffA);
;             PG8_WAIT_V(8); PG8_WAIT_L(0); PG8_BAR; PG8_MMA(0, 0, At, B0); PG8_MMA(0, 1, At, B1); PG8_BAR; PG8_SCHED;
	s_setprio 1
	s_waitcnt lgkmcnt(0)
	s_nop 0
	v_mfma_f32_16x16x32_bf16 v[60:63], v[140:143], v[176:179], v[60:63]
	v_mfma_f32_16x16x32_bf16 v[56:59], v[152:155], v[176:179], v[56:59]
	v_mfma_f32_16x16x32_bf16 v[44:47], v[140:143], v[184:187], v[44:47]
	v_mfma_f32_16x16x32_bf16 v[40:43], v[152:155], v[184:187], v[40:43]
	v_mfma_f32_16x16x32_bf16 v[28:31], v[140:143], v[204:207], v[28:31]
	v_mfma_f32_16x16x32_bf16 v[24:27], v[152:155], v[204:207], v[24:27]
	v_mfma_f32_16x16x32_bf16 v[12:15], v[140:143], v[218:221], v[12:15]
	v_mfma_f32_16x16x32_bf16 v[8:11], v[152:155], v[218:221], v[8:11]
	v_mfma_f32_16x16x32_bf16 v[60:63], v[144:147], v[180:183], v[60:63]
	v_mfma_f32_16x16x32_bf16 v[56:59], v[156:159], v[180:183], v[56:59]
	v_mfma_f32_16x16x32_bf16 v[44:47], v[144:147], v[188:191], v[44:47]
	v_mfma_f32_16x16x32_bf16 v[40:43], v[156:159], v[188:191], v[40:43]
	v_mfma_f32_16x16x32_bf16 v[28:31], v[144:147], v[208:211], v[28:31]
	v_mfma_f32_16x16x32_bf16 v[24:27], v[156:159], v[208:211], v[24:27]
	v_mfma_f32_16x16x32_bf16 v[12:15], v[144:147], v[222:225], v[12:15]
	v_mfma_f32_16x16x32_bf16 v[8:11], v[156:159], v[222:225], v[8:11]
	s_setprio 0
	s_setprio 1
	v_mfma_f32_16x16x32_bf16 v[52:55], v[160:163], v[176:179], v[52:55]
	v_mfma_f32_16x16x32_bf16 v[48:51], v[168:171], v[176:179], v[48:51]
	v_mfma_f32_16x16x32_bf16 v[36:39], v[160:163], v[184:187], v[36:39]
	v_mfma_f32_16x16x32_bf16 v[32:35], v[168:171], v[184:187], v[32:35]
	v_mfma_f32_16x16x32_bf16 v[20:23], v[160:163], v[204:207], v[20:23]
	v_mfma_f32_16x16x32_bf16 v[16:19], v[168:171], v[204:207], v[16:19]
	v_mfma_f32_16x16x32_bf16 v[4:7], v[160:163], v[218:221], v[4:7]
	v_mfma_f32_16x16x32_bf16 v[0:3], v[168:171], v[218:221], v[0:3]
	v_mfma_f32_16x16x32_bf16 v[52:55], v[164:167], v[180:183], v[52:55]
	v_mfma_f32_16x16x32_bf16 v[48:51], v[172:175], v[180:183], v[48:51]
	v_mfma_f32_16x16x32_bf16 v[36:39], v[164:167], v[188:191], v[36:39]
	v_mfma_f32_16x16x32_bf16 v[32:35], v[172:175], v[188:191], v[32:35]
	v_mfma_f32_16x16x32_bf16 v[20:23], v[164:167], v[208:211], v[20:23]
	v_mfma_f32_16x16x32_bf16 v[16:19], v[172:175], v[208:211], v[16:19]
	v_mfma_f32_16x16x32_bf16 v[4:7], v[164:167], v[222:225], v[4:7]
	v_mfma_f32_16x16x32_bf16 v[0:3], v[172:175], v[222:225], v[0:3]
	s_setprio 0
	s_barrier
	v_add_u32_e32 v156, s44, v149
	v_add_u32_e32 v172, s51, v149
	ds_read_b128 v[140:143], v156
	ds_read_b128 v[144:147], v156 offset:1024
	ds_read_b128 v[152:155], v156 offset:2048
	ds_read_b128 v[156:159], v156 offset:3072
	ds_read_b128 v[160:163], v172
	ds_read_b128 v[164:167], v172 offset:1024
	ds_read_b128 v[168:171], v172 offset:2048
	ds_read_b128 v[172:175], v172 offset:3072
	s_add_u32 s26, s26, 0x40000
	s_addc_u32 s27, s27, 0
	s_mov_b32 m0, s42
	v_lshl_add_u64 v[232:233], s[26:27], 0, v[132:133]
	ds_read_b128 v[176:179], v151 offset:32768
	ds_read_b128 v[180:183], v151 offset:33792
	ds_read_b128 v[184:187], v151 offset:34816
	ds_read_b128 v[188:191], v151 offset:35840
	ds_read_b128 v[204:207], v151 offset:36864
	ds_read_b128 v[208:211], v151 offset:37888
	ds_read_b128 v[218:221], v151 offset:38912
	ds_read_b128 v[222:225], v151 offset:39936
	global_load_lds_dwordx4 v[232:233], off
	v_lshl_add_u64 v[232:233], s[26:27], 0, v[130:131]
	s_mov_b32 m0, s43
	s_nop 0
	global_load_lds_dwordx4 v[232:233], off
	s_waitcnt vmcnt(8)
	s_waitcnt lgkmcnt(0)
	s_barrier
	s_setprio 1
	s_waitcnt lgkmcnt(0)
	s_nop 0
	v_mfma_f32_16x16x32_bf16 v[116:119], v[140:143], v[176:179], v[116:119]
	v_mfma_f32_16x16x32_bf16 v[112:115], v[152:155], v[176:179], v[112:115]
	v_mfma_f32_16x16x32_bf16 v[108:111], v[140:143], v[184:187], v[108:111]
	v_mfma_f32_16x16x32_bf16 v[104:107], v[152:155], v[184:187], v[104:107]
	v_mfma_f32_16x16x32_bf16 v[92:95], v[140:143], v[204:207], v[92:95]
	v_mfma_f32_16x16x32_bf16 v[88:91], v[152:155], v[204:207], v[88:91]
	v_mfma_f32_16x16x32_bf16 v[76:79], v[140:143], v[218:221], v[76:79]
	v_mfma_f32_16x16x32_bf16 v[72:75], v[152:155], v[218:221], v[72:75]
	v_mfma_f32_16x16x32_bf16 v[116:119], v[144:147], v[180:183], v[116:119]
	v_mfma_f32_16x16x32_bf16 v[112:115], v[156:159], v[180:183], v[112:115]
	v_mfma_f32_16x16x32_bf16 v[108:111], v[144:147], v[188:191], v[108:111]
	v_mfma_f32_16x16x32_bf16 v[104:107], v[156:159], v[188:191], v[104:107]
	v_mfma_f32_16x16x32_bf16 v[92:95], v[144:147], v[208:211], v[92:95]
	v_mfma_f32_16x16x32_bf16 v[88:91], v[156:159], v[208:211], v[88:91]
	v_mfma_f32_16x16x32_bf16 v[76:79], v[144:147], v[222:225], v[76:79]
	v_mfma_f32_16x16x32_bf16 v[72:75], v[156:159], v[222:225], v[72:75]
	s_setprio 0
	s_setprio 1
	v_mfma_f32_16x16x32_bf16 v[124:127], v[160:163], v[176:179], v[124:127]
	v_mfma_f32_16x16x32_bf16 v[120:123], v[168:171], v[176:179], v[120:123]
	v_mfma_f32_16x16x32_bf16 v[100:103], v[160:163], v[184:187], v[100:103]
	v_mfma_f32_16x16x32_bf16 v[96:99], v[168:171], v[184:187], v[96:99]
	v_mfma_f32_16x16x32_bf16 v[84:87], v[160:163], v[204:207], v[84:87]
	v_mfma_f32_16x16x32_bf16 v[80:83], v[168:171], v[204:207], v[80:83]
	v_mfma_f32_16x16x32_bf16 v[68:71], v[160:163], v[218:221], v[68:71]
	v_mfma_f32_16x16x32_bf16 v[64:67], v[168:171], v[218:221], v[64:67]
	v_mfma_f32_16x16x32_bf16 v[124:127], v[164:167], v[180:183], v[124:127]
	v_mfma_f32_16x16x32_bf16 v[120:123], v[172:175], v[180:183], v[120:123]
	v_mfma_f32_16x16x32_bf16 v[100:103], v[164:167], v[188:191], v[100:103]
	v_mfma_f32_16x16x32_bf16 v[96:99], v[172:175], v[188:191], v[96:99]
	v_mfma_f32_16x16x32_bf16 v[84:87], v[164:167], v[208:211], v[84:87]
	v_mfma_f32_16x16x32_bf16 v[80:83], v[172:175], v[208:211], v[80:83]
	v_mfma_f32_16x16x32_bf16 v[68:71], v[164:167], v[222:225], v[68:71]
	v_mfma_f32_16x16x32_bf16 v[64:67], v[172:175], v[222:225], v[64:67]
	s_setprio 0
	s_barrier
; #define PG8_STAGE(bufoff, gbase, voff) do { _Pragma("unroll") for (int _i = 0; _i < 2; ++_i) \
;         __builtin_amdgcn_global_load_lds((const unsigned*)((const char*)(gbase) + (voff)[_i]), (PG8_LAS unsigned*)(lds + (bufoff) + ldsw + _i * 8192), 16, 0, 0); } while (0)
; #define PG8_LDA(dst, b, h) do { _Pragma("unroll") for (int m = 0; m < 4; ++m) _Pragma("unroll") for (int k = 0; k < 2; ++k) dst[m][k] = *(const PG8_LAS bf16x8*)(lds + PG8_SA(b, h) + aoff + m * 2048 + k * 1024); } while (0)
; #define PG8_LDB(dst, b, h) do { _Pragma("unroll") for (int n = 0; n < 2; ++n) _Pragma("unroll") for (int k = 0; k < 2; ++k) dst[n][k] = *(const PG8_LAS bf16x8*)(lds + PG8_SB(b, h) + boff + n * 2048 + k * 1024); } while (0)
; #define PG8_MMA(ai, bj, At, Bt) do { __builtin_amdgcn_s_setprio(1); _Pragma("unroll") for (int m = 0; m < 4; ++m) _Pragma("unroll") for (int n = 0; n < 2; ++n) _Pragma("unroll") for (int k = 0; k < 2; ++k) \
;         acc[ai][bj][m][n] = __builtin_amdgcn_mfma_f32_16x16x32_bf16(Bt[n][k], At[m][k], acc[ai][bj][m][n], 0, 0, 0); __builtin_amdgcn_s_setprio(0); } while (0)
; template <class Epi, class Sched, bool ALIGN_EPI = false, bool SP2 = false>
; __device__ __forceinline__ void gemm_phase(PG8_LAS unsigned char* lds, const Gemm g, const Sched& S, const Epi& E) {
;     ...
;             if constexpr (SP2) {
;             PG8_LDB(B0, 0, 0); PG8_LDB(B1, 0, 1); PG8_SCHED; PG8_LDA(At, 0, 0); PG8_STAGE(PG8_SA(1, 1), a1 + hstepA, voffA);
;             PG8_WAIT_V(8); PG8_WAIT_L(0); PG8_BAR; PG8_MMA(0, 0, At, B0); PG8_MMA(0, 1, At, B1); PG8_BAR; PG8_SCHED;
;             PG8_LDA(At, 0, 1); PG8_STAGE(PG8_SB(0, 0), b2, voffB); PG8_STAGE(PG8_SB(0, 1), b2 + hstepB, voffB); PG8_STAGE(PG8_SA(0, 0), a2, voffA);
;             PG8_WAIT_V(8); PG8_WAIT_L(0); PG8_BAR; PG8_MMA(1, 0, At, B0); PG8_MMA(1, 1, At, B1); PG8_BAR; PG8_SCHED;
;             PG8_LDB(B0, 1, 0); PG8_LDB(B1, 1, 1); PG8_SCHED; PG8_LDA(At, 1, 0); PG8_STAGE(PG8_SA(0, 1), a2 + hstepA, voffA);
;             PG8_WAIT_V(8); PG8_WAIT_L(0); PG8_BAR; PG8_MMA(0, 0, At, B0); PG8_MMA(0, 1, At, B1); PG8_BAR; PG8_SCHED;
;             PG8_LDA(At, 1, 1); PG8_STAGE(PG8_SB(1, 0), b3, voffB); PG8_STAGE(PG8_SB(1, 1), b3 + hstepB, voffB); PG8_STAGE(PG8_SA(1, 0), a3, voffA);
;             PG8_WAIT_V(8); PG8_WAIT_L(0); PG8_BAR; PG8_MMA(1, 0, At, B0); PG8_MMA(1, 1, At, B1); PG8_BAR; PG8_SCHED;
	s_mov_b32 m0, s45
	v_lshl_add_u64 v[194:195], v[194:195], 0, s[76:77]
	s_add_u32 s24, s24, 0x40080
	ds_read_b128 v[176:179], v151 offset:49152
	ds_read_b128 v[180:183], v151 offset:50176
	ds_read_b128 v[184:187], v151 offset:51200
	ds_read_b128 v[188:191], v151 offset:52224
	ds_read_b128 v[204:207], v151 offset:53248
	ds_read_b128 v[208:211], v151 offset:54272
	ds_read_b128 v[218:221], v151 offset:55296
	ds_read_b128 v[222:225], v151 offset:56320
	global_load_lds_dwordx4 v[194:195], off
	v_lshl_add_u64 v[194:195], v[226:227], 0, s[76:77]
	s_mov_b32 m0, s48
	s_addc_u32 s25, s25, 0
	global_load_lds_dwordx4 v[194:195], off
	v_lshl_add_u64 v[194:195], s[24:25], 0, v[192:193]
	s_mov_b32 m0, s60
	s_nop 0
	global_load_lds_dwordx4 v[194:195], off
	v_lshl_add_u64 v[194:195], s[24:25], 0, v[128:129]
	s_mov_b32 m0, s61
	s_nop 0
	global_load_lds_dwordx4 v[194:195], off
	v_lshl_add_u64 v[194:195], v[228:229], 0, s[76:77]
	s_mov_b32 m0, s49
	s_nop 0
	global_load_lds_dwordx4 v[194:195], off
	v_lshl_add_u64 v[194:195], v[230:231], 0, s[76:77]
	s_mov_b32 m0, s50
	s_nop 0
	global_load_lds_dwordx4 v[194:195], off
	s_waitcnt vmcnt(8)
	s_waitcnt lgkmcnt(0)
	s_barrier
	s_setprio 1
	s_waitcnt lgkmcnt(0)
	v_mfma_f32_16x16x32_bf16 v[60:63], v[140:143], v[176:179], v[60:63]
	v_mfma_f32_16x16x32_bf16 v[56:59], v[152:155], v[176:179], v[56:59]
	v_mfma_f32_16x16x32_bf16 v[44:47], v[140:143], v[184:187], v[44:47]
	v_mfma_f32_16x16x32_bf16 v[40:43], v[152:155], v[184:187], v[40:43]
	v_mfma_f32_16x16x32_bf16 v[28:31], v[140:143], v[204:207], v[28:31]
	v_mfma_f32_16x16x32_bf16 v[24:27], v[152:155], v[204:207], v[24:27]
	v_mfma_f32_16x16x32_bf16 v[12:15], v[140:143], v[218:221], v[12:15]
	v_mfma_f32_16x16x32_bf16 v[8:11], v[152:155], v[218:221], v[8:11]
	v_mfma_f32_16x16x32_bf16 v[60:63], v[144:147], v[180:183], v[60:63]
	v_mfma_f32_16x16x32_bf16 v[56:59], v[156:159], v[180:183], v[56:59]
	v_mfma_f32_16x16x32_bf16 v[44:47], v[144:147], v[188:191], v[44:47]
	v_mfma_f32_16x16x32_bf16 v[40:43], v[156:159], v[188:191], v[40:43]
	v_mfma_f32_16x16x32_bf16 v[28:31], v[144:147], v[208:211], v[28:31]
	v_mfma_f32_16x16x32_bf16 v[24:27], v[156:159], v[208:211], v[24:27]
	v_mfma_f32_16x16x32_bf16 v[12:15], v[144:147], v[222:225], v[12:15]
	v_mfma_f32_16x16x32_bf16 v[8:11], v[156:159], v[222:225], v[8:11]
	s_setprio 0
	s_setprio 1
	v_mfma_f32_16x16x32_bf16 v[52:55], v[160:163], v[176:179], v[52:55]
	v_mfma_f32_16x16x32_bf16 v[48:51], v[168:171], v[176:179], v[48:51]
	v_mfma_f32_16x16x32_bf16 v[36:39], v[160:163], v[184:187], v[36:39]
	v_mfma_f32_16x16x32_bf16 v[32:35], v[168:171], v[184:187], v[32:35]
	v_mfma_f32_16x16x32_bf16 v[20:23], v[160:163], v[204:207], v[20:23]
	v_mfma_f32_16x16x32_bf16 v[16:19], v[168:171], v[204:207], v[16:19]
	v_mfma_f32_16x16x32_bf16 v[4:7], v[160:163], v[218:221], v[4:7]
	v_mfma_f32_16x16x32_bf16 v[0:3], v[168:171], v[218:221], v[0:3]
	v_mfma_f32_16x16x32_bf16 v[52:55], v[164:167], v[180:183], v[52:55]
	v_mfma_f32_16x16x32_bf16 v[48:51], v[172:175], v[180:183], v[48:51]
	v_mfma_f32_16x16x32_bf16 v[36:39], v[164:167], v[188:191], v[36:39]
	v_mfma_f32_16x16x32_bf16 v[32:35], v[172:175], v[188:191], v[32:35]
	v_mfma_f32_16x16x32_bf16 v[20:23], v[164:167], v[208:211], v[20:23]
	v_mfma_f32_16x16x32_bf16 v[16:19], v[172:175], v[208:211], v[16:19]
	v_mfma_f32_16x16x32_bf16 v[4:7], v[164:167], v[222:225], v[4:7]
	v_mfma_f32_16x16x32_bf16 v[0:3], v[172:175], v[222:225], v[0:3]
	s_setprio 0
	s_barrier
	s_add_i32 s72, s72, 2
	s_add_u32 s70, s70, 0x100
	s_addc_u32 s71, s71, 0
	s_add_u32 s22, s22, 0x100
	s_addc_u32 s23, s23, 0
	s_cmp_gt_u32 s72, 13
	s_cbranch_scc0 .LBB0_1221
	s_and_b64 vcc, exec, s[10:11]
	s_cbranch_vccz .LBB0_1224
	s_barrier

; #define PG8_STAGE(bufoff, gbase, voff) do { _Pragma("unroll") for (int _i = 0; _i < 2; ++_i) \
;         __builtin_amdgcn_global_load_lds((const unsigned*)((const char*)(gbase) + (voff)[_i]), (PG8_LAS unsigned*)(lds + (bufoff) + ldsw + _i * 8192), 16, 0, 0); } while (0)
; #define PG8_LDA(dst, b, h) do { _Pragma("unroll") for (int m = 0; m < 4; ++m) _Pragma("unroll") for (int k = 0; k < 2; ++k) dst[m][k] = *(const PG8_LAS bf16x8*)(lds + PG8_SA(b, h) + aoff + m * 2048 + k * 1024); } while (0)
; #define PG8_LDB(dst, b, h) do { _Pragma("unroll") for (int n = 0; n < 2; ++n) _Pragma("unroll") for (int k = 0; k < 2; ++k) dst[n][k] = *(const PG8_LAS bf16x8*)(lds + PG8_SB(b, h) + boff + n * 2048 + k * 1024); } while (0)
; #define PG8_MMA(ai, bj, At, Bt) do { __builtin_amdgcn_s_setprio(1); _Pragma("unroll") for (int m = 0; m < 4; ++m) _Pragma("unroll") for (int n = 0; n < 2; ++n) _Pragma("unroll") for (int k = 0; k < 2; ++k) \
;         acc[ai][bj][m][n] = __builtin_amdgcn_mfma_f32_16x16x32_bf16(Bt[n][k], At[m][k], acc[ai][bj][m][n], 0, 0, 0); __builtin_amdgcn_s_setprio(0); } while (0)
; #define PG8_WAIT_V(n) asm volatile("s_waitcnt vmcnt(" #n ")" ::: "memory")
; #define PG8_BAR __builtin_amdgcn_s_barrier()
; template <class Epi, class Sched, bool ALIGN_EPI = false, bool SP2 = false>
; __device__ __forceinline__ void gemm_phase(PG8_LAS unsigned char* lds, const Gemm g, const Sched& S, const Epi& E) {
;     ...
;         for (int t = 0; t < nt; t += 2) {
;             const bool last = (t == nt - 2);
;             const char* a1 = cA + (size_t)(t + 1) * kstep;
;             const char* a2 = last ? nA : cA + (size_t)(t + 2) * kstep; const char* b2 = last ? nB : cB + (size_t)(t + 2) * kstep;
;             const char* a3 = a2 + kstep; const char* b3 = b2 + kstep;
;             if (last && has_next) S.a_ready(nxt);
;             if constexpr (SP2) {
;             PG8_LDB(B0, 0, 0); PG8_LDB(B1, 0, 1); PG8_SCHED; PG8_LDA(At, 0, 0); PG8_STAGE(PG8_SA(1, 1), a1 + hstepA, voffA);
;             PG8_WAIT_V(8); PG8_WAIT_L(0); PG8_BAR; PG8_MMA(0, 0, At, B0); PG8_MMA(0, 1, At, B1); PG8_BAR; PG8_SCHED;
;             PG8_LDA(At, 0, 1); PG8_STAGE(PG8_SB(0, 0), b2, voffB); PG8_STAGE(PG8_SB(0, 1), b2 + hstepB, voffB); PG8_STAGE(PG8_SA(0, 0), a2, voffA);
;             PG8_WAIT_V(8); PG8_WAIT_L(0); PG8_BAR; PG8_MMA(1, 0, At, B0); PG8_MMA(1, 1, At, B1); PG8_BAR; PG8_SCHED;
.LBB0_1319:
	v_add_u32_e32 v142, s35, v145
	ds_read_b128 v[138:141], v142
	ds_read_b128 v[148:151], v142 offset:1024
	ds_read_b128 v[152:155], v142 offset:2048
	ds_read_b128 v[156:159], v142 offset:3072
	v_add_u32_e32 v142, s38, v145
	ds_read_b128 v[160:163], v142
	ds_read_b128 v[164:167], v142 offset:1024
	ds_read_b128 v[168:171], v142 offset:2048
	ds_read_b128 v[172:175], v142 offset:3072
	s_add_u32 s22, s20, 0x100
	s_addc_u32 s23, s21, 0
	s_cmp_eq_u32 s78, 40
	s_cselect_b32 s27, s9, s23
	s_cselect_b32 s26, s8, s22
	s_cselect_b32 s25, s19, s75
	s_cselect_b32 s24, s18, s74
	v_lshl_add_u64 v[142:143], s[20:21], 0, v[136:137]
	s_add_i32 m0, s41, 0xc000
	ds_read_b128 v[176:179], v147
	ds_read_b128 v[180:183], v147 offset:1024
	ds_read_b128 v[184:187], v147 offset:2048
	ds_read_b128 v[188:191], v147 offset:3072
	ds_read_b128 v[204:207], v147 offset:4096
	ds_read_b128 v[208:211], v147 offset:5120
	ds_read_b128 v[218:221], v147 offset:6144
	ds_read_b128 v[222:225], v147 offset:7168
	global_load_lds_dwordx4 v[142:143], off
	v_lshl_add_u64 v[142:143], s[20:21], 0, v[134:135]
	s_add_i32 m0, s41, 0xe000
	s_nop 0
	global_load_lds_dwordx4 v[142:143], off
	s_waitcnt vmcnt(8)
	s_waitcnt lgkmcnt(0)
	s_barrier
	s_setprio 1
	s_waitcnt lgkmcnt(0)
	s_nop 0
	v_mfma_f32_16x16x32_bf16 v[124:127], v[138:141], v[176:179], v[124:127]
	v_mfma_f32_16x16x32_bf16 v[120:123], v[152:155], v[176:179], v[120:123]
	v_mfma_f32_16x16x32_bf16 v[108:111], v[138:141], v[184:187], v[108:111]
	v_mfma_f32_16x16x32_bf16 v[104:107], v[152:155], v[184:187], v[104:107]
	v_mfma_f32_16x16x32_bf16 v[92:95], v[138:141], v[204:207], v[92:95]
	v_mfma_f32_16x16x32_bf16 v[88:91], v[152:155], v[204:207], v[88:91]
	v_mfma_f32_16x16x32_bf16 v[76:79], v[138:141], v[218:221], v[76:79]
	v_mfma_f32_16x16x32_bf16 v[72:75], v[152:155], v[218:221], v[72:75]
	v_mfma_f32_16x16x32_bf16 v[124:127], v[148:151], v[180:183], v[124:127]
	v_mfma_f32_16x16x32_bf16 v[120:123], v[156:159], v[180:183], v[120:123]
	v_mfma_f32_16x16x32_bf16 v[108:111], v[148:151], v[188:191], v[108:111]
	v_mfma_f32_16x16x32_bf16 v[104:107], v[156:159], v[188:191], v[104:107]
	v_mfma_f32_16x16x32_bf16 v[92:95], v[148:151], v[208:211], v[92:95]
	v_mfma_f32_16x16x32_bf16 v[88:91], v[156:159], v[208:211], v[88:91]
	v_mfma_f32_16x16x32_bf16 v[76:79], v[148:151], v[222:225], v[76:79]
	v_mfma_f32_16x16x32_bf16 v[72:75], v[156:159], v[222:225], v[72:75]
	s_setprio 0
	s_setprio 1
	v_mfma_f32_16x16x32_bf16 v[116:119], v[160:163], v[176:179], v[116:119]
	v_mfma_f32_16x16x32_bf16 v[112:115], v[168:171], v[176:179], v[112:115]
	v_mfma_f32_16x16x32_bf16 v[100:103], v[160:163], v[184:187], v[100:103]
	v_mfma_f32_16x16x32_bf16 v[96:99], v[168:171], v[184:187], v[96:99]
	v_mfma_f32_16x16x32_bf16 v[84:87], v[160:163], v[204:207], v[84:87]
	v_mfma_f32_16x16x32_bf16 v[80:83], v[168:171], v[204:207], v[80:83]
	v_mfma_f32_16x16x32_bf16 v[68:71], v[160:163], v[218:221], v[68:71]
	v_mfma_f32_16x16x32_bf16 v[64:67], v[168:171], v[218:221], v[64:67]
	v_mfma_f32_16x16x32_bf16 v[116:119], v[164:167], v[180:183], v[116:119]
	v_mfma_f32_16x16x32_bf16 v[112:115], v[172:175], v[180:183], v[112:115]
	v_mfma_f32_16x16x32_bf16 v[100:103], v[164:167], v[188:191], v[100:103]
	v_mfma_f32_16x16x32_bf16 v[96:99], v[172:175], v[188:191], v[96:99]
	v_mfma_f32_16x16x32_bf16 v[84:87], v[164:167], v[208:211], v[84:87]
	v_mfma_f32_16x16x32_bf16 v[80:83], v[172:175], v[208:211], v[80:83]
	v_mfma_f32_16x16x32_bf16 v[68:71], v[164:167], v[222:225], v[68:71]
	v_mfma_f32_16x16x32_bf16 v[64:67], v[172:175], v[222:225], v[64:67]
	s_setprio 0
	s_barrier
	s_mov_b32 m0, s36
	v_lshl_add_u64 v[142:143], s[24:25], 0, v[192:193]
	s_add_u32 s20, s24, 0xb0000
	ds_read_b128 v[176:179], v147 offset:16384
	ds_read_b128 v[180:183], v147 offset:17408
	ds_read_b128 v[184:187], v147 offset:18432
	ds_read_b128 v[188:191], v147 offset:19456
	ds_read_b128 v[204:207], v147 offset:20480
	ds_read_b128 v[208:211], v147 offset:21504
	ds_read_b128 v[218:221], v147 offset:22528
	ds_read_b128 v[222:225], v147 offset:23552
	global_load_lds_dwordx4 v[142:143], off
	v_lshl_add_u64 v[194:195], s[24:25], 0, v[132:133]
	s_mov_b32 m0, s37
	s_addc_u32 s21, s25, 0
	global_load_lds_dwordx4 v[194:195], off
	v_lshl_add_u64 v[226:227], s[20:21], 0, v[192:193]
	s_mov_b32 m0, s39
	v_lshl_add_u64 v[228:229], s[26:27], 0, v[130:131]
	global_load_lds_dwordx4 v[226:227], off
	v_lshl_add_u64 v[226:227], s[20:21], 0, v[132:133]
	s_mov_b32 m0, s40
	s_nop 0
	global_load_lds_dwordx4 v[226:227], off
	v_lshl_add_u64 v[226:227], s[26:27], 0, v[128:129]
	s_mov_b32 m0, s41
	s_nop 0
	global_load_lds_dwordx4 v[226:227], off
	s_mov_b32 m0, s42
	s_nop 0
	global_load_lds_dwordx4 v[228:229], off
	s_waitcnt vmcnt(8)
	s_waitcnt lgkmcnt(0)
	s_barrier
; #define PG8_STAGE(bufoff, gbase, voff) do { _Pragma("unroll") for (int _i = 0; _i < 2; ++_i) \
;         __builtin_amdgcn_global_load_lds((const unsigned*)((const char*)(gbase) + (voff)[_i]), (PG8_LAS unsigned*)(lds + (bufoff) + ldsw + _i * 8192), 16, 0, 0); } while (0)
; #define PG8_LDA(dst, b, h) do { _Pragma("unroll") for (int m = 0; m < 4; ++m) _Pragma("unroll") for (int k = 0; k < 2; ++k) dst[m][k] = *(const PG8_LAS bf16x8*)(lds + PG8_SA(b, h) + aoff + m * 2048 + k * 1024); } while (0)
; #define PG8_LDB(dst, b, h) do { _Pragma("unroll") for (int n = 0; n < 2; ++n) _Pragma("unroll") for (int k = 0; k < 2; ++k) dst[n][k] = *(const PG8_LAS bf16x8*)(lds + PG8_SB(b, h) + boff + n * 2048 + k * 1024); } while (0)
; #define PG8_MMA(ai, bj, At, Bt) do { __builtin_amdgcn_s_setprio(1); _Pragma("unroll") for (int m = 0; m < 4; ++m) _Pragma("unroll") for (int n = 0; n < 2; ++n) _Pragma("unroll") for (int k = 0; k < 2; ++k) \
;         acc[ai][bj][m][n] = __builtin_amdgcn_mfma_f32_16x16x32_bf16(Bt[n][k], At[m][k], acc[ai][bj][m][n], 0, 0, 0); __builtin_amdgcn_s_setprio(0); } while (0)
; #define PG8_WAIT_V(n) asm volatile("s_waitcnt vmcnt(" #n ")" ::: "memory")
; #define PG8_WAIT_L(n) asm volatile("s_waitcnt lgkmcnt(" #n ")" ::: "memory")
; #define PG8_BAR __builtin_amdgcn_s_barrier()
; #define PG8_SCHED __builtin_amdgcn_sched_barrier(0)
; template <class Epi, class Sched, bool ALIGN_EPI = false, bool SP2 = false>
; __device__ __forceinline__ void gemm_phase(PG8_LAS unsigned char* lds, const Gemm g, const Sched& S, const Epi& E) {
;     ...
;             if constexpr (SP2) {
;             PG8_LDB(B0, 0, 0); PG8_LDB(B1, 0, 1); PG8_SCHED; PG8_LDA(At, 0, 0); PG8_STAGE(PG8_SA(1, 1), a1 + hstepA, voffA);
;             PG8_WAIT_V(8); PG8_WAIT_L(0); PG8_BAR; PG8_MMA(0, 0, At, B0); PG8_MMA(0, 1, At, B1); PG8_BAR; PG8_SCHED;
;             PG8_LDA(At, 0, 1); PG8_STAGE(PG8_SB(0, 0), b2, voffB); PG8_STAGE(PG8_SB(0, 1), b2 + hstepB, voffB); PG8_STAGE(PG8_SA(0, 0), a2, voffA);
;             PG8_WAIT_V(8); PG8_WAIT_L(0); PG8_BAR; PG8_MMA(1, 0, At, B0); PG8_MMA(1, 1, At, B1); PG8_BAR; PG8_SCHED;
;             PG8_LDB(B0, 1, 0); PG8_LDB(B1, 1, 1); PG8_SCHED; PG8_LDA(At, 1, 0); PG8_STAGE(PG8_SA(0, 1), a2 + hstepA, voffA);
;             PG8_WAIT_V(8); PG8_WAIT_L(0); PG8_BAR; PG8_MMA(0, 0, At, B0); PG8_MMA(0, 1, At, B1); PG8_BAR; PG8_SCHED;
	s_setprio 1
	s_waitcnt lgkmcnt(0)
	s_nop 0
	v_mfma_f32_16x16x32_bf16 v[60:63], v[138:141], v[176:179], v[60:63]
	v_mfma_f32_16x16x32_bf16 v[56:59], v[152:155], v[176:179], v[56:59]
	v_mfma_f32_16x16x32_bf16 v[44:47], v[138:141], v[184:187], v[44:47]
	v_mfma_f32_16x16x32_bf16 v[40:43], v[152:155], v[184:187], v[40:43]
	v_mfma_f32_16x16x32_bf16 v[28:31], v[138:141], v[204:207], v[28:31]
	v_mfma_f32_16x16x32_bf16 v[24:27], v[152:155], v[204:207], v[24:27]
	v_mfma_f32_16x16x32_bf16 v[12:15], v[138:141], v[218:221], v[12:15]
	v_mfma_f32_16x16x32_bf16 v[8:11], v[152:155], v[218:221], v[8:11]
	v_mfma_f32_16x16x32_bf16 v[60:63], v[148:151], v[180:183], v[60:63]
	v_mfma_f32_16x16x32_bf16 v[56:59], v[156:159], v[180:183], v[56:59]
	v_mfma_f32_16x16x32_bf16 v[44:47], v[148:151], v[188:191], v[44:47]
	v_mfma_f32_16x16x32_bf16 v[40:43], v[156:159], v[188:191], v[40:43]
	v_mfma_f32_16x16x32_bf16 v[28:31], v[148:151], v[208:211], v[28:31]
	v_mfma_f32_16x16x32_bf16 v[24:27], v[156:159], v[208:211], v[24:27]
	v_mfma_f32_16x16x32_bf16 v[12:15], v[148:151], v[222:225], v[12:15]
	v_mfma_f32_16x16x32_bf16 v[8:11], v[156:159], v[222:225], v[8:11]
	s_setprio 0
	s_setprio 1
	v_mfma_f32_16x16x32_bf16 v[52:55], v[160:163], v[176:179], v[52:55]
	v_mfma_f32_16x16x32_bf16 v[48:51], v[168:171], v[176:179], v[48:51]
	v_mfma_f32_16x16x32_bf16 v[36:39], v[160:163], v[184:187], v[36:39]
	v_mfma_f32_16x16x32_bf16 v[32:35], v[168:171], v[184:187], v[32:35]
	v_mfma_f32_16x16x32_bf16 v[20:23], v[160:163], v[204:207], v[20:23]
	v_mfma_f32_16x16x32_bf16 v[16:19], v[168:171], v[204:207], v[16:19]
	v_mfma_f32_16x16x32_bf16 v[4:7], v[160:163], v[218:221], v[4:7]
	v_mfma_f32_16x16x32_bf16 v[0:3], v[168:171], v[218:221], v[0:3]
	v_mfma_f32_16x16x32_bf16 v[52:55], v[164:167], v[180:183], v[52:55]
	v_mfma_f32_16x16x32_bf16 v[48:51], v[172:175], v[180:183], v[48:51]
	v_mfma_f32_16x16x32_bf16 v[36:39], v[164:167], v[188:191], v[36:39]
	v_mfma_f32_16x16x32_bf16 v[32:35], v[172:175], v[188:191], v[32:35]
	v_mfma_f32_16x16x32_bf16 v[20:23], v[164:167], v[208:211], v[20:23]
	v_mfma_f32_16x16x32_bf16 v[16:19], v[172:175], v[208:211], v[16:19]
	v_mfma_f32_16x16x32_bf16 v[4:7], v[164:167], v[222:225], v[4:7]
	v_mfma_f32_16x16x32_bf16 v[0:3], v[172:175], v[222:225], v[0:3]
	s_setprio 0
	s_barrier
	v_add_u32_e32 v156, s48, v145
	v_add_u32_e32 v172, s61, v145
	ds_read_b128 v[138:141], v156
	ds_read_b128 v[148:151], v156 offset:1024
	ds_read_b128 v[152:155], v156 offset:2048
	ds_read_b128 v[156:159], v156 offset:3072
	ds_read_b128 v[160:163], v172
	ds_read_b128 v[164:167], v172 offset:1024
	ds_read_b128 v[168:171], v172 offset:2048
	ds_read_b128 v[172:175], v172 offset:3072
	s_add_u32 s20, s26, 0xb0000
	s_addc_u32 s21, s27, 0
	s_mov_b32 m0, s43
	v_lshl_add_u64 v[230:231], s[20:21], 0, v[128:129]
	ds_read_b128 v[176:179], v147 offset:32768
	ds_read_b128 v[180:183], v147 offset:33792
	ds_read_b128 v[184:187], v147 offset:34816
	ds_read_b128 v[188:191], v147 offset:35840
	ds_read_b128 v[204:207], v147 offset:36864
	ds_read_b128 v[208:211], v147 offset:37888
	ds_read_b128 v[218:221], v147 offset:38912
	ds_read_b128 v[222:225], v147 offset:39936
	global_load_lds_dwordx4 v[230:231], off
	v_lshl_add_u64 v[230:231], s[20:21], 0, v[130:131]
	s_mov_b32 m0, s44
	s_nop 0
	global_load_lds_dwordx4 v[230:231], off
	s_waitcnt vmcnt(8)
	s_waitcnt lgkmcnt(0)
	s_barrier
	s_setprio 1
	s_waitcnt lgkmcnt(0)
	s_nop 0
	v_mfma_f32_16x16x32_bf16 v[124:127], v[138:141], v[176:179], v[124:127]
	v_mfma_f32_16x16x32_bf16 v[120:123], v[152:155], v[176:179], v[120:123]
	v_mfma_f32_16x16x32_bf16 v[108:111], v[138:141], v[184:187], v[108:111]
	v_mfma_f32_16x16x32_bf16 v[104:107], v[152:155], v[184:187], v[104:107]
	v_mfma_f32_16x16x32_bf16 v[92:95], v[138:141], v[204:207], v[92:95]
	v_mfma_f32_16x16x32_bf16 v[88:91], v[152:155], v[204:207], v[88:91]
	v_mfma_f32_16x16x32_bf16 v[76:79], v[138:141], v[218:221], v[76:79]
	v_mfma_f32_16x16x32_bf16 v[72:75], v[152:155], v[218:221], v[72:75]
	v_mfma_f32_16x16x32_bf16 v[124:127], v[148:151], v[180:183], v[124:127]
	v_mfma_f32_16x16x32_bf16 v[120:123], v[156:159], v[180:183], v[120:123]
	v_mfma_f32_16x16x32_bf16 v[108:111], v[148:151], v[188:191], v[108:111]
	v_mfma_f32_16x16x32_bf16 v[104:107], v[156:159], v[188:191], v[104:107]
	v_mfma_f32_16x16x32_bf16 v[92:95], v[148:151], v[208:211], v[92:95]
	v_mfma_f32_16x16x32_bf16 v[88:91], v[156:159], v[208:211], v[88:91]
	v_mfma_f32_16x16x32_bf16 v[76:79], v[148:151], v[222:225], v[76:79]
	v_mfma_f32_16x16x32_bf16 v[72:75], v[156:159], v[222:225], v[72:75]
	s_setprio 0
	s_setprio 1
	v_mfma_f32_16x16x32_bf16 v[116:119], v[160:163], v[176:179], v[116:119]
	v_mfma_f32_16x16x32_bf16 v[112:115], v[168:171], v[176:179], v[112:115]
	v_mfma_f32_16x16x32_bf16 v[100:103], v[160:163], v[184:187], v[100:103]
	v_mfma_f32_16x16x32_bf16 v[96:99], v[168:171], v[184:187], v[96:99]
	v_mfma_f32_16x16x32_bf16 v[84:87], v[160:163], v[204:207], v[84:87]
	v_mfma_f32_16x16x32_bf16 v[80:83], v[168:171], v[204:207], v[80:83]
	v_mfma_f32_16x16x32_bf16 v[68:71], v[160:163], v[218:221], v[68:71]
	v_mfma_f32_16x16x32_bf16 v[64:67], v[168:171], v[218:221], v[64:67]
	v_mfma_f32_16x16x32_bf16 v[116:119], v[164:167], v[180:183], v[116:119]
	v_mfma_f32_16x16x32_bf16 v[112:115], v[172:175], v[180:183], v[112:115]
	v_mfma_f32_16x16x32_bf16 v[100:103], v[164:167], v[188:191], v[100:103]
	v_mfma_f32_16x16x32_bf16 v[96:99], v[172:175], v[188:191], v[96:99]
	v_mfma_f32_16x16x32_bf16 v[84:87], v[164:167], v[208:211], v[84:87]
	v_mfma_f32_16x16x32_bf16 v[80:83], v[172:175], v[208:211], v[80:83]
	v_mfma_f32_16x16x32_bf16 v[68:71], v[164:167], v[222:225], v[68:71]
	v_mfma_f32_16x16x32_bf16 v[64:67], v[172:175], v[222:225], v[64:67]
	s_setprio 0
	s_barrier
; #define PG8_STAGE(bufoff, gbase, voff) do { _Pragma("unroll") for (int _i = 0; _i < 2; ++_i) \
;         __builtin_amdgcn_global_load_lds((const unsigned*)((const char*)(gbase) + (voff)[_i]), (PG8_LAS unsigned*)(lds + (bufoff) + ldsw + _i * 8192), 16, 0, 0); } while (0)
; #define PG8_LDA(dst, b, h) do { _Pragma("unroll") for (int m = 0; m < 4; ++m) _Pragma("unroll") for (int k = 0; k < 2; ++k) dst[m][k] = *(const PG8_LAS bf16x8*)(lds + PG8_SA(b, h) + aoff + m * 2048 + k * 1024); } while (0)
; #define PG8_MMA(ai, bj, At, Bt) do { __builtin_amdgcn_s_setprio(1); _Pragma("unroll") for (int m = 0; m < 4; ++m) _Pragma("unroll") for (int n = 0; n < 2; ++n) _Pragma("unroll") for (int k = 0; k < 2; ++k) \
;         acc[ai][bj][m][n] = __builtin_amdgcn_mfma_f32_16x16x32_bf16(Bt[n][k], At[m][k], acc[ai][bj][m][n], 0, 0, 0); __builtin_amdgcn_s_setprio(0); } while (0)
; #define PG8_WAIT_V(n) asm volatile("s_waitcnt vmcnt(" #n ")" ::: "memory")
; #define PG8_WAIT_L(n) asm volatile("s_waitcnt lgkmcnt(" #n ")" ::: "memory")
; #define PG8_BAR __builtin_amdgcn_s_barrier()
; #define PG8_SCHED __builtin_amdgcn_sched_barrier(0)
; template <class Epi, class Sched, bool ALIGN_EPI = false, bool SP2 = false>
; __device__ __forceinline__ void gemm_phase(PG8_LAS unsigned char* lds, const Gemm g, const Sched& S, const Epi& E) {
;     ...
;             PG8_LDA(At, 1, 1); PG8_STAGE(PG8_SB(1, 0), b3, voffB); PG8_STAGE(PG8_SB(1, 1), b3 + hstepB, voffB); PG8_STAGE(PG8_SA(1, 0), a3, voffA);
;             PG8_WAIT_V(8); PG8_WAIT_L(0); PG8_BAR; PG8_MMA(1, 0, At, B0); PG8_MMA(1, 1, At, B1); PG8_BAR; PG8_SCHED;
;     ...
;         if constexpr (ALIGN_EPI) { if (wr == 0) PG8_BAR; }
;     __device__ __forceinline__ void operator()(const f32x4 (&acc)[2][2][4][2], const pg8::Unit& u, int wr, int wc, int fr, int fq) const {
;         const int row0 = u.pm * 256 + wr * 64 + fr, col0 = u.pn * 256 + wc * 32 + 8 * fq;
; #pragma unroll
;         for (int ai = 0; ai < 2; ++ai)
; #pragma unroll
;             for (int m = 0; m < 4; ++m) {
;                 const int row = row0 + ai * 128 + m * 16; float ss = 0.f;
; #pragma unroll
;                 for (int bj = 0; bj < 2; ++bj) {
;                     const size_t off = (size_t)row * DM + col0 + bj * 128;
;                     const v4u b = *(const v4u*)(xb + off);
	s_mov_b32 m0, s49
	v_lshl_add_u64 v[142:143], v[142:143], 0, s[76:77]
	s_add_u32 s20, s24, 0xb0080
	ds_read_b128 v[176:179], v147 offset:49152
	ds_read_b128 v[180:183], v147 offset:50176
	ds_read_b128 v[184:187], v147 offset:51200
	ds_read_b128 v[188:191], v147 offset:52224
	ds_read_b128 v[204:207], v147 offset:53248
	ds_read_b128 v[208:211], v147 offset:54272
	ds_read_b128 v[218:221], v147 offset:55296
	ds_read_b128 v[222:225], v147 offset:56320
	global_load_lds_dwordx4 v[142:143], off
	v_lshl_add_u64 v[142:143], v[194:195], 0, s[76:77]
	s_mov_b32 m0, s50
	s_addc_u32 s21, s25, 0
	global_load_lds_dwordx4 v[142:143], off
	v_lshl_add_u64 v[142:143], s[20:21], 0, v[192:193]
	s_mov_b32 m0, s64
	s_nop 0
	global_load_lds_dwordx4 v[142:143], off
	v_lshl_add_u64 v[142:143], s[20:21], 0, v[132:133]
	s_mov_b32 m0, s65
	s_nop 0
	global_load_lds_dwordx4 v[142:143], off
	v_lshl_add_u64 v[142:143], v[226:227], 0, s[76:77]
	s_mov_b32 m0, s51
	s_nop 0
	global_load_lds_dwordx4 v[142:143], off
	v_lshl_add_u64 v[142:143], v[228:229], 0, s[76:77]
	s_mov_b32 m0, s60
	s_nop 0
	global_load_lds_dwordx4 v[142:143], off
	s_waitcnt vmcnt(8)
	s_waitcnt lgkmcnt(0)
	s_barrier
	s_setprio 1
	s_waitcnt lgkmcnt(0)
	v_mfma_f32_16x16x32_bf16 v[60:63], v[138:141], v[176:179], v[60:63]
	v_mfma_f32_16x16x32_bf16 v[56:59], v[152:155], v[176:179], v[56:59]
	v_mfma_f32_16x16x32_bf16 v[44:47], v[138:141], v[184:187], v[44:47]
	v_mfma_f32_16x16x32_bf16 v[40:43], v[152:155], v[184:187], v[40:43]
	v_mfma_f32_16x16x32_bf16 v[28:31], v[138:141], v[204:207], v[28:31]
	v_mfma_f32_16x16x32_bf16 v[24:27], v[152:155], v[204:207], v[24:27]
	v_mfma_f32_16x16x32_bf16 v[12:15], v[138:141], v[218:221], v[12:15]
	v_mfma_f32_16x16x32_bf16 v[8:11], v[152:155], v[218:221], v[8:11]
	v_mfma_f32_16x16x32_bf16 v[60:63], v[148:151], v[180:183], v[60:63]
	v_mfma_f32_16x16x32_bf16 v[56:59], v[156:159], v[180:183], v[56:59]
	v_mfma_f32_16x16x32_bf16 v[44:47], v[148:151], v[188:191], v[44:47]
	v_mfma_f32_16x16x32_bf16 v[40:43], v[156:159], v[188:191], v[40:43]
	v_mfma_f32_16x16x32_bf16 v[28:31], v[148:151], v[208:211], v[28:31]
	v_mfma_f32_16x16x32_bf16 v[24:27], v[156:159], v[208:211], v[24:27]
	v_mfma_f32_16x16x32_bf16 v[12:15], v[148:151], v[222:225], v[12:15]
	v_mfma_f32_16x16x32_bf16 v[8:11], v[156:159], v[222:225], v[8:11]
	s_setprio 0
	s_setprio 1
	v_mfma_f32_16x16x32_bf16 v[52:55], v[160:163], v[176:179], v[52:55]
	v_mfma_f32_16x16x32_bf16 v[48:51], v[168:171], v[176:179], v[48:51]
	v_mfma_f32_16x16x32_bf16 v[36:39], v[160:163], v[184:187], v[36:39]
	v_mfma_f32_16x16x32_bf16 v[32:35], v[168:171], v[184:187], v[32:35]
	v_mfma_f32_16x16x32_bf16 v[20:23], v[160:163], v[204:207], v[20:23]
	v_mfma_f32_16x16x32_bf16 v[16:19], v[168:171], v[204:207], v[16:19]
	v_mfma_f32_16x16x32_bf16 v[4:7], v[160:163], v[218:221], v[4:7]
	v_mfma_f32_16x16x32_bf16 v[0:3], v[168:171], v[218:221], v[0:3]
	v_mfma_f32_16x16x32_bf16 v[52:55], v[164:167], v[180:183], v[52:55]
	v_mfma_f32_16x16x32_bf16 v[48:51], v[172:175], v[180:183], v[48:51]
	v_mfma_f32_16x16x32_bf16 v[36:39], v[164:167], v[188:191], v[36:39]
	v_mfma_f32_16x16x32_bf16 v[32:35], v[172:175], v[188:191], v[32:35]
	v_mfma_f32_16x16x32_bf16 v[20:23], v[164:167], v[208:211], v[20:23]
	v_mfma_f32_16x16x32_bf16 v[16:19], v[172:175], v[208:211], v[16:19]
	v_mfma_f32_16x16x32_bf16 v[4:7], v[164:167], v[222:225], v[4:7]
	v_mfma_f32_16x16x32_bf16 v[0:3], v[172:175], v[222:225], v[0:3]
	s_setprio 0
	s_barrier
	s_add_i32 s78, s78, 2
	s_add_u32 s74, s74, 0x100
	s_addc_u32 s75, s75, 0
	s_cmp_gt_u32 s78, 41
	s_mov_b64 s[20:21], s[22:23]
	s_cbranch_scc0 .LBB0_1319
	v_lshl_add_u32 v159, s68, 8, v144
	v_lshl_or_b32 v158, s34, 8, v146
	v_lshlrev_b32_e32 v159, 11, v159
	v_lshl_add_u32 v159, v158, 1, v159
	v_add_u32_e32 v218, 0x8000, v159
	v_add_u32_e32 v219, 0x10000, v159
	v_add_u32_e32 v240, 0x18000, v159
	v_add_u32_e32 v241, 0x40000, v159
	v_add_u32_e32 v245, 0x48000, v159
	v_add_u32_e32 v246, 0x50000, v159
	v_add_u32_e32 v247, 0x58000, v159
	global_load_dwordx4 v[160:163], v159, s[12:13]
	global_load_dwordx4 v[164:167], v159, s[12:13] offset:256
	global_load_dwordx4 v[168:171], v218, s[12:13]
	global_load_dwordx4 v[172:175], v218, s[12:13] offset:256
	global_load_dwordx4 v[176:179], v219, s[12:13]
	global_load_dwordx4 v[180:183], v219, s[12:13] offset:256
	global_load_dwordx4 v[184:187], v240, s[12:13]
	global_load_dwordx4 v[188:191], v240, s[12:13] offset:256
	global_load_dwordx4 v[204:207], v241, s[12:13]
	global_load_dwordx4 v[208:211], v241, s[12:13] offset:256
	global_load_dwordx4 v[220:223], v245, s[12:13]
	global_load_dwordx4 v[224:227], v245, s[12:13] offset:256
	global_load_dwordx4 v[228:231], v246, s[12:13]
	global_load_dwordx4 v[232:235], v246, s[12:13] offset:256
	global_load_dwordx4 v[236:239], v247, s[12:13]
	global_load_dwordx4 v[248:251], v247, s[12:13] offset:256
	s_and_b64 vcc, exec, s[16:17]
	s_cbranch_vccz .LBB0_1322
	s_barrier
